# GEMM K-loops (all seven): hipcc's per-cluster s_setprio 1/0 flips deleted (A/B of the flips; timing-only, bit-identical)
# baseline (speedup 1.0000x reference)
; #define PG8_STAGE(bufoff, gbase, voff) do { _Pragma("unroll") for (int _i = 0; _i < 2; ++_i) \
;         __builtin_amdgcn_global_load_lds((const unsigned*)((const char*)(gbase) + (voff)[_i]), (PG8_LAS unsigned*)(lds + (bufoff) + ldsw + _i * 8192), 16, 0, 0); } while (0)
; #define PG8_LDA(dst, b, h) do { _Pragma("unroll") for (int m = 0; m < 4; ++m) _Pragma("unroll") for (int k = 0; k < 2; ++k) dst[m][k] = *(const PG8_LAS bf16x8*)(lds + PG8_SA(b, h) + aoff + m * 2048 + k * 1024); } while (0)
; #define PG8_LDB(dst, b, h) do { _Pragma("unroll") for (int n = 0; n < 2; ++n) _Pragma("unroll") for (int k = 0; k < 2; ++k) dst[n][k] = *(const PG8_LAS bf16x8*)(lds + PG8_SB(b, h) + boff + n * 2048 + k * 1024); } while (0)
; #define PG8_MMA(ai, bj, At, Bt) do { __builtin_amdgcn_s_setprio(1); _Pragma("unroll") for (int m = 0; m < 4; ++m) _Pragma("unroll") for (int n = 0; n < 2; ++n) _Pragma("unroll") for (int k = 0; k < 2; ++k) \
;         acc[ai][bj][m][n] = __builtin_amdgcn_mfma_f32_16x16x32_bf16(Bt[n][k], At[m][k], acc[ai][bj][m][n], 0, 0, 0); __builtin_amdgcn_s_setprio(0); } while (0)
; #define PG8_WAIT_V(n) asm volatile("s_waitcnt vmcnt(" #n ")" ::: "memory")
; #define PG8_WAIT_L(n) asm volatile("s_waitcnt lgkmcnt(" #n ")" ::: "memory")
; #define PG8_BAR __builtin_amdgcn_s_barrier()
; template <class Epi, class Sched, bool ALIGN_EPI = false, bool SP2 = false>
; __device__ __forceinline__ void gemm_phase(PG8_LAS unsigned char* lds, const Gemm g, const Sched& S, const Epi& E) {
;     ...
;             const char* a1 = cA + (size_t)(t + 1) * kstep;
;             const char* a2 = last ? nA : cA + (size_t)(t + 2) * kstep; const char* b2 = last ? nB : cB + (size_t)(t + 2) * kstep;
;             const char* a3 = a2 + kstep; const char* b3 = b2 + kstep;
;             if (last && has_next) S.a_ready(nxt);
;             if constexpr (SP2) {
;             PG8_LDB(B0, 0, 0); PG8_LDB(B1, 0, 1); PG8_SCHED; PG8_LDA(At, 0, 0); PG8_STAGE(PG8_SA(1, 1), a1 + hstep, voffA);
;             PG8_WAIT_V(8); PG8_WAIT_L(0); PG8_BAR; PG8_MMA(0, 0, At, B0); PG8_MMA(0, 1, At, B1); PG8_BAR; PG8_SCHED;
;             PG8_LDA(At, 0, 1); PG8_STAGE(PG8_SB(0, 0), b2, voffB); PG8_STAGE(PG8_SB(0, 1), b2 + hstep, voffB); PG8_STAGE(PG8_SA(0, 0), a2, voffA);
;             PG8_WAIT_V(8); PG8_WAIT_L(0); PG8_BAR; PG8_MMA(1, 0, At, B0); PG8_MMA(1, 1, At, B1); PG8_BAR; PG8_SCHED;
.LBB0_178:
	s_add_u32 s26, s24, 0xfffc0080
	s_addc_u32 s27, s25, -1
	s_add_i32 s78, 0, 0x10000
	s_cmp_eq_u32 s77, 12
	s_cselect_b32 s37, s19, s27
	s_cselect_b32 s36, s73, s26
	s_cselect_b32 s27, s15, s76
	s_cselect_b32 s26, s74, s75
	s_add_i32 s80, 0, 0x14000
	v_add_u32_e32 v154, s78, v144
	v_add_u32_e32 v170, s80, v144
	ds_read_b128 v[140:143], v154
	ds_read_b128 v[146:149], v154 offset:1024
	ds_read_b128 v[150:153], v154 offset:2048
	ds_read_b128 v[154:157], v154 offset:3072
	ds_read_b128 v[158:161], v170
	ds_read_b128 v[162:165], v170 offset:1024
	ds_read_b128 v[166:169], v170 offset:2048
	ds_read_b128 v[170:173], v170 offset:3072
	v_lshl_add_u64 v[206:207], s[24:25], 0, v[138:139]
	s_add_i32 m0, s40, 0xc000
	ds_read_b128 v[174:177], v145
	ds_read_b128 v[178:181], v145 offset:1024
	ds_read_b128 v[182:185], v145 offset:2048
	ds_read_b128 v[186:189], v145 offset:3072
	ds_read_b128 v[190:193], v145 offset:4096
	ds_read_b128 v[194:197], v145 offset:5120
	ds_read_b128 v[198:201], v145 offset:6144
	ds_read_b128 v[202:205], v145 offset:7168
	global_load_lds_dwordx4 v[206:207], off
	v_lshl_add_u64 v[206:207], s[24:25], 0, v[136:137]
	s_add_i32 m0, s40, 0xe000
	s_nop 0
	global_load_lds_dwordx4 v[206:207], off
	s_waitcnt vmcnt(8)
	s_waitcnt lgkmcnt(0)
	s_barrier
	s_waitcnt lgkmcnt(0)
	v_mfma_f32_16x16x32_bf16 v[126:129], v[140:143], v[174:177], v[126:129]
	v_mfma_f32_16x16x32_bf16 v[118:121], v[150:153], v[174:177], v[118:121]
	v_mfma_f32_16x16x32_bf16 v[106:109], v[140:143], v[182:185], v[106:109]
	v_mfma_f32_16x16x32_bf16 v[98:101], v[150:153], v[182:185], v[98:101]
	v_mfma_f32_16x16x32_bf16 v[94:97], v[140:143], v[190:193], v[94:97]
	v_mfma_f32_16x16x32_bf16 v[82:85], v[150:153], v[190:193], v[82:85]
	v_mfma_f32_16x16x32_bf16 v[78:81], v[140:143], v[198:201], v[78:81]
	v_mfma_f32_16x16x32_bf16 v[66:69], v[150:153], v[198:201], v[66:69]
	v_mfma_f32_16x16x32_bf16 v[126:129], v[146:149], v[178:181], v[126:129]
	v_mfma_f32_16x16x32_bf16 v[118:121], v[154:157], v[178:181], v[118:121]
	v_mfma_f32_16x16x32_bf16 v[106:109], v[146:149], v[186:189], v[106:109]
	v_mfma_f32_16x16x32_bf16 v[98:101], v[154:157], v[186:189], v[98:101]
	v_mfma_f32_16x16x32_bf16 v[94:97], v[146:149], v[194:197], v[94:97]
	v_mfma_f32_16x16x32_bf16 v[82:85], v[154:157], v[194:197], v[82:85]
	v_mfma_f32_16x16x32_bf16 v[78:81], v[146:149], v[202:205], v[78:81]
	v_mfma_f32_16x16x32_bf16 v[66:69], v[154:157], v[202:205], v[66:69]
	v_mfma_f32_16x16x32_bf16 v[122:125], v[158:161], v[174:177], v[122:125]
	v_mfma_f32_16x16x32_bf16 v[114:117], v[166:169], v[174:177], v[114:117]
	v_mfma_f32_16x16x32_bf16 v[110:113], v[158:161], v[182:185], v[110:113]
	v_mfma_f32_16x16x32_bf16 v[102:105], v[166:169], v[182:185], v[102:105]
	v_mfma_f32_16x16x32_bf16 v[90:93], v[158:161], v[190:193], v[90:93]
	v_mfma_f32_16x16x32_bf16 v[86:89], v[166:169], v[190:193], v[86:89]
	v_mfma_f32_16x16x32_bf16 v[74:77], v[158:161], v[198:201], v[74:77]
	v_mfma_f32_16x16x32_bf16 v[70:73], v[166:169], v[198:201], v[70:73]
	v_mfma_f32_16x16x32_bf16 v[122:125], v[162:165], v[178:181], v[122:125]
	v_mfma_f32_16x16x32_bf16 v[114:117], v[170:173], v[178:181], v[114:117]
	v_mfma_f32_16x16x32_bf16 v[110:113], v[162:165], v[186:189], v[110:113]
	v_mfma_f32_16x16x32_bf16 v[102:105], v[170:173], v[186:189], v[102:105]
	v_mfma_f32_16x16x32_bf16 v[90:93], v[162:165], v[194:197], v[90:93]
	v_mfma_f32_16x16x32_bf16 v[86:89], v[170:173], v[194:197], v[86:89]
	v_mfma_f32_16x16x32_bf16 v[74:77], v[162:165], v[202:205], v[74:77]
	v_mfma_f32_16x16x32_bf16 v[70:73], v[170:173], v[202:205], v[70:73]
	s_barrier
	s_add_i32 s78, s78, s52
	v_lshl_add_u64 v[206:207], s[26:27], 0, v[0:1]
	s_mov_b32 m0, s78
	ds_read_b128 v[174:177], v145 offset:16384
	ds_read_b128 v[178:181], v145 offset:17408
	ds_read_b128 v[182:185], v145 offset:18432
	ds_read_b128 v[186:189], v145 offset:19456
	ds_read_b128 v[190:193], v145 offset:20480
	ds_read_b128 v[194:197], v145 offset:21504
	ds_read_b128 v[198:201], v145 offset:22528
	ds_read_b128 v[202:205], v145 offset:23552
	global_load_lds_dwordx4 v[206:207], off
	s_add_i32 m0, s78, 0x2000
	s_add_u32 s78, s26, 0x40000
	v_lshl_add_u64 v[208:209], s[26:27], 0, v[130:131]
	s_addc_u32 s79, s27, 0
	s_add_i32 s80, s80, s52
	global_load_lds_dwordx4 v[208:209], off
	v_lshl_add_u64 v[210:211], s[78:79], 0, v[0:1]
	s_mov_b32 m0, s80
	v_lshl_add_u64 v[220:221], s[36:37], 0, v[132:133]
	global_load_lds_dwordx4 v[210:211], off
	v_lshl_add_u64 v[210:211], s[78:79], 0, v[130:131]
	s_add_i32 m0, s80, 0x2000
	s_nop 0
	global_load_lds_dwordx4 v[210:211], off
	v_lshl_add_u64 v[210:211], s[36:37], 0, v[134:135]
	s_mov_b32 m0, s40
	s_nop 0
	global_load_lds_dwordx4 v[210:211], off
	s_mov_b32 m0, s41
	s_nop 0
	global_load_lds_dwordx4 v[220:221], off
	s_waitcnt vmcnt(8)
	s_waitcnt lgkmcnt(0)
	s_barrier
; #define PG8_STAGE(bufoff, gbase, voff) do { _Pragma("unroll") for (int _i = 0; _i < 2; ++_i) \
;         __builtin_amdgcn_global_load_lds((const unsigned*)((const char*)(gbase) + (voff)[_i]), (PG8_LAS unsigned*)(lds + (bufoff) + ldsw + _i * 8192), 16, 0, 0); } while (0)
; #define PG8_LDA(dst, b, h) do { _Pragma("unroll") for (int m = 0; m < 4; ++m) _Pragma("unroll") for (int k = 0; k < 2; ++k) dst[m][k] = *(const PG8_LAS bf16x8*)(lds + PG8_SA(b, h) + aoff + m * 2048 + k * 1024); } while (0)
; #define PG8_LDB(dst, b, h) do { _Pragma("unroll") for (int n = 0; n < 2; ++n) _Pragma("unroll") for (int k = 0; k < 2; ++k) dst[n][k] = *(const PG8_LAS bf16x8*)(lds + PG8_SB(b, h) + boff + n * 2048 + k * 1024); } while (0)
; #define PG8_MMA(ai, bj, At, Bt) do { __builtin_amdgcn_s_setprio(1); _Pragma("unroll") for (int m = 0; m < 4; ++m) _Pragma("unroll") for (int n = 0; n < 2; ++n) _Pragma("unroll") for (int k = 0; k < 2; ++k) \
;         acc[ai][bj][m][n] = __builtin_amdgcn_mfma_f32_16x16x32_bf16(Bt[n][k], At[m][k], acc[ai][bj][m][n], 0, 0, 0); __builtin_amdgcn_s_setprio(0); } while (0)
; #define PG8_WAIT_V(n) asm volatile("s_waitcnt vmcnt(" #n ")" ::: "memory")
; #define PG8_WAIT_L(n) asm volatile("s_waitcnt lgkmcnt(" #n ")" ::: "memory")
; #define PG8_BAR __builtin_amdgcn_s_barrier()
; #define PG8_SCHED __builtin_amdgcn_sched_barrier(0)
; template <class Epi, class Sched, bool ALIGN_EPI = false, bool SP2 = false>
; __device__ __forceinline__ void gemm_phase(PG8_LAS unsigned char* lds, const Gemm g, const Sched& S, const Epi& E) {
;     ...
;             PG8_WAIT_V(8); PG8_WAIT_L(0); PG8_BAR; PG8_MMA(1, 0, At, B0); PG8_MMA(1, 1, At, B1); PG8_BAR; PG8_SCHED;
;             PG8_LDB(B0, 1, 0); PG8_LDB(B1, 1, 1); PG8_SCHED; PG8_LDA(At, 1, 0); PG8_STAGE(PG8_SA(0, 1), a2 + hstep, voffA);
;             PG8_WAIT_V(8); PG8_WAIT_L(0); PG8_BAR; PG8_MMA(0, 0, At, B0); PG8_MMA(0, 1, At, B1); PG8_BAR; PG8_SCHED;
	s_waitcnt lgkmcnt(0)
	v_mfma_f32_16x16x32_bf16 v[62:65], v[140:143], v[174:177], v[62:65]
	v_mfma_f32_16x16x32_bf16 v[50:53], v[150:153], v[174:177], v[50:53]
	v_mfma_f32_16x16x32_bf16 v[46:49], v[140:143], v[182:185], v[46:49]
	v_mfma_f32_16x16x32_bf16 v[34:37], v[150:153], v[182:185], v[34:37]
	v_mfma_f32_16x16x32_bf16 v[30:33], v[140:143], v[190:193], v[30:33]
	v_mfma_f32_16x16x32_bf16 v[18:21], v[150:153], v[190:193], v[18:21]
	v_mfma_f32_16x16x32_bf16 v[14:17], v[140:143], v[198:201], v[14:17]
	v_mfma_f32_16x16x32_bf16 v[6:9], v[150:153], v[198:201], v[6:9]
	v_mfma_f32_16x16x32_bf16 v[62:65], v[146:149], v[178:181], v[62:65]
	v_mfma_f32_16x16x32_bf16 v[50:53], v[154:157], v[178:181], v[50:53]
	v_mfma_f32_16x16x32_bf16 v[46:49], v[146:149], v[186:189], v[46:49]
	v_mfma_f32_16x16x32_bf16 v[34:37], v[154:157], v[186:189], v[34:37]
	v_mfma_f32_16x16x32_bf16 v[30:33], v[146:149], v[194:197], v[30:33]
	v_mfma_f32_16x16x32_bf16 v[18:21], v[154:157], v[194:197], v[18:21]
	v_mfma_f32_16x16x32_bf16 v[14:17], v[146:149], v[202:205], v[14:17]
	v_mfma_f32_16x16x32_bf16 v[6:9], v[154:157], v[202:205], v[6:9]
	v_mfma_f32_16x16x32_bf16 v[58:61], v[158:161], v[174:177], v[58:61]
	v_mfma_f32_16x16x32_bf16 v[54:57], v[166:169], v[174:177], v[54:57]
	v_mfma_f32_16x16x32_bf16 v[42:45], v[158:161], v[182:185], v[42:45]
	v_mfma_f32_16x16x32_bf16 v[38:41], v[166:169], v[182:185], v[38:41]
	v_mfma_f32_16x16x32_bf16 v[26:29], v[158:161], v[190:193], v[26:29]
	v_mfma_f32_16x16x32_bf16 v[22:25], v[166:169], v[190:193], v[22:25]
	v_mfma_f32_16x16x32_bf16 v[10:13], v[158:161], v[198:201], v[10:13]
	v_mfma_f32_16x16x32_bf16 v[2:5], v[166:169], v[198:201], v[2:5]
	v_mfma_f32_16x16x32_bf16 v[58:61], v[162:165], v[178:181], v[58:61]
	v_mfma_f32_16x16x32_bf16 v[54:57], v[170:173], v[178:181], v[54:57]
	v_mfma_f32_16x16x32_bf16 v[42:45], v[162:165], v[186:189], v[42:45]
	v_mfma_f32_16x16x32_bf16 v[38:41], v[170:173], v[186:189], v[38:41]
	v_mfma_f32_16x16x32_bf16 v[26:29], v[162:165], v[194:197], v[26:29]
	v_mfma_f32_16x16x32_bf16 v[22:25], v[170:173], v[194:197], v[22:25]
	v_mfma_f32_16x16x32_bf16 v[10:13], v[162:165], v[202:205], v[10:13]
	v_mfma_f32_16x16x32_bf16 v[2:5], v[170:173], v[202:205], v[2:5]
	s_barrier
	s_add_i32 s78, 0, 0x18000
	s_add_i32 s79, 0, 0x1c000
	v_add_u32_e32 v154, s78, v144
	v_add_u32_e32 v170, s79, v144
	ds_read_b128 v[140:143], v154
	ds_read_b128 v[146:149], v154 offset:1024
	ds_read_b128 v[150:153], v154 offset:2048
	ds_read_b128 v[154:157], v154 offset:3072
	ds_read_b128 v[158:161], v170
	ds_read_b128 v[162:165], v170 offset:1024
	ds_read_b128 v[166:169], v170 offset:2048
	ds_read_b128 v[170:173], v170 offset:3072
	s_add_u32 s36, s36, 0x40000
	s_addc_u32 s37, s37, 0
	s_mov_b32 m0, s53
	v_lshl_add_u64 v[222:223], s[36:37], 0, v[134:135]
	ds_read_b128 v[174:177], v145 offset:32768
	ds_read_b128 v[178:181], v145 offset:33792
	ds_read_b128 v[182:185], v145 offset:34816
	ds_read_b128 v[186:189], v145 offset:35840
	ds_read_b128 v[190:193], v145 offset:36864
	ds_read_b128 v[194:197], v145 offset:37888
	ds_read_b128 v[198:201], v145 offset:38912
	ds_read_b128 v[202:205], v145 offset:39936
	global_load_lds_dwordx4 v[222:223], off
	v_lshl_add_u64 v[222:223], s[36:37], 0, v[132:133]
	s_mov_b32 m0, s60
	s_nop 0
	global_load_lds_dwordx4 v[222:223], off
	s_waitcnt vmcnt(8)
	s_waitcnt lgkmcnt(0)
	s_barrier
	s_waitcnt lgkmcnt(0)
	v_mfma_f32_16x16x32_bf16 v[126:129], v[140:143], v[174:177], v[126:129]
	v_mfma_f32_16x16x32_bf16 v[118:121], v[150:153], v[174:177], v[118:121]
	v_mfma_f32_16x16x32_bf16 v[106:109], v[140:143], v[182:185], v[106:109]
	v_mfma_f32_16x16x32_bf16 v[98:101], v[150:153], v[182:185], v[98:101]
	v_mfma_f32_16x16x32_bf16 v[94:97], v[140:143], v[190:193], v[94:97]
	v_mfma_f32_16x16x32_bf16 v[82:85], v[150:153], v[190:193], v[82:85]
	v_mfma_f32_16x16x32_bf16 v[78:81], v[140:143], v[198:201], v[78:81]
	v_mfma_f32_16x16x32_bf16 v[66:69], v[150:153], v[198:201], v[66:69]
	v_mfma_f32_16x16x32_bf16 v[126:129], v[146:149], v[178:181], v[126:129]
	v_mfma_f32_16x16x32_bf16 v[118:121], v[154:157], v[178:181], v[118:121]
	v_mfma_f32_16x16x32_bf16 v[106:109], v[146:149], v[186:189], v[106:109]
	v_mfma_f32_16x16x32_bf16 v[98:101], v[154:157], v[186:189], v[98:101]
	v_mfma_f32_16x16x32_bf16 v[94:97], v[146:149], v[194:197], v[94:97]
	v_mfma_f32_16x16x32_bf16 v[82:85], v[154:157], v[194:197], v[82:85]
	v_mfma_f32_16x16x32_bf16 v[78:81], v[146:149], v[202:205], v[78:81]
	v_mfma_f32_16x16x32_bf16 v[66:69], v[154:157], v[202:205], v[66:69]
	v_mfma_f32_16x16x32_bf16 v[122:125], v[158:161], v[174:177], v[122:125]
	v_mfma_f32_16x16x32_bf16 v[114:117], v[166:169], v[174:177], v[114:117]
	v_mfma_f32_16x16x32_bf16 v[110:113], v[158:161], v[182:185], v[110:113]
	v_mfma_f32_16x16x32_bf16 v[102:105], v[166:169], v[182:185], v[102:105]
	v_mfma_f32_16x16x32_bf16 v[90:93], v[158:161], v[190:193], v[90:93]
	v_mfma_f32_16x16x32_bf16 v[86:89], v[166:169], v[190:193], v[86:89]
	v_mfma_f32_16x16x32_bf16 v[74:77], v[158:161], v[198:201], v[74:77]
	v_mfma_f32_16x16x32_bf16 v[70:73], v[166:169], v[198:201], v[70:73]
	v_mfma_f32_16x16x32_bf16 v[122:125], v[162:165], v[178:181], v[122:125]
	v_mfma_f32_16x16x32_bf16 v[114:117], v[170:173], v[178:181], v[114:117]
	v_mfma_f32_16x16x32_bf16 v[110:113], v[162:165], v[186:189], v[110:113]
	v_mfma_f32_16x16x32_bf16 v[102:105], v[170:173], v[186:189], v[102:105]
	v_mfma_f32_16x16x32_bf16 v[90:93], v[162:165], v[194:197], v[90:93]
	v_mfma_f32_16x16x32_bf16 v[86:89], v[170:173], v[194:197], v[86:89]
	v_mfma_f32_16x16x32_bf16 v[74:77], v[162:165], v[202:205], v[74:77]
	v_mfma_f32_16x16x32_bf16 v[70:73], v[170:173], v[202:205], v[70:73]
	s_barrier
; #define PG8_STAGE(bufoff, gbase, voff) do { _Pragma("unroll") for (int _i = 0; _i < 2; ++_i) \
;         __builtin_amdgcn_global_load_lds((const unsigned*)((const char*)(gbase) + (voff)[_i]), (PG8_LAS unsigned*)(lds + (bufoff) + ldsw + _i * 8192), 16, 0, 0); } while (0)
; #define PG8_LDA(dst, b, h) do { _Pragma("unroll") for (int m = 0; m < 4; ++m) _Pragma("unroll") for (int k = 0; k < 2; ++k) dst[m][k] = *(const PG8_LAS bf16x8*)(lds + PG8_SA(b, h) + aoff + m * 2048 + k * 1024); } while (0)
; #define PG8_MMA(ai, bj, At, Bt) do { __builtin_amdgcn_s_setprio(1); _Pragma("unroll") for (int m = 0; m < 4; ++m) _Pragma("unroll") for (int n = 0; n < 2; ++n) _Pragma("unroll") for (int k = 0; k < 2; ++k) \
;         acc[ai][bj][m][n] = __builtin_amdgcn_mfma_f32_16x16x32_bf16(Bt[n][k], At[m][k], acc[ai][bj][m][n], 0, 0, 0); __builtin_amdgcn_s_setprio(0); } while (0)
; #define PG8_WAIT_V(n) asm volatile("s_waitcnt vmcnt(" #n ")" ::: "memory")
; #define PG8_WAIT_L(n) asm volatile("s_waitcnt lgkmcnt(" #n ")" ::: "memory")
; #define PG8_BAR __builtin_amdgcn_s_barrier()
; #define PG8_SCHED __builtin_amdgcn_sched_barrier(0)
; template <class Epi, class Sched, bool ALIGN_EPI = false, bool SP2 = false>
; __device__ __forceinline__ void gemm_phase(PG8_LAS unsigned char* lds, const Gemm g, const Sched& S, const Epi& E) {
;     ...
;             PG8_WAIT_V(8); PG8_WAIT_L(0); PG8_BAR; PG8_MMA(0, 0, At, B0); PG8_MMA(0, 1, At, B1); PG8_BAR; PG8_SCHED;
;             PG8_LDA(At, 1, 1); PG8_STAGE(PG8_SB(1, 0), b3, voffB); PG8_STAGE(PG8_SB(1, 1), b3 + hstep, voffB); PG8_STAGE(PG8_SA(1, 0), a3, voffA);
;             PG8_WAIT_V(8); PG8_WAIT_L(0); PG8_BAR; PG8_MMA(1, 0, At, B0); PG8_MMA(1, 1, At, B1); PG8_BAR; PG8_SCHED;
	s_add_i32 s36, s78, s52
	v_lshl_add_u64 v[206:207], v[206:207], 0, s[28:29]
	s_mov_b32 m0, s36
	ds_read_b128 v[174:177], v145 offset:49152
	ds_read_b128 v[178:181], v145 offset:50176
	ds_read_b128 v[182:185], v145 offset:51200
	ds_read_b128 v[186:189], v145 offset:52224
	ds_read_b128 v[190:193], v145 offset:53248
	ds_read_b128 v[194:197], v145 offset:54272
	ds_read_b128 v[198:201], v145 offset:55296
	ds_read_b128 v[202:205], v145 offset:56320
	global_load_lds_dwordx4 v[206:207], off
	s_add_i32 m0, s36, 0x2000
	s_add_u32 s26, s26, 0x40080
	v_lshl_add_u64 v[206:207], v[208:209], 0, s[28:29]
	s_addc_u32 s27, s27, 0
	s_add_i32 s36, s79, s52
	global_load_lds_dwordx4 v[206:207], off
	v_lshl_add_u64 v[206:207], s[26:27], 0, v[0:1]
	s_mov_b32 m0, s36
	s_nop 0
	global_load_lds_dwordx4 v[206:207], off
	v_lshl_add_u64 v[206:207], s[26:27], 0, v[130:131]
	s_add_i32 m0, s36, 0x2000
	s_nop 0
	global_load_lds_dwordx4 v[206:207], off
	v_lshl_add_u64 v[206:207], v[210:211], 0, s[28:29]
	s_mov_b32 m0, s65
	s_nop 0
	global_load_lds_dwordx4 v[206:207], off
	v_lshl_add_u64 v[206:207], v[220:221], 0, s[28:29]
	s_mov_b32 m0, s69
	s_nop 0
	global_load_lds_dwordx4 v[206:207], off
	s_waitcnt vmcnt(8)
	s_waitcnt lgkmcnt(0)
	s_barrier
	s_waitcnt lgkmcnt(0)
	v_mfma_f32_16x16x32_bf16 v[62:65], v[140:143], v[174:177], v[62:65]
	v_mfma_f32_16x16x32_bf16 v[50:53], v[150:153], v[174:177], v[50:53]
	v_mfma_f32_16x16x32_bf16 v[46:49], v[140:143], v[182:185], v[46:49]
	v_mfma_f32_16x16x32_bf16 v[34:37], v[150:153], v[182:185], v[34:37]
	v_mfma_f32_16x16x32_bf16 v[30:33], v[140:143], v[190:193], v[30:33]
	v_mfma_f32_16x16x32_bf16 v[18:21], v[150:153], v[190:193], v[18:21]
	v_mfma_f32_16x16x32_bf16 v[14:17], v[140:143], v[198:201], v[14:17]
	v_mfma_f32_16x16x32_bf16 v[6:9], v[150:153], v[198:201], v[6:9]
	v_mfma_f32_16x16x32_bf16 v[62:65], v[146:149], v[178:181], v[62:65]
	v_mfma_f32_16x16x32_bf16 v[50:53], v[154:157], v[178:181], v[50:53]
	v_mfma_f32_16x16x32_bf16 v[46:49], v[146:149], v[186:189], v[46:49]
	v_mfma_f32_16x16x32_bf16 v[34:37], v[154:157], v[186:189], v[34:37]
	v_mfma_f32_16x16x32_bf16 v[30:33], v[146:149], v[194:197], v[30:33]
	v_mfma_f32_16x16x32_bf16 v[18:21], v[154:157], v[194:197], v[18:21]
	v_mfma_f32_16x16x32_bf16 v[14:17], v[146:149], v[202:205], v[14:17]
	v_mfma_f32_16x16x32_bf16 v[6:9], v[154:157], v[202:205], v[6:9]
	v_mfma_f32_16x16x32_bf16 v[58:61], v[158:161], v[174:177], v[58:61]
	v_mfma_f32_16x16x32_bf16 v[54:57], v[166:169], v[174:177], v[54:57]
	v_mfma_f32_16x16x32_bf16 v[42:45], v[158:161], v[182:185], v[42:45]
	v_mfma_f32_16x16x32_bf16 v[38:41], v[166:169], v[182:185], v[38:41]
	v_mfma_f32_16x16x32_bf16 v[26:29], v[158:161], v[190:193], v[26:29]
	v_mfma_f32_16x16x32_bf16 v[22:25], v[166:169], v[190:193], v[22:25]
	v_mfma_f32_16x16x32_bf16 v[10:13], v[158:161], v[198:201], v[10:13]
	v_mfma_f32_16x16x32_bf16 v[2:5], v[166:169], v[198:201], v[2:5]
	v_mfma_f32_16x16x32_bf16 v[58:61], v[162:165], v[178:181], v[58:61]
	v_mfma_f32_16x16x32_bf16 v[54:57], v[170:173], v[178:181], v[54:57]
	v_mfma_f32_16x16x32_bf16 v[42:45], v[162:165], v[186:189], v[42:45]
	v_mfma_f32_16x16x32_bf16 v[38:41], v[170:173], v[186:189], v[38:41]
	v_mfma_f32_16x16x32_bf16 v[26:29], v[162:165], v[194:197], v[26:29]
	v_mfma_f32_16x16x32_bf16 v[22:25], v[170:173], v[194:197], v[22:25]
	v_mfma_f32_16x16x32_bf16 v[10:13], v[162:165], v[202:205], v[10:13]
	v_mfma_f32_16x16x32_bf16 v[2:5], v[170:173], v[202:205], v[2:5]
	s_barrier
	s_add_i32 s77, s77, 2
	s_add_u32 s75, s75, 0x100
	s_addc_u32 s76, s76, 0
	s_add_u32 s24, s24, 0x100
	s_addc_u32 s25, s25, 0
	s_cmp_gt_u32 s77, 13
	s_cbranch_scc0 .LBB0_178
	s_and_b64 vcc, exec, s[6:7]
	s_cbranch_vccz .LBB0_181
	s_barrier

; #define PG8_STAGE(bufoff, gbase, voff) do { _Pragma("unroll") for (int _i = 0; _i < 2; ++_i) \
;         __builtin_amdgcn_global_load_lds((const unsigned*)((const char*)(gbase) + (voff)[_i]), (PG8_LAS unsigned*)(lds + (bufoff) + ldsw + _i * 8192), 16, 0, 0); } while (0)
; #define PG8_LDA(dst, b, h) do { _Pragma("unroll") for (int m = 0; m < 4; ++m) _Pragma("unroll") for (int k = 0; k < 2; ++k) dst[m][k] = *(const PG8_LAS bf16x8*)(lds + PG8_SA(b, h) + aoff + m * 2048 + k * 1024); } while (0)
; #define PG8_LDB(dst, b, h) do { _Pragma("unroll") for (int n = 0; n < 2; ++n) _Pragma("unroll") for (int k = 0; k < 2; ++k) dst[n][k] = *(const PG8_LAS bf16x8*)(lds + PG8_SB(b, h) + boff + n * 2048 + k * 1024); } while (0)
; #define PG8_MMA(ai, bj, At, Bt) do { __builtin_amdgcn_s_setprio(1); _Pragma("unroll") for (int m = 0; m < 4; ++m) _Pragma("unroll") for (int n = 0; n < 2; ++n) _Pragma("unroll") for (int k = 0; k < 2; ++k) \
;         acc[ai][bj][m][n] = __builtin_amdgcn_mfma_f32_16x16x32_bf16(Bt[n][k], At[m][k], acc[ai][bj][m][n], 0, 0, 0); __builtin_amdgcn_s_setprio(0); } while (0)
; #define PG8_WAIT_V(n) asm volatile("s_waitcnt vmcnt(" #n ")" ::: "memory")
; #define PG8_WAIT_L(n) asm volatile("s_waitcnt lgkmcnt(" #n ")" ::: "memory")
; #define PG8_BAR __builtin_amdgcn_s_barrier()
; #define PG8_SCHED __builtin_amdgcn_sched_barrier(0)
; template <class Epi, class Sched, bool ALIGN_EPI = false, bool SP2 = false>
; __device__ __forceinline__ void gemm_phase(PG8_LAS unsigned char* lds, const Gemm g, const Sched& S, const Epi& E) {
;     ...
;             PG8_LDB(B0, 0, 0); PG8_LDB(B1, 0, 1); PG8_SCHED; PG8_LDA(At, 0, 0); PG8_STAGE(PG8_SA(1, 1), a1 + hstep, voffA);
;             PG8_WAIT_V(8); PG8_WAIT_L(0); PG8_BAR; PG8_MMA(0, 0, At, B0); PG8_MMA(0, 1, At, B1); PG8_BAR; PG8_SCHED;
;             PG8_LDA(At, 0, 1); PG8_STAGE(PG8_SB(0, 0), b2, voffB); PG8_STAGE(PG8_SB(0, 1), b2 + hstep, voffB); PG8_STAGE(PG8_SA(0, 0), a2, voffA);
;             PG8_WAIT_V(8); PG8_WAIT_L(0); PG8_BAR; PG8_MMA(1, 0, At, B0); PG8_MMA(1, 1, At, B1); PG8_BAR; PG8_SCHED;
.Lrw_dn_1:
	s_waitcnt lgkmcnt(0)
	s_barrier
	s_waitcnt lgkmcnt(0)
	v_mfma_f32_16x16x32_bf16 v[142:145], v[66:69], v[162:165], v[142:145]
	v_mfma_f32_16x16x32_bf16 v[138:141], v[74:77], v[162:165], v[138:141]
	v_mfma_f32_16x16x32_bf16 v[126:129], v[66:69], v[170:173], v[126:129]
	v_mfma_f32_16x16x32_bf16 v[122:125], v[74:77], v[170:173], v[122:125]
	v_mfma_f32_16x16x32_bf16 v[110:113], v[66:69], v[178:181], v[110:113]
	v_mfma_f32_16x16x32_bf16 v[106:109], v[74:77], v[178:181], v[106:109]
	v_mfma_f32_16x16x32_bf16 v[94:97], v[66:69], v[186:189], v[94:97]
	v_mfma_f32_16x16x32_bf16 v[90:93], v[74:77], v[186:189], v[90:93]
	v_mfma_f32_16x16x32_bf16 v[142:145], v[70:73], v[166:169], v[142:145]
	v_mfma_f32_16x16x32_bf16 v[138:141], v[78:81], v[166:169], v[138:141]
	v_mfma_f32_16x16x32_bf16 v[126:129], v[70:73], v[174:177], v[126:129]
	v_mfma_f32_16x16x32_bf16 v[122:125], v[78:81], v[174:177], v[122:125]
	v_mfma_f32_16x16x32_bf16 v[110:113], v[70:73], v[182:185], v[110:113]
	v_mfma_f32_16x16x32_bf16 v[106:109], v[78:81], v[182:185], v[106:109]
	v_mfma_f32_16x16x32_bf16 v[94:97], v[70:73], v[190:193], v[94:97]
	v_mfma_f32_16x16x32_bf16 v[90:93], v[78:81], v[190:193], v[90:93]
	v_mfma_f32_16x16x32_bf16 v[134:137], v[146:149], v[162:165], v[134:137]
	v_mfma_f32_16x16x32_bf16 v[130:133], v[154:157], v[162:165], v[130:133]
	v_mfma_f32_16x16x32_bf16 v[118:121], v[146:149], v[170:173], v[118:121]
	v_mfma_f32_16x16x32_bf16 v[114:117], v[154:157], v[170:173], v[114:117]
	v_mfma_f32_16x16x32_bf16 v[102:105], v[146:149], v[178:181], v[102:105]
	v_mfma_f32_16x16x32_bf16 v[98:101], v[154:157], v[178:181], v[98:101]
	v_mfma_f32_16x16x32_bf16 v[86:89], v[146:149], v[186:189], v[86:89]
	v_mfma_f32_16x16x32_bf16 v[82:85], v[154:157], v[186:189], v[82:85]
	v_mfma_f32_16x16x32_bf16 v[134:137], v[150:153], v[166:169], v[134:137]
	v_mfma_f32_16x16x32_bf16 v[130:133], v[158:161], v[166:169], v[130:133]
	v_mfma_f32_16x16x32_bf16 v[118:121], v[150:153], v[174:177], v[118:121]
	v_mfma_f32_16x16x32_bf16 v[114:117], v[158:161], v[174:177], v[114:117]
	v_mfma_f32_16x16x32_bf16 v[102:105], v[150:153], v[182:185], v[102:105]
	v_mfma_f32_16x16x32_bf16 v[98:101], v[158:161], v[182:185], v[98:101]
	v_mfma_f32_16x16x32_bf16 v[86:89], v[150:153], v[190:193], v[86:89]
	v_mfma_f32_16x16x32_bf16 v[82:85], v[158:161], v[190:193], v[82:85]
	s_barrier
	s_add_i32 s52, s85, s40
	v_lshl_add_u64 v[194:195], s[36:37], 0, v[222:223]
	s_mov_b32 m0, s52
	ds_read_b128 v[162:165], v211 offset:16384
	ds_read_b128 v[166:169], v211 offset:17408
	ds_read_b128 v[170:173], v211 offset:18432
	ds_read_b128 v[174:177], v211 offset:19456
	ds_read_b128 v[178:181], v211 offset:20480
	ds_read_b128 v[182:185], v211 offset:21504
	ds_read_b128 v[186:189], v211 offset:22528
	ds_read_b128 v[190:193], v211 offset:23552
	global_load_lds_dwordx4 v[194:195], off
	s_add_i32 m0, s52, 0x2000
	s_add_u32 s52, s36, 0xb0000
	v_lshl_add_u64 v[196:197], s[36:37], 0, v[226:227]
	s_addc_u32 s53, s37, 0
	s_add_i32 s85, s86, s40
	global_load_lds_dwordx4 v[196:197], off
	v_lshl_add_u64 v[198:199], s[52:53], 0, v[222:223]
	s_mov_b32 m0, s85
	v_lshl_add_u64 v[200:201], s[38:39], 0, v[224:225]
	global_load_lds_dwordx4 v[198:199], off
	v_lshl_add_u64 v[198:199], s[52:53], 0, v[226:227]
	s_add_i32 m0, s85, 0x2000
	s_nop 0
	global_load_lds_dwordx4 v[198:199], off
	v_lshl_add_u64 v[198:199], s[38:39], 0, v[220:221]
	s_mov_b32 m0, s41
	s_nop 0
	global_load_lds_dwordx4 v[198:199], off
	s_mov_b32 m0, s70
	s_nop 0
	global_load_lds_dwordx4 v[200:201], off
	s_cmp_lg_u32 s98, 0
	s_cbranch_scc1 .Lrw_dn_2
	s_waitcnt vmcnt(8)
.Lrw_dn_2:
	s_mov_b32 s98, 0
	s_waitcnt lgkmcnt(0)
	s_barrier
	s_waitcnt lgkmcnt(0)
	v_mfma_f32_16x16x32_bf16 v[62:65], v[66:69], v[162:165], v[62:65]
	v_mfma_f32_16x16x32_bf16 v[58:61], v[74:77], v[162:165], v[58:61]
	v_mfma_f32_16x16x32_bf16 v[46:49], v[66:69], v[170:173], v[46:49]
	v_mfma_f32_16x16x32_bf16 v[42:45], v[74:77], v[170:173], v[42:45]
	v_mfma_f32_16x16x32_bf16 v[30:33], v[66:69], v[178:181], v[30:33]
	v_mfma_f32_16x16x32_bf16 v[26:29], v[74:77], v[178:181], v[26:29]
	v_mfma_f32_16x16x32_bf16 v[14:17], v[66:69], v[186:189], v[14:17]
	v_mfma_f32_16x16x32_bf16 v[10:13], v[74:77], v[186:189], v[10:13]
	v_mfma_f32_16x16x32_bf16 v[62:65], v[70:73], v[166:169], v[62:65]
	v_mfma_f32_16x16x32_bf16 v[58:61], v[78:81], v[166:169], v[58:61]
	v_mfma_f32_16x16x32_bf16 v[46:49], v[70:73], v[174:177], v[46:49]
	v_mfma_f32_16x16x32_bf16 v[42:45], v[78:81], v[174:177], v[42:45]
	v_mfma_f32_16x16x32_bf16 v[30:33], v[70:73], v[182:185], v[30:33]
	v_mfma_f32_16x16x32_bf16 v[26:29], v[78:81], v[182:185], v[26:29]
	v_mfma_f32_16x16x32_bf16 v[14:17], v[70:73], v[190:193], v[14:17]
	v_mfma_f32_16x16x32_bf16 v[10:13], v[78:81], v[190:193], v[10:13]
	v_mfma_f32_16x16x32_bf16 v[54:57], v[146:149], v[162:165], v[54:57]
	v_mfma_f32_16x16x32_bf16 v[50:53], v[154:157], v[162:165], v[50:53]
	v_mfma_f32_16x16x32_bf16 v[38:41], v[146:149], v[170:173], v[38:41]
	v_mfma_f32_16x16x32_bf16 v[34:37], v[154:157], v[170:173], v[34:37]
	v_mfma_f32_16x16x32_bf16 v[22:25], v[146:149], v[178:181], v[22:25]
	v_mfma_f32_16x16x32_bf16 v[18:21], v[154:157], v[178:181], v[18:21]
	v_mfma_f32_16x16x32_bf16 v[6:9], v[146:149], v[186:189], v[6:9]
	v_mfma_f32_16x16x32_bf16 v[2:5], v[154:157], v[186:189], v[2:5]
	v_mfma_f32_16x16x32_bf16 v[54:57], v[150:153], v[166:169], v[54:57]
	v_mfma_f32_16x16x32_bf16 v[50:53], v[158:161], v[166:169], v[50:53]
	v_mfma_f32_16x16x32_bf16 v[38:41], v[150:153], v[174:177], v[38:41]
	v_mfma_f32_16x16x32_bf16 v[34:37], v[158:161], v[174:177], v[34:37]
	v_mfma_f32_16x16x32_bf16 v[22:25], v[150:153], v[182:185], v[22:25]
	v_mfma_f32_16x16x32_bf16 v[18:21], v[158:161], v[182:185], v[18:21]
	v_mfma_f32_16x16x32_bf16 v[6:9], v[150:153], v[190:193], v[6:9]
	v_mfma_f32_16x16x32_bf16 v[2:5], v[158:161], v[190:193], v[2:5]
	s_barrier
; #define PG8_STAGE(bufoff, gbase, voff) do { _Pragma("unroll") for (int _i = 0; _i < 2; ++_i) \
;         __builtin_amdgcn_global_load_lds((const unsigned*)((const char*)(gbase) + (voff)[_i]), (PG8_LAS unsigned*)(lds + (bufoff) + ldsw + _i * 8192), 16, 0, 0); } while (0)
; #define PG8_LDA(dst, b, h) do { _Pragma("unroll") for (int m = 0; m < 4; ++m) _Pragma("unroll") for (int k = 0; k < 2; ++k) dst[m][k] = *(const PG8_LAS bf16x8*)(lds + PG8_SA(b, h) + aoff + m * 2048 + k * 1024); } while (0)
; #define PG8_LDB(dst, b, h) do { _Pragma("unroll") for (int n = 0; n < 2; ++n) _Pragma("unroll") for (int k = 0; k < 2; ++k) dst[n][k] = *(const PG8_LAS bf16x8*)(lds + PG8_SB(b, h) + boff + n * 2048 + k * 1024); } while (0)
; #define PG8_MMA(ai, bj, At, Bt) do { __builtin_amdgcn_s_setprio(1); _Pragma("unroll") for (int m = 0; m < 4; ++m) _Pragma("unroll") for (int n = 0; n < 2; ++n) _Pragma("unroll") for (int k = 0; k < 2; ++k) \
;         acc[ai][bj][m][n] = __builtin_amdgcn_mfma_f32_16x16x32_bf16(Bt[n][k], At[m][k], acc[ai][bj][m][n], 0, 0, 0); __builtin_amdgcn_s_setprio(0); } while (0)
; #define PG8_WAIT_V(n) asm volatile("s_waitcnt vmcnt(" #n ")" ::: "memory")
; #define PG8_WAIT_L(n) asm volatile("s_waitcnt lgkmcnt(" #n ")" ::: "memory")
; #define PG8_BAR __builtin_amdgcn_s_barrier()
; #define PG8_SCHED __builtin_amdgcn_sched_barrier(0)
; template <class Epi, class Sched, bool ALIGN_EPI = false, bool SP2 = false>
; __device__ __forceinline__ void gemm_phase(PG8_LAS unsigned char* lds, const Gemm g, const Sched& S, const Epi& E) {
;     ...
;             PG8_LDB(B0, 1, 0); PG8_LDB(B1, 1, 1); PG8_SCHED; PG8_LDA(At, 1, 0); PG8_STAGE(PG8_SA(0, 1), a2 + hstep, voffA);
;             PG8_WAIT_V(8); PG8_WAIT_L(0); PG8_BAR; PG8_MMA(0, 0, At, B0); PG8_MMA(0, 1, At, B1); PG8_BAR; PG8_SCHED;
;             PG8_LDA(At, 1, 1); PG8_STAGE(PG8_SB(1, 0), b3, voffB); PG8_STAGE(PG8_SB(1, 1), b3 + hstep, voffB); PG8_STAGE(PG8_SA(1, 0), a3, voffA);
;             PG8_WAIT_V(8); PG8_WAIT_L(0); PG8_BAR; PG8_MMA(1, 0, At, B0); PG8_MMA(1, 1, At, B1); PG8_BAR; PG8_SCHED;
	s_add_i32 s52, 0, 0x18000
	v_add_u32_e32 v0, s52, v210
	s_add_i32 s53, 0, 0x1c000
	ds_read_b128 v[66:69], v0
	ds_read_b128 v[70:73], v0 offset:1024
	ds_read_b128 v[74:77], v0 offset:2048
	ds_read_b128 v[78:81], v0 offset:3072
	v_add_u32_e32 v0, s53, v210
	ds_read_b128 v[146:149], v0
	ds_read_b128 v[150:153], v0 offset:1024
	ds_read_b128 v[154:157], v0 offset:2048
	ds_read_b128 v[158:161], v0 offset:3072
	s_add_u32 s38, s38, 0xb0000
	s_addc_u32 s39, s39, 0
	s_mov_b32 m0, s71
	v_lshl_add_u64 v[202:203], s[38:39], 0, v[220:221]
	ds_read_b128 v[162:165], v211 offset:32768
	ds_read_b128 v[166:169], v211 offset:33792
	ds_read_b128 v[170:173], v211 offset:34816
	ds_read_b128 v[174:177], v211 offset:35840
	ds_read_b128 v[178:181], v211 offset:36864
	ds_read_b128 v[182:185], v211 offset:37888
	ds_read_b128 v[186:189], v211 offset:38912
	ds_read_b128 v[190:193], v211 offset:39936
	global_load_lds_dwordx4 v[202:203], off
	v_lshl_add_u64 v[202:203], s[38:39], 0, v[224:225]
	s_mov_b32 m0, s72
	s_nop 0
	global_load_lds_dwordx4 v[202:203], off
	s_waitcnt vmcnt(8)
	s_waitcnt lgkmcnt(0)
	s_barrier
	s_waitcnt lgkmcnt(0)
	v_mfma_f32_16x16x32_bf16 v[142:145], v[66:69], v[162:165], v[142:145]
	v_mfma_f32_16x16x32_bf16 v[138:141], v[74:77], v[162:165], v[138:141]
	v_mfma_f32_16x16x32_bf16 v[126:129], v[66:69], v[170:173], v[126:129]
	v_mfma_f32_16x16x32_bf16 v[122:125], v[74:77], v[170:173], v[122:125]
	v_mfma_f32_16x16x32_bf16 v[110:113], v[66:69], v[178:181], v[110:113]
	v_mfma_f32_16x16x32_bf16 v[106:109], v[74:77], v[178:181], v[106:109]
	v_mfma_f32_16x16x32_bf16 v[94:97], v[66:69], v[186:189], v[94:97]
	v_mfma_f32_16x16x32_bf16 v[90:93], v[74:77], v[186:189], v[90:93]
	v_mfma_f32_16x16x32_bf16 v[142:145], v[70:73], v[166:169], v[142:145]
	v_mfma_f32_16x16x32_bf16 v[138:141], v[78:81], v[166:169], v[138:141]
	v_mfma_f32_16x16x32_bf16 v[126:129], v[70:73], v[174:177], v[126:129]
	v_mfma_f32_16x16x32_bf16 v[122:125], v[78:81], v[174:177], v[122:125]
	v_mfma_f32_16x16x32_bf16 v[110:113], v[70:73], v[182:185], v[110:113]
	v_mfma_f32_16x16x32_bf16 v[106:109], v[78:81], v[182:185], v[106:109]
	v_mfma_f32_16x16x32_bf16 v[94:97], v[70:73], v[190:193], v[94:97]
	v_mfma_f32_16x16x32_bf16 v[90:93], v[78:81], v[190:193], v[90:93]
	v_mfma_f32_16x16x32_bf16 v[134:137], v[146:149], v[162:165], v[134:137]
	v_mfma_f32_16x16x32_bf16 v[130:133], v[154:157], v[162:165], v[130:133]
	v_mfma_f32_16x16x32_bf16 v[118:121], v[146:149], v[170:173], v[118:121]
	v_mfma_f32_16x16x32_bf16 v[114:117], v[154:157], v[170:173], v[114:117]
	v_mfma_f32_16x16x32_bf16 v[102:105], v[146:149], v[178:181], v[102:105]
	v_mfma_f32_16x16x32_bf16 v[98:101], v[154:157], v[178:181], v[98:101]
	v_mfma_f32_16x16x32_bf16 v[86:89], v[146:149], v[186:189], v[86:89]
	v_mfma_f32_16x16x32_bf16 v[82:85], v[154:157], v[186:189], v[82:85]
	v_mfma_f32_16x16x32_bf16 v[134:137], v[150:153], v[166:169], v[134:137]
	v_mfma_f32_16x16x32_bf16 v[130:133], v[158:161], v[166:169], v[130:133]
	v_mfma_f32_16x16x32_bf16 v[118:121], v[150:153], v[174:177], v[118:121]
	v_mfma_f32_16x16x32_bf16 v[114:117], v[158:161], v[174:177], v[114:117]
	v_mfma_f32_16x16x32_bf16 v[102:105], v[150:153], v[182:185], v[102:105]
	v_mfma_f32_16x16x32_bf16 v[98:101], v[158:161], v[182:185], v[98:101]
	v_mfma_f32_16x16x32_bf16 v[86:89], v[150:153], v[190:193], v[86:89]
	v_mfma_f32_16x16x32_bf16 v[82:85], v[158:161], v[190:193], v[82:85]
	s_barrier
	s_add_i32 s38, s52, s40
	v_lshl_add_u64 v[194:195], v[194:195], 0, s[28:29]
	s_mov_b32 m0, s38
	ds_read_b128 v[162:165], v211 offset:49152
	ds_read_b128 v[166:169], v211 offset:50176
	ds_read_b128 v[170:173], v211 offset:51200
	ds_read_b128 v[174:177], v211 offset:52224
	ds_read_b128 v[178:181], v211 offset:53248
	ds_read_b128 v[182:185], v211 offset:54272
	ds_read_b128 v[186:189], v211 offset:55296
	ds_read_b128 v[190:193], v211 offset:56320
	global_load_lds_dwordx4 v[194:195], off
	s_add_i32 m0, s38, 0x2000
	s_add_u32 s36, s36, 0xb0080
	v_lshl_add_u64 v[194:195], v[196:197], 0, s[28:29]
	s_addc_u32 s37, s37, 0
	s_add_i32 s38, s53, s40
	global_load_lds_dwordx4 v[194:195], off
	v_lshl_add_u64 v[194:195], s[36:37], 0, v[222:223]
	s_mov_b32 m0, s38
	s_nop 0
	global_load_lds_dwordx4 v[194:195], off
	v_lshl_add_u64 v[194:195], s[36:37], 0, v[226:227]
	s_add_i32 m0, s38, 0x2000
	s_nop 0
	global_load_lds_dwordx4 v[194:195], off
	v_lshl_add_u64 v[194:195], v[198:199], 0, s[28:29]
	s_mov_b32 m0, s75
	s_nop 0
	global_load_lds_dwordx4 v[194:195], off
	v_lshl_add_u64 v[194:195], v[200:201], 0, s[28:29]
	s_mov_b32 m0, s76
	s_nop 0
	global_load_lds_dwordx4 v[194:195], off
	s_waitcnt vmcnt(8)
	s_waitcnt lgkmcnt(0)
	s_barrier
	s_waitcnt lgkmcnt(0)
	v_mfma_f32_16x16x32_bf16 v[62:65], v[66:69], v[162:165], v[62:65]
	v_mfma_f32_16x16x32_bf16 v[58:61], v[74:77], v[162:165], v[58:61]
	v_mfma_f32_16x16x32_bf16 v[46:49], v[66:69], v[170:173], v[46:49]
	v_mfma_f32_16x16x32_bf16 v[42:45], v[74:77], v[170:173], v[42:45]
	v_mfma_f32_16x16x32_bf16 v[30:33], v[66:69], v[178:181], v[30:33]
	v_mfma_f32_16x16x32_bf16 v[26:29], v[74:77], v[178:181], v[26:29]
	v_mfma_f32_16x16x32_bf16 v[14:17], v[66:69], v[186:189], v[14:17]
	v_mfma_f32_16x16x32_bf16 v[10:13], v[74:77], v[186:189], v[10:13]
	v_mfma_f32_16x16x32_bf16 v[62:65], v[70:73], v[166:169], v[62:65]
	v_mfma_f32_16x16x32_bf16 v[58:61], v[78:81], v[166:169], v[58:61]
	v_mfma_f32_16x16x32_bf16 v[46:49], v[70:73], v[174:177], v[46:49]
	v_mfma_f32_16x16x32_bf16 v[42:45], v[78:81], v[174:177], v[42:45]
	v_mfma_f32_16x16x32_bf16 v[30:33], v[70:73], v[182:185], v[30:33]
	v_mfma_f32_16x16x32_bf16 v[26:29], v[78:81], v[182:185], v[26:29]
	v_mfma_f32_16x16x32_bf16 v[14:17], v[70:73], v[190:193], v[14:17]
	v_mfma_f32_16x16x32_bf16 v[10:13], v[78:81], v[190:193], v[10:13]
	v_mfma_f32_16x16x32_bf16 v[54:57], v[146:149], v[162:165], v[54:57]
	v_mfma_f32_16x16x32_bf16 v[50:53], v[154:157], v[162:165], v[50:53]
	v_mfma_f32_16x16x32_bf16 v[38:41], v[146:149], v[170:173], v[38:41]
	v_mfma_f32_16x16x32_bf16 v[34:37], v[154:157], v[170:173], v[34:37]
	v_mfma_f32_16x16x32_bf16 v[22:25], v[146:149], v[178:181], v[22:25]
	v_mfma_f32_16x16x32_bf16 v[18:21], v[154:157], v[178:181], v[18:21]
	v_mfma_f32_16x16x32_bf16 v[6:9], v[146:149], v[186:189], v[6:9]
	v_mfma_f32_16x16x32_bf16 v[2:5], v[154:157], v[186:189], v[2:5]
	v_mfma_f32_16x16x32_bf16 v[54:57], v[150:153], v[166:169], v[54:57]
	v_mfma_f32_16x16x32_bf16 v[50:53], v[158:161], v[166:169], v[50:53]
	v_mfma_f32_16x16x32_bf16 v[38:41], v[150:153], v[174:177], v[38:41]
	v_mfma_f32_16x16x32_bf16 v[34:37], v[158:161], v[174:177], v[34:37]
	v_mfma_f32_16x16x32_bf16 v[22:25], v[150:153], v[182:185], v[22:25]
	v_mfma_f32_16x16x32_bf16 v[18:21], v[158:161], v[182:185], v[18:21]
	v_mfma_f32_16x16x32_bf16 v[6:9], v[150:153], v[190:193], v[6:9]
	v_mfma_f32_16x16x32_bf16 v[2:5], v[158:161], v[190:193], v[2:5]
	s_barrier
	s_add_i32 s84, s84, 2
	s_add_u32 s82, s82, 0x100
	s_addc_u32 s83, s83, 0
	s_cmp_gt_u32 s84, 41
	s_mov_b64 s[52:53], s[4:5]
	s_cbranch_scc0 .LBB0_264
	s_and_b64 vcc, exec, s[6:7]
	s_cbranch_vccz .LBB0_267
	s_barrier

; #define PG8_STAGE(bufoff, gbase, voff) do { _Pragma("unroll") for (int _i = 0; _i < 2; ++_i) \
;         __builtin_amdgcn_global_load_lds((const unsigned*)((const char*)(gbase) + (voff)[_i]), (PG8_LAS unsigned*)(lds + (bufoff) + ldsw + _i * 8192), 16, 0, 0); } while (0)
; #define PG8_LDA(dst, b, h) do { _Pragma("unroll") for (int m = 0; m < 4; ++m) _Pragma("unroll") for (int k = 0; k < 2; ++k) dst[m][k] = *(const PG8_LAS bf16x8*)(lds + PG8_SA(b, h) + aoff + m * 2048 + k * 1024); } while (0)
; #define PG8_LDB(dst, b, h) do { _Pragma("unroll") for (int n = 0; n < 2; ++n) _Pragma("unroll") for (int k = 0; k < 2; ++k) dst[n][k] = *(const PG8_LAS bf16x8*)(lds + PG8_SB(b, h) + boff + n * 2048 + k * 1024); } while (0)
; #define PG8_MMA(ai, bj, At, Bt) do { __builtin_amdgcn_s_setprio(1); _Pragma("unroll") for (int m = 0; m < 4; ++m) _Pragma("unroll") for (int n = 0; n < 2; ++n) _Pragma("unroll") for (int k = 0; k < 2; ++k) \
;         acc[ai][bj][m][n] = __builtin_amdgcn_mfma_f32_16x16x32_bf16(Bt[n][k], At[m][k], acc[ai][bj][m][n], 0, 0, 0); __builtin_amdgcn_s_setprio(0); } while (0)
; #define PG8_WAIT_V(n) asm volatile("s_waitcnt vmcnt(" #n ")" ::: "memory")
; #define PG8_WAIT_L(n) asm volatile("s_waitcnt lgkmcnt(" #n ")" ::: "memory")
; #define PG8_BAR __builtin_amdgcn_s_barrier()
; #define PG8_SCHED __builtin_amdgcn_sched_barrier(0)
; template <class Epi, class Sched, bool ALIGN_EPI = false, bool SP2 = false>
; __device__ __forceinline__ void gemm_phase(PG8_LAS unsigned char* lds, const Gemm g, const Sched& S, const Epi& E) {
;     ...
;             PG8_LDB(B0, 0, 0); PG8_LDB(B1, 0, 1); PG8_SCHED; PG8_LDA(At, 0, 0); PG8_STAGE(PG8_SA(1, 1), a1 + hstep, voffA);
;             PG8_WAIT_V(8); PG8_WAIT_L(0); PG8_BAR; PG8_MMA(0, 0, At, B0); PG8_MMA(0, 1, At, B1); PG8_BAR; PG8_SCHED;
;             PG8_LDA(At, 0, 1); PG8_STAGE(PG8_SB(0, 0), b2, voffB); PG8_STAGE(PG8_SB(0, 1), b2 + hstep, voffB); PG8_STAGE(PG8_SA(0, 0), a2, voffA);
;             PG8_WAIT_V(8); PG8_WAIT_L(0); PG8_BAR; PG8_MMA(1, 0, At, B0); PG8_MMA(1, 1, At, B1); PG8_BAR; PG8_SCHED;
.Lrw_dl_1:
	s_waitcnt lgkmcnt(0)
	s_barrier
	s_waitcnt lgkmcnt(0)
	v_mfma_f32_16x16x32_bf16 v[126:129], v[130:133], v[162:165], v[126:129]
	v_mfma_f32_16x16x32_bf16 v[122:125], v[138:141], v[162:165], v[122:125]
	v_mfma_f32_16x16x32_bf16 v[118:121], v[130:133], v[170:173], v[118:121]
	v_mfma_f32_16x16x32_bf16 v[110:113], v[138:141], v[170:173], v[110:113]
	v_mfma_f32_16x16x32_bf16 v[102:105], v[130:133], v[190:193], v[102:105]
	v_mfma_f32_16x16x32_bf16 v[94:97], v[138:141], v[190:193], v[94:97]
	v_mfma_f32_16x16x32_bf16 v[78:81], v[130:133], v[198:201], v[78:81]
	v_mfma_f32_16x16x32_bf16 v[74:77], v[138:141], v[198:201], v[74:77]
	v_mfma_f32_16x16x32_bf16 v[126:129], v[134:137], v[166:169], v[126:129]
	v_mfma_f32_16x16x32_bf16 v[122:125], v[142:145], v[166:169], v[122:125]
	v_mfma_f32_16x16x32_bf16 v[118:121], v[134:137], v[174:177], v[118:121]
	v_mfma_f32_16x16x32_bf16 v[110:113], v[142:145], v[174:177], v[110:113]
	v_mfma_f32_16x16x32_bf16 v[102:105], v[134:137], v[194:197], v[102:105]
	v_mfma_f32_16x16x32_bf16 v[94:97], v[142:145], v[194:197], v[94:97]
	v_mfma_f32_16x16x32_bf16 v[78:81], v[134:137], v[206:209], v[78:81]
	v_mfma_f32_16x16x32_bf16 v[74:77], v[142:145], v[206:209], v[74:77]
	v_mfma_f32_16x16x32_bf16 v[114:117], v[146:149], v[162:165], v[114:117]
	v_mfma_f32_16x16x32_bf16 v[106:109], v[154:157], v[162:165], v[106:109]
	v_mfma_f32_16x16x32_bf16 v[98:101], v[146:149], v[170:173], v[98:101]
	v_mfma_f32_16x16x32_bf16 v[90:93], v[154:157], v[170:173], v[90:93]
	v_mfma_f32_16x16x32_bf16 v[86:89], v[146:149], v[190:193], v[86:89]
	v_mfma_f32_16x16x32_bf16 v[82:85], v[154:157], v[190:193], v[82:85]
	v_mfma_f32_16x16x32_bf16 v[70:73], v[146:149], v[198:201], v[70:73]
	v_mfma_f32_16x16x32_bf16 v[66:69], v[154:157], v[198:201], v[66:69]
	v_mfma_f32_16x16x32_bf16 v[114:117], v[150:153], v[166:169], v[114:117]
	v_mfma_f32_16x16x32_bf16 v[106:109], v[158:161], v[166:169], v[106:109]
	v_mfma_f32_16x16x32_bf16 v[98:101], v[150:153], v[174:177], v[98:101]
	v_mfma_f32_16x16x32_bf16 v[90:93], v[158:161], v[174:177], v[90:93]
	v_mfma_f32_16x16x32_bf16 v[86:89], v[150:153], v[194:197], v[86:89]
	v_mfma_f32_16x16x32_bf16 v[82:85], v[158:161], v[194:197], v[82:85]
	v_mfma_f32_16x16x32_bf16 v[70:73], v[150:153], v[206:209], v[70:73]
	v_mfma_f32_16x16x32_bf16 v[66:69], v[158:161], v[206:209], v[66:69]
	s_barrier
	s_add_i32 s22, s77, s38
	v_lshl_add_u64 v[202:203], s[26:27], 0, v[180:181]
	s_mov_b32 m0, s22
	ds_read_b128 v[162:165], v205 offset:16384
	ds_read_b128 v[166:169], v205 offset:17408
	ds_read_b128 v[170:173], v205 offset:18432
	ds_read_b128 v[174:177], v205 offset:19456
	ds_read_b128 v[190:193], v205 offset:20480
	ds_read_b128 v[194:197], v205 offset:21504
	ds_read_b128 v[198:201], v205 offset:22528
	ds_read_b128 v[206:209], v205 offset:23552
	global_load_lds_dwordx4 v[202:203], off
	s_add_i32 m0, s22, 0x2000
	s_add_u32 s22, s26, 0xb0000
	v_lshl_add_u64 v[210:211], s[26:27], 0, v[184:185]
	s_addc_u32 s23, s27, 0
	s_add_i32 s77, s78, s38
	global_load_lds_dwordx4 v[210:211], off
	v_lshl_add_u64 v[220:221], s[22:23], 0, v[180:181]
	s_mov_b32 m0, s77
	v_lshl_add_u64 v[222:223], s[36:37], 0, v[182:183]
	global_load_lds_dwordx4 v[220:221], off
	v_lshl_add_u64 v[220:221], s[22:23], 0, v[184:185]
	s_add_i32 m0, s77, 0x2000
	s_nop 0
	global_load_lds_dwordx4 v[220:221], off
	v_lshl_add_u64 v[220:221], s[36:37], 0, v[178:179]
	s_mov_b32 m0, s39
	s_nop 0
	global_load_lds_dwordx4 v[220:221], off
	s_mov_b32 m0, s40
	s_nop 0
	global_load_lds_dwordx4 v[222:223], off
	s_cmp_lg_u32 s98, 0
	s_cbranch_scc1 .Lrw_dl_2
	s_waitcnt vmcnt(8)
.Lrw_dl_2:
	s_mov_b32 s98, 0
	s_waitcnt lgkmcnt(0)
	s_barrier
	s_waitcnt lgkmcnt(0)
	v_mfma_f32_16x16x32_bf16 v[62:65], v[130:133], v[162:165], v[62:65]
	v_mfma_f32_16x16x32_bf16 v[58:61], v[138:141], v[162:165], v[58:61]
	v_mfma_f32_16x16x32_bf16 v[54:57], v[130:133], v[170:173], v[54:57]
	v_mfma_f32_16x16x32_bf16 v[46:49], v[138:141], v[170:173], v[46:49]
	v_mfma_f32_16x16x32_bf16 v[38:41], v[130:133], v[190:193], v[38:41]
	v_mfma_f32_16x16x32_bf16 v[30:33], v[138:141], v[190:193], v[30:33]
	v_mfma_f32_16x16x32_bf16 v[14:17], v[130:133], v[198:201], v[14:17]
	v_mfma_f32_16x16x32_bf16 v[10:13], v[138:141], v[198:201], v[10:13]
	v_mfma_f32_16x16x32_bf16 v[62:65], v[134:137], v[166:169], v[62:65]
	v_mfma_f32_16x16x32_bf16 v[58:61], v[142:145], v[166:169], v[58:61]
	v_mfma_f32_16x16x32_bf16 v[54:57], v[134:137], v[174:177], v[54:57]
	v_mfma_f32_16x16x32_bf16 v[46:49], v[142:145], v[174:177], v[46:49]
	v_mfma_f32_16x16x32_bf16 v[38:41], v[134:137], v[194:197], v[38:41]
	v_mfma_f32_16x16x32_bf16 v[30:33], v[142:145], v[194:197], v[30:33]
	v_mfma_f32_16x16x32_bf16 v[14:17], v[134:137], v[206:209], v[14:17]
	v_mfma_f32_16x16x32_bf16 v[10:13], v[142:145], v[206:209], v[10:13]
	v_mfma_f32_16x16x32_bf16 v[50:53], v[146:149], v[162:165], v[50:53]
	v_mfma_f32_16x16x32_bf16 v[42:45], v[154:157], v[162:165], v[42:45]
	v_mfma_f32_16x16x32_bf16 v[34:37], v[146:149], v[170:173], v[34:37]
	v_mfma_f32_16x16x32_bf16 v[26:29], v[154:157], v[170:173], v[26:29]
	v_mfma_f32_16x16x32_bf16 v[22:25], v[146:149], v[190:193], v[22:25]
	v_mfma_f32_16x16x32_bf16 v[18:21], v[154:157], v[190:193], v[18:21]
	v_mfma_f32_16x16x32_bf16 v[6:9], v[146:149], v[198:201], v[6:9]
	v_mfma_f32_16x16x32_bf16 v[2:5], v[154:157], v[198:201], v[2:5]
	v_mfma_f32_16x16x32_bf16 v[50:53], v[150:153], v[166:169], v[50:53]
	v_mfma_f32_16x16x32_bf16 v[42:45], v[158:161], v[166:169], v[42:45]
	v_mfma_f32_16x16x32_bf16 v[34:37], v[150:153], v[174:177], v[34:37]
	v_mfma_f32_16x16x32_bf16 v[26:29], v[158:161], v[174:177], v[26:29]
	v_mfma_f32_16x16x32_bf16 v[22:25], v[150:153], v[194:197], v[22:25]
	v_mfma_f32_16x16x32_bf16 v[18:21], v[158:161], v[194:197], v[18:21]
	v_mfma_f32_16x16x32_bf16 v[6:9], v[150:153], v[206:209], v[6:9]
	v_mfma_f32_16x16x32_bf16 v[2:5], v[158:161], v[206:209], v[2:5]
	s_barrier
; #define PG8_STAGE(bufoff, gbase, voff) do { _Pragma("unroll") for (int _i = 0; _i < 2; ++_i) \
;         __builtin_amdgcn_global_load_lds((const unsigned*)((const char*)(gbase) + (voff)[_i]), (PG8_LAS unsigned*)(lds + (bufoff) + ldsw + _i * 8192), 16, 0, 0); } while (0)
; #define PG8_LDA(dst, b, h) do { _Pragma("unroll") for (int m = 0; m < 4; ++m) _Pragma("unroll") for (int k = 0; k < 2; ++k) dst[m][k] = *(const PG8_LAS bf16x8*)(lds + PG8_SA(b, h) + aoff + m * 2048 + k * 1024); } while (0)
; #define PG8_LDB(dst, b, h) do { _Pragma("unroll") for (int n = 0; n < 2; ++n) _Pragma("unroll") for (int k = 0; k < 2; ++k) dst[n][k] = *(const PG8_LAS bf16x8*)(lds + PG8_SB(b, h) + boff + n * 2048 + k * 1024); } while (0)
; #define PG8_MMA(ai, bj, At, Bt) do { __builtin_amdgcn_s_setprio(1); _Pragma("unroll") for (int m = 0; m < 4; ++m) _Pragma("unroll") for (int n = 0; n < 2; ++n) _Pragma("unroll") for (int k = 0; k < 2; ++k) \
;         acc[ai][bj][m][n] = __builtin_amdgcn_mfma_f32_16x16x32_bf16(Bt[n][k], At[m][k], acc[ai][bj][m][n], 0, 0, 0); __builtin_amdgcn_s_setprio(0); } while (0)
; #define PG8_WAIT_V(n) asm volatile("s_waitcnt vmcnt(" #n ")" ::: "memory")
; #define PG8_WAIT_L(n) asm volatile("s_waitcnt lgkmcnt(" #n ")" ::: "memory")
; #define PG8_BAR __builtin_amdgcn_s_barrier()
; #define PG8_SCHED __builtin_amdgcn_sched_barrier(0)
; template <class Epi, class Sched, bool ALIGN_EPI = false, bool SP2 = false>
; __device__ __forceinline__ void gemm_phase(PG8_LAS unsigned char* lds, const Gemm g, const Sched& S, const Epi& E) {
;     ...
;             PG8_LDB(B0, 1, 0); PG8_LDB(B1, 1, 1); PG8_SCHED; PG8_LDA(At, 1, 0); PG8_STAGE(PG8_SA(0, 1), a2 + hstep, voffA);
;             PG8_WAIT_V(8); PG8_WAIT_L(0); PG8_BAR; PG8_MMA(0, 0, At, B0); PG8_MMA(0, 1, At, B1); PG8_BAR; PG8_SCHED;
	s_add_i32 s77, 0, 0x18000
	v_add_u32_e32 v0, s77, v204
	s_add_i32 s78, 0, 0x1c000
	ds_read_b128 v[130:133], v0
	ds_read_b128 v[134:137], v0 offset:1024
	ds_read_b128 v[138:141], v0 offset:2048
	ds_read_b128 v[142:145], v0 offset:3072
	v_add_u32_e32 v0, s78, v204
	ds_read_b128 v[146:149], v0
	ds_read_b128 v[150:153], v0 offset:1024
	ds_read_b128 v[154:157], v0 offset:2048
	ds_read_b128 v[158:161], v0 offset:3072
	s_add_u32 s22, s36, 0xb0000
	s_addc_u32 s23, s37, 0
	s_mov_b32 m0, s41
	v_lshl_add_u64 v[224:225], s[22:23], 0, v[178:179]
	ds_read_b128 v[162:165], v205 offset:32768
	ds_read_b128 v[166:169], v205 offset:33792
	ds_read_b128 v[170:173], v205 offset:34816
	ds_read_b128 v[174:177], v205 offset:35840
	ds_read_b128 v[190:193], v205 offset:36864
	ds_read_b128 v[194:197], v205 offset:37888
	ds_read_b128 v[198:201], v205 offset:38912
	ds_read_b128 v[206:209], v205 offset:39936
	global_load_lds_dwordx4 v[224:225], off
	v_lshl_add_u64 v[224:225], s[22:23], 0, v[182:183]
	s_mov_b32 m0, s52
	s_nop 0
	global_load_lds_dwordx4 v[224:225], off
	s_waitcnt vmcnt(8)
	s_waitcnt lgkmcnt(0)
	s_barrier
	s_waitcnt lgkmcnt(0)
	v_mfma_f32_16x16x32_bf16 v[126:129], v[130:133], v[162:165], v[126:129]
	v_mfma_f32_16x16x32_bf16 v[122:125], v[138:141], v[162:165], v[122:125]
	v_mfma_f32_16x16x32_bf16 v[118:121], v[130:133], v[170:173], v[118:121]
	v_mfma_f32_16x16x32_bf16 v[110:113], v[138:141], v[170:173], v[110:113]
	v_mfma_f32_16x16x32_bf16 v[102:105], v[130:133], v[190:193], v[102:105]
	v_mfma_f32_16x16x32_bf16 v[94:97], v[138:141], v[190:193], v[94:97]
	v_mfma_f32_16x16x32_bf16 v[78:81], v[130:133], v[198:201], v[78:81]
	v_mfma_f32_16x16x32_bf16 v[74:77], v[138:141], v[198:201], v[74:77]
	v_mfma_f32_16x16x32_bf16 v[126:129], v[134:137], v[166:169], v[126:129]
	v_mfma_f32_16x16x32_bf16 v[122:125], v[142:145], v[166:169], v[122:125]
	v_mfma_f32_16x16x32_bf16 v[118:121], v[134:137], v[174:177], v[118:121]
	v_mfma_f32_16x16x32_bf16 v[110:113], v[142:145], v[174:177], v[110:113]
	v_mfma_f32_16x16x32_bf16 v[102:105], v[134:137], v[194:197], v[102:105]
	v_mfma_f32_16x16x32_bf16 v[94:97], v[142:145], v[194:197], v[94:97]
	v_mfma_f32_16x16x32_bf16 v[78:81], v[134:137], v[206:209], v[78:81]
	v_mfma_f32_16x16x32_bf16 v[74:77], v[142:145], v[206:209], v[74:77]
	v_mfma_f32_16x16x32_bf16 v[114:117], v[146:149], v[162:165], v[114:117]
	v_mfma_f32_16x16x32_bf16 v[106:109], v[154:157], v[162:165], v[106:109]
	v_mfma_f32_16x16x32_bf16 v[98:101], v[146:149], v[170:173], v[98:101]
	v_mfma_f32_16x16x32_bf16 v[90:93], v[154:157], v[170:173], v[90:93]
	v_mfma_f32_16x16x32_bf16 v[86:89], v[146:149], v[190:193], v[86:89]
	v_mfma_f32_16x16x32_bf16 v[82:85], v[154:157], v[190:193], v[82:85]
	v_mfma_f32_16x16x32_bf16 v[70:73], v[146:149], v[198:201], v[70:73]
	v_mfma_f32_16x16x32_bf16 v[66:69], v[154:157], v[198:201], v[66:69]
	v_mfma_f32_16x16x32_bf16 v[114:117], v[150:153], v[166:169], v[114:117]
	v_mfma_f32_16x16x32_bf16 v[106:109], v[158:161], v[166:169], v[106:109]
	v_mfma_f32_16x16x32_bf16 v[98:101], v[150:153], v[174:177], v[98:101]
	v_mfma_f32_16x16x32_bf16 v[90:93], v[158:161], v[174:177], v[90:93]
	v_mfma_f32_16x16x32_bf16 v[86:89], v[150:153], v[194:197], v[86:89]
	v_mfma_f32_16x16x32_bf16 v[82:85], v[158:161], v[194:197], v[82:85]
	v_mfma_f32_16x16x32_bf16 v[70:73], v[150:153], v[206:209], v[70:73]
	v_mfma_f32_16x16x32_bf16 v[66:69], v[158:161], v[206:209], v[66:69]
	s_barrier
; #define PG8_STAGE(bufoff, gbase, voff) do { _Pragma("unroll") for (int _i = 0; _i < 2; ++_i) \
;         __builtin_amdgcn_global_load_lds((const unsigned*)((const char*)(gbase) + (voff)[_i]), (PG8_LAS unsigned*)(lds + (bufoff) + ldsw + _i * 8192), 16, 0, 0); } while (0)
; #define PG8_LDA(dst, b, h) do { _Pragma("unroll") for (int m = 0; m < 4; ++m) _Pragma("unroll") for (int k = 0; k < 2; ++k) dst[m][k] = *(const PG8_LAS bf16x8*)(lds + PG8_SA(b, h) + aoff + m * 2048 + k * 1024); } while (0)
; #define PG8_MMA(ai, bj, At, Bt) do { __builtin_amdgcn_s_setprio(1); _Pragma("unroll") for (int m = 0; m < 4; ++m) _Pragma("unroll") for (int n = 0; n < 2; ++n) _Pragma("unroll") for (int k = 0; k < 2; ++k) \
;         acc[ai][bj][m][n] = __builtin_amdgcn_mfma_f32_16x16x32_bf16(Bt[n][k], At[m][k], acc[ai][bj][m][n], 0, 0, 0); __builtin_amdgcn_s_setprio(0); } while (0)
; #define PG8_WAIT_V(n) asm volatile("s_waitcnt vmcnt(" #n ")" ::: "memory")
; #define PG8_WAIT_L(n) asm volatile("s_waitcnt lgkmcnt(" #n ")" ::: "memory")
; #define PG8_BAR __builtin_amdgcn_s_barrier()
; #define PG8_SCHED __builtin_amdgcn_sched_barrier(0)
; template <class Epi, class Sched, bool ALIGN_EPI = false, bool SP2 = false>
; __device__ __forceinline__ void gemm_phase(PG8_LAS unsigned char* lds, const Gemm g, const Sched& S, const Epi& E) {
;     ...
;             PG8_LDA(At, 1, 1); PG8_STAGE(PG8_SB(1, 0), b3, voffB); PG8_STAGE(PG8_SB(1, 1), b3 + hstep, voffB); PG8_STAGE(PG8_SA(1, 0), a3, voffA);
;             PG8_WAIT_V(8); PG8_WAIT_L(0); PG8_BAR; PG8_MMA(1, 0, At, B0); PG8_MMA(1, 1, At, B1); PG8_BAR; PG8_SCHED;
	s_add_i32 s22, s77, s38
	v_lshl_add_u64 v[202:203], v[202:203], 0, s[28:29]
	s_mov_b32 m0, s22
	ds_read_b128 v[162:165], v205 offset:49152
	ds_read_b128 v[166:169], v205 offset:50176
	ds_read_b128 v[170:173], v205 offset:51200
	ds_read_b128 v[174:177], v205 offset:52224
	ds_read_b128 v[190:193], v205 offset:53248
	ds_read_b128 v[194:197], v205 offset:54272
	ds_read_b128 v[198:201], v205 offset:55296
	ds_read_b128 v[206:209], v205 offset:56320
	global_load_lds_dwordx4 v[202:203], off
	s_add_i32 m0, s22, 0x2000
	s_add_u32 s22, s26, 0xb0080
	v_lshl_add_u64 v[202:203], v[210:211], 0, s[28:29]
	s_addc_u32 s23, s27, 0
	s_add_i32 s26, s78, s38
	global_load_lds_dwordx4 v[202:203], off
	v_lshl_add_u64 v[202:203], s[22:23], 0, v[180:181]
	s_mov_b32 m0, s26
	s_nop 0
	global_load_lds_dwordx4 v[202:203], off
	v_lshl_add_u64 v[202:203], s[22:23], 0, v[184:185]
	s_add_i32 m0, s26, 0x2000
	s_nop 0
	global_load_lds_dwordx4 v[202:203], off
	v_lshl_add_u64 v[202:203], v[220:221], 0, s[28:29]
	s_mov_b32 m0, s61
	s_nop 0
	global_load_lds_dwordx4 v[202:203], off
	v_lshl_add_u64 v[202:203], v[222:223], 0, s[28:29]
	s_mov_b32 m0, s64
	s_nop 0
	global_load_lds_dwordx4 v[202:203], off
	s_waitcnt vmcnt(8)
	s_waitcnt lgkmcnt(0)
	s_barrier
	s_waitcnt lgkmcnt(0)
	v_mfma_f32_16x16x32_bf16 v[62:65], v[130:133], v[162:165], v[62:65]
	v_mfma_f32_16x16x32_bf16 v[58:61], v[138:141], v[162:165], v[58:61]
	v_mfma_f32_16x16x32_bf16 v[54:57], v[130:133], v[170:173], v[54:57]
	v_mfma_f32_16x16x32_bf16 v[46:49], v[138:141], v[170:173], v[46:49]
	v_mfma_f32_16x16x32_bf16 v[38:41], v[130:133], v[190:193], v[38:41]
	v_mfma_f32_16x16x32_bf16 v[30:33], v[138:141], v[190:193], v[30:33]
	v_mfma_f32_16x16x32_bf16 v[14:17], v[130:133], v[198:201], v[14:17]
	v_mfma_f32_16x16x32_bf16 v[10:13], v[138:141], v[198:201], v[10:13]
	v_mfma_f32_16x16x32_bf16 v[62:65], v[134:137], v[166:169], v[62:65]
	v_mfma_f32_16x16x32_bf16 v[58:61], v[142:145], v[166:169], v[58:61]
	v_mfma_f32_16x16x32_bf16 v[54:57], v[134:137], v[174:177], v[54:57]
	v_mfma_f32_16x16x32_bf16 v[46:49], v[142:145], v[174:177], v[46:49]
	v_mfma_f32_16x16x32_bf16 v[38:41], v[134:137], v[194:197], v[38:41]
	v_mfma_f32_16x16x32_bf16 v[30:33], v[142:145], v[194:197], v[30:33]
	v_mfma_f32_16x16x32_bf16 v[14:17], v[134:137], v[206:209], v[14:17]
	v_mfma_f32_16x16x32_bf16 v[10:13], v[142:145], v[206:209], v[10:13]
	v_mfma_f32_16x16x32_bf16 v[50:53], v[146:149], v[162:165], v[50:53]
	v_mfma_f32_16x16x32_bf16 v[42:45], v[154:157], v[162:165], v[42:45]
	v_mfma_f32_16x16x32_bf16 v[34:37], v[146:149], v[170:173], v[34:37]
	v_mfma_f32_16x16x32_bf16 v[26:29], v[154:157], v[170:173], v[26:29]
	v_mfma_f32_16x16x32_bf16 v[22:25], v[146:149], v[190:193], v[22:25]
	v_mfma_f32_16x16x32_bf16 v[18:21], v[154:157], v[190:193], v[18:21]
	v_mfma_f32_16x16x32_bf16 v[6:9], v[146:149], v[198:201], v[6:9]
	v_mfma_f32_16x16x32_bf16 v[2:5], v[154:157], v[198:201], v[2:5]
	v_mfma_f32_16x16x32_bf16 v[50:53], v[150:153], v[166:169], v[50:53]
	v_mfma_f32_16x16x32_bf16 v[42:45], v[158:161], v[166:169], v[42:45]
	v_mfma_f32_16x16x32_bf16 v[34:37], v[150:153], v[174:177], v[34:37]
	v_mfma_f32_16x16x32_bf16 v[26:29], v[158:161], v[174:177], v[26:29]
	v_mfma_f32_16x16x32_bf16 v[22:25], v[150:153], v[194:197], v[22:25]
	v_mfma_f32_16x16x32_bf16 v[18:21], v[158:161], v[194:197], v[18:21]
	v_mfma_f32_16x16x32_bf16 v[6:9], v[150:153], v[206:209], v[6:9]
	v_mfma_f32_16x16x32_bf16 v[2:5], v[158:161], v[206:209], v[2:5]
	s_barrier
	s_add_i32 s76, s76, 2
	s_add_u32 s74, s74, 0x100
	s_addc_u32 s75, s75, 0
	s_cmp_gt_u32 s76, 41
	s_mov_b64 s[22:23], s[24:25]
	s_cbranch_scc0 .LBB0_388
	s_and_b64 vcc, exec, s[8:9]
	s_cbranch_vccz .LBB0_391
	s_barrier

; #define PG8_STAGE(bufoff, gbase, voff) do { _Pragma("unroll") for (int _i = 0; _i < 2; ++_i) \
;         __builtin_amdgcn_global_load_lds((const unsigned*)((const char*)(gbase) + (voff)[_i]), (PG8_LAS unsigned*)(lds + (bufoff) + ldsw + _i * 8192), 16, 0, 0); } while (0)
; #define PG8_LDA(dst, b, h) do { _Pragma("unroll") for (int m = 0; m < 4; ++m) _Pragma("unroll") for (int k = 0; k < 2; ++k) dst[m][k] = *(const PG8_LAS bf16x8*)(lds + PG8_SA(b, h) + aoff + m * 2048 + k * 1024); } while (0)
; #define PG8_LDB(dst, b, h) do { _Pragma("unroll") for (int n = 0; n < 2; ++n) _Pragma("unroll") for (int k = 0; k < 2; ++k) dst[n][k] = *(const PG8_LAS bf16x8*)(lds + PG8_SB(b, h) + boff + n * 2048 + k * 1024); } while (0)
; #define PG8_MMA(ai, bj, At, Bt) do { __builtin_amdgcn_s_setprio(1); _Pragma("unroll") for (int m = 0; m < 4; ++m) _Pragma("unroll") for (int n = 0; n < 2; ++n) _Pragma("unroll") for (int k = 0; k < 2; ++k) \
;         acc[ai][bj][m][n] = __builtin_amdgcn_mfma_f32_16x16x32_bf16(Bt[n][k], At[m][k], acc[ai][bj][m][n], 0, 0, 0); __builtin_amdgcn_s_setprio(0); } while (0)
; #define PG8_WAIT_V(n) asm volatile("s_waitcnt vmcnt(" #n ")" ::: "memory")
; #define PG8_WAIT_L(n) asm volatile("s_waitcnt lgkmcnt(" #n ")" ::: "memory")
; #define PG8_BAR __builtin_amdgcn_s_barrier()
; template <class Epi, class Sched, bool ALIGN_EPI = false, bool SP2 = false>
; __device__ __forceinline__ void gemm_phase(PG8_LAS unsigned char* lds, const Gemm g, const Sched& S, const Epi& E) {
;     ...
;             const char* a1 = cA + (size_t)(t + 1) * kstep;
;             const char* a2 = last ? nA : cA + (size_t)(t + 2) * kstep; const char* b2 = last ? nB : cB + (size_t)(t + 2) * kstep;
;             const char* a3 = a2 + kstep; const char* b3 = b2 + kstep;
;             if (last && has_next) S.a_ready(nxt);
;             if constexpr (SP2) {
;             PG8_LDB(B0, 0, 0); PG8_LDB(B1, 0, 1); PG8_SCHED; PG8_LDA(At, 0, 0); PG8_STAGE(PG8_SA(1, 1), a1 + hstep, voffA);
;             PG8_WAIT_V(8); PG8_WAIT_L(0); PG8_BAR; PG8_MMA(0, 0, At, B0); PG8_MMA(0, 1, At, B1); PG8_BAR; PG8_SCHED;
;             PG8_LDA(At, 0, 1); PG8_STAGE(PG8_SB(0, 0), b2, voffB); PG8_STAGE(PG8_SB(0, 1), b2 + hstep, voffB); PG8_STAGE(PG8_SA(0, 0), a2, voffA);
;             PG8_WAIT_V(8); PG8_WAIT_L(0); PG8_BAR; PG8_MMA(1, 0, At, B0); PG8_MMA(1, 1, At, B1); PG8_BAR; PG8_SCHED;
.LBB0_547:
	s_add_u32 s36, s60, 0xfffc0080
	s_addc_u32 s37, s61, -1
	s_add_i32 s77, 0, 0x10000
	s_cmp_eq_u32 s76, 12
	s_cselect_b32 s39, s5, s37
	s_cselect_b32 s38, s23, s36
	s_cselect_b32 s37, s15, s75
	s_cselect_b32 s36, s73, s74
	s_add_i32 s80, 0, 0x14000
	v_add_u32_e32 v154, s77, v148
	v_add_u32_e32 v170, s80, v148
	ds_read_b128 v[140:143], v154
	ds_read_b128 v[144:147], v154 offset:1024
	ds_read_b128 v[150:153], v154 offset:2048
	ds_read_b128 v[154:157], v154 offset:3072
	ds_read_b128 v[158:161], v170
	ds_read_b128 v[162:165], v170 offset:1024
	ds_read_b128 v[166:169], v170 offset:2048
	ds_read_b128 v[170:173], v170 offset:3072
	v_lshl_add_u64 v[206:207], s[60:61], 0, v[138:139]
	s_add_i32 m0, s53, 0xc000
	ds_read_b128 v[174:177], v149
	ds_read_b128 v[178:181], v149 offset:1024
	ds_read_b128 v[182:185], v149 offset:2048
	ds_read_b128 v[186:189], v149 offset:3072
	ds_read_b128 v[190:193], v149 offset:4096
	ds_read_b128 v[194:197], v149 offset:5120
	ds_read_b128 v[198:201], v149 offset:6144
	ds_read_b128 v[202:205], v149 offset:7168
	global_load_lds_dwordx4 v[206:207], off
	v_lshl_add_u64 v[206:207], s[60:61], 0, v[136:137]
	s_add_i32 m0, s53, 0xe000
	s_nop 0
	global_load_lds_dwordx4 v[206:207], off
	s_waitcnt vmcnt(8)
	s_waitcnt lgkmcnt(0)
	s_barrier
	s_waitcnt lgkmcnt(0)
	v_mfma_f32_16x16x32_bf16 v[126:129], v[140:143], v[174:177], v[126:129]
	v_mfma_f32_16x16x32_bf16 v[122:125], v[150:153], v[174:177], v[122:125]
	v_mfma_f32_16x16x32_bf16 v[110:113], v[140:143], v[182:185], v[110:113]
	v_mfma_f32_16x16x32_bf16 v[106:109], v[150:153], v[182:185], v[106:109]
	v_mfma_f32_16x16x32_bf16 v[94:97], v[140:143], v[190:193], v[94:97]
	v_mfma_f32_16x16x32_bf16 v[90:93], v[150:153], v[190:193], v[90:93]
	v_mfma_f32_16x16x32_bf16 v[78:81], v[140:143], v[198:201], v[78:81]
	v_mfma_f32_16x16x32_bf16 v[74:77], v[150:153], v[198:201], v[74:77]
	v_mfma_f32_16x16x32_bf16 v[126:129], v[144:147], v[178:181], v[126:129]
	v_mfma_f32_16x16x32_bf16 v[122:125], v[154:157], v[178:181], v[122:125]
	v_mfma_f32_16x16x32_bf16 v[110:113], v[144:147], v[186:189], v[110:113]
	v_mfma_f32_16x16x32_bf16 v[106:109], v[154:157], v[186:189], v[106:109]
	v_mfma_f32_16x16x32_bf16 v[94:97], v[144:147], v[194:197], v[94:97]
	v_mfma_f32_16x16x32_bf16 v[90:93], v[154:157], v[194:197], v[90:93]
	v_mfma_f32_16x16x32_bf16 v[78:81], v[144:147], v[202:205], v[78:81]
	v_mfma_f32_16x16x32_bf16 v[74:77], v[154:157], v[202:205], v[74:77]
	v_mfma_f32_16x16x32_bf16 v[118:121], v[158:161], v[174:177], v[118:121]
	v_mfma_f32_16x16x32_bf16 v[114:117], v[166:169], v[174:177], v[114:117]
	v_mfma_f32_16x16x32_bf16 v[102:105], v[158:161], v[182:185], v[102:105]
	v_mfma_f32_16x16x32_bf16 v[98:101], v[166:169], v[182:185], v[98:101]
	v_mfma_f32_16x16x32_bf16 v[86:89], v[158:161], v[190:193], v[86:89]
	v_mfma_f32_16x16x32_bf16 v[82:85], v[166:169], v[190:193], v[82:85]
	v_mfma_f32_16x16x32_bf16 v[70:73], v[158:161], v[198:201], v[70:73]
	v_mfma_f32_16x16x32_bf16 v[66:69], v[166:169], v[198:201], v[66:69]
	v_mfma_f32_16x16x32_bf16 v[118:121], v[162:165], v[178:181], v[118:121]
	v_mfma_f32_16x16x32_bf16 v[114:117], v[170:173], v[178:181], v[114:117]
	v_mfma_f32_16x16x32_bf16 v[102:105], v[162:165], v[186:189], v[102:105]
	v_mfma_f32_16x16x32_bf16 v[98:101], v[170:173], v[186:189], v[98:101]
	v_mfma_f32_16x16x32_bf16 v[86:89], v[162:165], v[194:197], v[86:89]
	v_mfma_f32_16x16x32_bf16 v[82:85], v[170:173], v[194:197], v[82:85]
	v_mfma_f32_16x16x32_bf16 v[70:73], v[162:165], v[202:205], v[70:73]
	v_mfma_f32_16x16x32_bf16 v[66:69], v[170:173], v[202:205], v[66:69]
	s_barrier
	s_add_i32 s77, s77, s41
	v_lshl_add_u64 v[206:207], s[36:37], 0, v[0:1]
	s_mov_b32 m0, s77
	ds_read_b128 v[174:177], v149 offset:16384
	ds_read_b128 v[178:181], v149 offset:17408
	ds_read_b128 v[182:185], v149 offset:18432
	ds_read_b128 v[186:189], v149 offset:19456
	ds_read_b128 v[190:193], v149 offset:20480
	ds_read_b128 v[194:197], v149 offset:21504
	ds_read_b128 v[198:201], v149 offset:22528
	ds_read_b128 v[202:205], v149 offset:23552
	global_load_lds_dwordx4 v[206:207], off
	s_add_i32 m0, s77, 0x2000
	s_add_u32 s78, s36, 0x40000
	v_lshl_add_u64 v[208:209], s[36:37], 0, v[134:135]
	s_addc_u32 s79, s37, 0
	s_add_i32 s77, s80, s41
	global_load_lds_dwordx4 v[208:209], off
	v_lshl_add_u64 v[210:211], s[78:79], 0, v[0:1]
	s_mov_b32 m0, s77
	v_lshl_add_u64 v[212:213], s[38:39], 0, v[132:133]
	global_load_lds_dwordx4 v[210:211], off
	v_lshl_add_u64 v[210:211], s[78:79], 0, v[134:135]
	s_add_i32 m0, s77, 0x2000
	s_nop 0
	global_load_lds_dwordx4 v[210:211], off
	v_lshl_add_u64 v[210:211], s[38:39], 0, v[130:131]
	s_mov_b32 m0, s53
	s_nop 0
	global_load_lds_dwordx4 v[210:211], off
	s_mov_b32 m0, s62
	s_nop 0
	global_load_lds_dwordx4 v[212:213], off
	s_waitcnt vmcnt(8)
	s_waitcnt lgkmcnt(0)
	s_barrier
; #define PG8_STAGE(bufoff, gbase, voff) do { _Pragma("unroll") for (int _i = 0; _i < 2; ++_i) \
;         __builtin_amdgcn_global_load_lds((const unsigned*)((const char*)(gbase) + (voff)[_i]), (PG8_LAS unsigned*)(lds + (bufoff) + ldsw + _i * 8192), 16, 0, 0); } while (0)
; #define PG8_LDA(dst, b, h) do { _Pragma("unroll") for (int m = 0; m < 4; ++m) _Pragma("unroll") for (int k = 0; k < 2; ++k) dst[m][k] = *(const PG8_LAS bf16x8*)(lds + PG8_SA(b, h) + aoff + m * 2048 + k * 1024); } while (0)
; #define PG8_LDB(dst, b, h) do { _Pragma("unroll") for (int n = 0; n < 2; ++n) _Pragma("unroll") for (int k = 0; k < 2; ++k) dst[n][k] = *(const PG8_LAS bf16x8*)(lds + PG8_SB(b, h) + boff + n * 2048 + k * 1024); } while (0)
; #define PG8_MMA(ai, bj, At, Bt) do { __builtin_amdgcn_s_setprio(1); _Pragma("unroll") for (int m = 0; m < 4; ++m) _Pragma("unroll") for (int n = 0; n < 2; ++n) _Pragma("unroll") for (int k = 0; k < 2; ++k) \
;         acc[ai][bj][m][n] = __builtin_amdgcn_mfma_f32_16x16x32_bf16(Bt[n][k], At[m][k], acc[ai][bj][m][n], 0, 0, 0); __builtin_amdgcn_s_setprio(0); } while (0)
; #define PG8_WAIT_V(n) asm volatile("s_waitcnt vmcnt(" #n ")" ::: "memory")
; #define PG8_WAIT_L(n) asm volatile("s_waitcnt lgkmcnt(" #n ")" ::: "memory")
; #define PG8_BAR __builtin_amdgcn_s_barrier()
; #define PG8_SCHED __builtin_amdgcn_sched_barrier(0)
; template <class Epi, class Sched, bool ALIGN_EPI = false, bool SP2 = false>
; __device__ __forceinline__ void gemm_phase(PG8_LAS unsigned char* lds, const Gemm g, const Sched& S, const Epi& E) {
;     ...
;             PG8_WAIT_V(8); PG8_WAIT_L(0); PG8_BAR; PG8_MMA(1, 0, At, B0); PG8_MMA(1, 1, At, B1); PG8_BAR; PG8_SCHED;
;             PG8_LDB(B0, 1, 0); PG8_LDB(B1, 1, 1); PG8_SCHED; PG8_LDA(At, 1, 0); PG8_STAGE(PG8_SA(0, 1), a2 + hstep, voffA);
;             PG8_WAIT_V(8); PG8_WAIT_L(0); PG8_BAR; PG8_MMA(0, 0, At, B0); PG8_MMA(0, 1, At, B1); PG8_BAR; PG8_SCHED;
	s_waitcnt lgkmcnt(0)
	v_mfma_f32_16x16x32_bf16 v[62:65], v[140:143], v[174:177], v[62:65]
	v_mfma_f32_16x16x32_bf16 v[58:61], v[150:153], v[174:177], v[58:61]
	v_mfma_f32_16x16x32_bf16 v[46:49], v[140:143], v[182:185], v[46:49]
	v_mfma_f32_16x16x32_bf16 v[42:45], v[150:153], v[182:185], v[42:45]
	v_mfma_f32_16x16x32_bf16 v[30:33], v[140:143], v[190:193], v[30:33]
	v_mfma_f32_16x16x32_bf16 v[26:29], v[150:153], v[190:193], v[26:29]
	v_mfma_f32_16x16x32_bf16 v[14:17], v[140:143], v[198:201], v[14:17]
	v_mfma_f32_16x16x32_bf16 v[10:13], v[150:153], v[198:201], v[10:13]
	v_mfma_f32_16x16x32_bf16 v[62:65], v[144:147], v[178:181], v[62:65]
	v_mfma_f32_16x16x32_bf16 v[58:61], v[154:157], v[178:181], v[58:61]
	v_mfma_f32_16x16x32_bf16 v[46:49], v[144:147], v[186:189], v[46:49]
	v_mfma_f32_16x16x32_bf16 v[42:45], v[154:157], v[186:189], v[42:45]
	v_mfma_f32_16x16x32_bf16 v[30:33], v[144:147], v[194:197], v[30:33]
	v_mfma_f32_16x16x32_bf16 v[26:29], v[154:157], v[194:197], v[26:29]
	v_mfma_f32_16x16x32_bf16 v[14:17], v[144:147], v[202:205], v[14:17]
	v_mfma_f32_16x16x32_bf16 v[10:13], v[154:157], v[202:205], v[10:13]
	v_mfma_f32_16x16x32_bf16 v[54:57], v[158:161], v[174:177], v[54:57]
	v_mfma_f32_16x16x32_bf16 v[50:53], v[166:169], v[174:177], v[50:53]
	v_mfma_f32_16x16x32_bf16 v[38:41], v[158:161], v[182:185], v[38:41]
	v_mfma_f32_16x16x32_bf16 v[34:37], v[166:169], v[182:185], v[34:37]
	v_mfma_f32_16x16x32_bf16 v[22:25], v[158:161], v[190:193], v[22:25]
	v_mfma_f32_16x16x32_bf16 v[18:21], v[166:169], v[190:193], v[18:21]
	v_mfma_f32_16x16x32_bf16 v[6:9], v[158:161], v[198:201], v[6:9]
	v_mfma_f32_16x16x32_bf16 v[2:5], v[166:169], v[198:201], v[2:5]
	v_mfma_f32_16x16x32_bf16 v[54:57], v[162:165], v[178:181], v[54:57]
	v_mfma_f32_16x16x32_bf16 v[50:53], v[170:173], v[178:181], v[50:53]
	v_mfma_f32_16x16x32_bf16 v[38:41], v[162:165], v[186:189], v[38:41]
	v_mfma_f32_16x16x32_bf16 v[34:37], v[170:173], v[186:189], v[34:37]
	v_mfma_f32_16x16x32_bf16 v[22:25], v[162:165], v[194:197], v[22:25]
	v_mfma_f32_16x16x32_bf16 v[18:21], v[170:173], v[194:197], v[18:21]
	v_mfma_f32_16x16x32_bf16 v[6:9], v[162:165], v[202:205], v[6:9]
	v_mfma_f32_16x16x32_bf16 v[2:5], v[170:173], v[202:205], v[2:5]
	s_barrier
	s_add_i32 s77, 0, 0x18000
	s_add_i32 s78, 0, 0x1c000
	v_add_u32_e32 v154, s77, v148
	v_add_u32_e32 v170, s78, v148
	ds_read_b128 v[140:143], v154
	ds_read_b128 v[144:147], v154 offset:1024
	ds_read_b128 v[150:153], v154 offset:2048
	ds_read_b128 v[154:157], v154 offset:3072
	ds_read_b128 v[158:161], v170
	ds_read_b128 v[162:165], v170 offset:1024
	ds_read_b128 v[166:169], v170 offset:2048
	ds_read_b128 v[170:173], v170 offset:3072
	s_add_u32 s38, s38, 0x40000
	s_addc_u32 s39, s39, 0
	s_mov_b32 m0, s63
	v_lshl_add_u64 v[214:215], s[38:39], 0, v[130:131]
	ds_read_b128 v[174:177], v149 offset:32768
	ds_read_b128 v[178:181], v149 offset:33792
	ds_read_b128 v[182:185], v149 offset:34816
	ds_read_b128 v[186:189], v149 offset:35840
	ds_read_b128 v[190:193], v149 offset:36864
	ds_read_b128 v[194:197], v149 offset:37888
	ds_read_b128 v[198:201], v149 offset:38912
	ds_read_b128 v[202:205], v149 offset:39936
	global_load_lds_dwordx4 v[214:215], off
	v_lshl_add_u64 v[214:215], s[38:39], 0, v[132:133]
	s_mov_b32 m0, s64
	s_nop 0
	global_load_lds_dwordx4 v[214:215], off
	s_waitcnt vmcnt(8)
	s_waitcnt lgkmcnt(0)
	s_barrier
	s_waitcnt lgkmcnt(0)
	v_mfma_f32_16x16x32_bf16 v[126:129], v[140:143], v[174:177], v[126:129]
	v_mfma_f32_16x16x32_bf16 v[122:125], v[150:153], v[174:177], v[122:125]
	v_mfma_f32_16x16x32_bf16 v[110:113], v[140:143], v[182:185], v[110:113]
	v_mfma_f32_16x16x32_bf16 v[106:109], v[150:153], v[182:185], v[106:109]
	v_mfma_f32_16x16x32_bf16 v[94:97], v[140:143], v[190:193], v[94:97]
	v_mfma_f32_16x16x32_bf16 v[90:93], v[150:153], v[190:193], v[90:93]
	v_mfma_f32_16x16x32_bf16 v[78:81], v[140:143], v[198:201], v[78:81]
	v_mfma_f32_16x16x32_bf16 v[74:77], v[150:153], v[198:201], v[74:77]
	v_mfma_f32_16x16x32_bf16 v[126:129], v[144:147], v[178:181], v[126:129]
	v_mfma_f32_16x16x32_bf16 v[122:125], v[154:157], v[178:181], v[122:125]
	v_mfma_f32_16x16x32_bf16 v[110:113], v[144:147], v[186:189], v[110:113]
	v_mfma_f32_16x16x32_bf16 v[106:109], v[154:157], v[186:189], v[106:109]
	v_mfma_f32_16x16x32_bf16 v[94:97], v[144:147], v[194:197], v[94:97]
	v_mfma_f32_16x16x32_bf16 v[90:93], v[154:157], v[194:197], v[90:93]
	v_mfma_f32_16x16x32_bf16 v[78:81], v[144:147], v[202:205], v[78:81]
	v_mfma_f32_16x16x32_bf16 v[74:77], v[154:157], v[202:205], v[74:77]
	v_mfma_f32_16x16x32_bf16 v[118:121], v[158:161], v[174:177], v[118:121]
	v_mfma_f32_16x16x32_bf16 v[114:117], v[166:169], v[174:177], v[114:117]
	v_mfma_f32_16x16x32_bf16 v[102:105], v[158:161], v[182:185], v[102:105]
	v_mfma_f32_16x16x32_bf16 v[98:101], v[166:169], v[182:185], v[98:101]
	v_mfma_f32_16x16x32_bf16 v[86:89], v[158:161], v[190:193], v[86:89]
	v_mfma_f32_16x16x32_bf16 v[82:85], v[166:169], v[190:193], v[82:85]
	v_mfma_f32_16x16x32_bf16 v[70:73], v[158:161], v[198:201], v[70:73]
	v_mfma_f32_16x16x32_bf16 v[66:69], v[166:169], v[198:201], v[66:69]
	v_mfma_f32_16x16x32_bf16 v[118:121], v[162:165], v[178:181], v[118:121]
	v_mfma_f32_16x16x32_bf16 v[114:117], v[170:173], v[178:181], v[114:117]
	v_mfma_f32_16x16x32_bf16 v[102:105], v[162:165], v[186:189], v[102:105]
	v_mfma_f32_16x16x32_bf16 v[98:101], v[170:173], v[186:189], v[98:101]
	v_mfma_f32_16x16x32_bf16 v[86:89], v[162:165], v[194:197], v[86:89]
	v_mfma_f32_16x16x32_bf16 v[82:85], v[170:173], v[194:197], v[82:85]
	v_mfma_f32_16x16x32_bf16 v[70:73], v[162:165], v[202:205], v[70:73]
	v_mfma_f32_16x16x32_bf16 v[66:69], v[170:173], v[202:205], v[66:69]
	s_barrier
; #define PG8_STAGE(bufoff, gbase, voff) do { _Pragma("unroll") for (int _i = 0; _i < 2; ++_i) \
;         __builtin_amdgcn_global_load_lds((const unsigned*)((const char*)(gbase) + (voff)[_i]), (PG8_LAS unsigned*)(lds + (bufoff) + ldsw + _i * 8192), 16, 0, 0); } while (0)
; #define PG8_LDA(dst, b, h) do { _Pragma("unroll") for (int m = 0; m < 4; ++m) _Pragma("unroll") for (int k = 0; k < 2; ++k) dst[m][k] = *(const PG8_LAS bf16x8*)(lds + PG8_SA(b, h) + aoff + m * 2048 + k * 1024); } while (0)
; #define PG8_MMA(ai, bj, At, Bt) do { __builtin_amdgcn_s_setprio(1); _Pragma("unroll") for (int m = 0; m < 4; ++m) _Pragma("unroll") for (int n = 0; n < 2; ++n) _Pragma("unroll") for (int k = 0; k < 2; ++k) \
;         acc[ai][bj][m][n] = __builtin_amdgcn_mfma_f32_16x16x32_bf16(Bt[n][k], At[m][k], acc[ai][bj][m][n], 0, 0, 0); __builtin_amdgcn_s_setprio(0); } while (0)
; #define PG8_WAIT_V(n) asm volatile("s_waitcnt vmcnt(" #n ")" ::: "memory")
; #define PG8_WAIT_L(n) asm volatile("s_waitcnt lgkmcnt(" #n ")" ::: "memory")
; #define PG8_BAR __builtin_amdgcn_s_barrier()
; #define PG8_SCHED __builtin_amdgcn_sched_barrier(0)
; template <class Epi, class Sched, bool ALIGN_EPI = false, bool SP2 = false>
; __device__ __forceinline__ void gemm_phase(PG8_LAS unsigned char* lds, const Gemm g, const Sched& S, const Epi& E) {
;     ...
;             PG8_WAIT_V(8); PG8_WAIT_L(0); PG8_BAR; PG8_MMA(0, 0, At, B0); PG8_MMA(0, 1, At, B1); PG8_BAR; PG8_SCHED;
;             PG8_LDA(At, 1, 1); PG8_STAGE(PG8_SB(1, 0), b3, voffB); PG8_STAGE(PG8_SB(1, 1), b3 + hstep, voffB); PG8_STAGE(PG8_SA(1, 0), a3, voffA);
;             PG8_WAIT_V(8); PG8_WAIT_L(0); PG8_BAR; PG8_MMA(1, 0, At, B0); PG8_MMA(1, 1, At, B1); PG8_BAR; PG8_SCHED;
	s_add_i32 s38, s77, s41
	v_lshl_add_u64 v[206:207], v[206:207], 0, s[28:29]
	s_mov_b32 m0, s38
	ds_read_b128 v[174:177], v149 offset:49152
	ds_read_b128 v[178:181], v149 offset:50176
	ds_read_b128 v[182:185], v149 offset:51200
	ds_read_b128 v[186:189], v149 offset:52224
	ds_read_b128 v[190:193], v149 offset:53248
	ds_read_b128 v[194:197], v149 offset:54272
	ds_read_b128 v[198:201], v149 offset:55296
	ds_read_b128 v[202:205], v149 offset:56320
	global_load_lds_dwordx4 v[206:207], off
	s_add_i32 m0, s38, 0x2000
	s_add_u32 s36, s36, 0x40080
	v_lshl_add_u64 v[206:207], v[208:209], 0, s[28:29]
	s_addc_u32 s37, s37, 0
	s_add_i32 s38, s78, s41
	global_load_lds_dwordx4 v[206:207], off
	v_lshl_add_u64 v[206:207], s[36:37], 0, v[0:1]
	s_mov_b32 m0, s38
	s_nop 0
	global_load_lds_dwordx4 v[206:207], off
	v_lshl_add_u64 v[206:207], s[36:37], 0, v[134:135]
	s_add_i32 m0, s38, 0x2000
	s_nop 0
	global_load_lds_dwordx4 v[206:207], off
	v_lshl_add_u64 v[206:207], v[210:211], 0, s[28:29]
	s_mov_b32 m0, s70
	s_nop 0
	global_load_lds_dwordx4 v[206:207], off
	v_lshl_add_u64 v[206:207], v[212:213], 0, s[28:29]
	s_mov_b32 m0, s71
	s_nop 0
	global_load_lds_dwordx4 v[206:207], off
	s_waitcnt vmcnt(8)
	s_waitcnt lgkmcnt(0)
	s_barrier
	s_waitcnt lgkmcnt(0)
	v_mfma_f32_16x16x32_bf16 v[62:65], v[140:143], v[174:177], v[62:65]
	v_mfma_f32_16x16x32_bf16 v[58:61], v[150:153], v[174:177], v[58:61]
	v_mfma_f32_16x16x32_bf16 v[46:49], v[140:143], v[182:185], v[46:49]
	v_mfma_f32_16x16x32_bf16 v[42:45], v[150:153], v[182:185], v[42:45]
	v_mfma_f32_16x16x32_bf16 v[30:33], v[140:143], v[190:193], v[30:33]
	v_mfma_f32_16x16x32_bf16 v[26:29], v[150:153], v[190:193], v[26:29]
	v_mfma_f32_16x16x32_bf16 v[14:17], v[140:143], v[198:201], v[14:17]
	v_mfma_f32_16x16x32_bf16 v[10:13], v[150:153], v[198:201], v[10:13]
	v_mfma_f32_16x16x32_bf16 v[62:65], v[144:147], v[178:181], v[62:65]
	v_mfma_f32_16x16x32_bf16 v[58:61], v[154:157], v[178:181], v[58:61]
	v_mfma_f32_16x16x32_bf16 v[46:49], v[144:147], v[186:189], v[46:49]
	v_mfma_f32_16x16x32_bf16 v[42:45], v[154:157], v[186:189], v[42:45]
	v_mfma_f32_16x16x32_bf16 v[30:33], v[144:147], v[194:197], v[30:33]
	v_mfma_f32_16x16x32_bf16 v[26:29], v[154:157], v[194:197], v[26:29]
	v_mfma_f32_16x16x32_bf16 v[14:17], v[144:147], v[202:205], v[14:17]
	v_mfma_f32_16x16x32_bf16 v[10:13], v[154:157], v[202:205], v[10:13]
	v_mfma_f32_16x16x32_bf16 v[54:57], v[158:161], v[174:177], v[54:57]
	v_mfma_f32_16x16x32_bf16 v[50:53], v[166:169], v[174:177], v[50:53]
	v_mfma_f32_16x16x32_bf16 v[38:41], v[158:161], v[182:185], v[38:41]
	v_mfma_f32_16x16x32_bf16 v[34:37], v[166:169], v[182:185], v[34:37]
	v_mfma_f32_16x16x32_bf16 v[22:25], v[158:161], v[190:193], v[22:25]
	v_mfma_f32_16x16x32_bf16 v[18:21], v[166:169], v[190:193], v[18:21]
	v_mfma_f32_16x16x32_bf16 v[6:9], v[158:161], v[198:201], v[6:9]
	v_mfma_f32_16x16x32_bf16 v[2:5], v[166:169], v[198:201], v[2:5]
	v_mfma_f32_16x16x32_bf16 v[54:57], v[162:165], v[178:181], v[54:57]
	v_mfma_f32_16x16x32_bf16 v[50:53], v[170:173], v[178:181], v[50:53]
	v_mfma_f32_16x16x32_bf16 v[38:41], v[162:165], v[186:189], v[38:41]
	v_mfma_f32_16x16x32_bf16 v[34:37], v[170:173], v[186:189], v[34:37]
	v_mfma_f32_16x16x32_bf16 v[22:25], v[162:165], v[194:197], v[22:25]
	v_mfma_f32_16x16x32_bf16 v[18:21], v[170:173], v[194:197], v[18:21]
	v_mfma_f32_16x16x32_bf16 v[6:9], v[162:165], v[202:205], v[6:9]
	v_mfma_f32_16x16x32_bf16 v[2:5], v[170:173], v[202:205], v[2:5]
	s_barrier
	s_add_i32 s76, s76, 2
	s_add_u32 s74, s74, 0x100
	s_addc_u32 s75, s75, 0
	s_add_u32 s60, s60, 0x100
	s_addc_u32 s61, s61, 0
	s_cmp_gt_u32 s76, 13
	s_cbranch_scc0 .LBB0_547
	s_and_b64 vcc, exec, s[8:9]
	s_cbranch_vccz .LBB0_550
	s_barrier

; #define PG8_STAGE(bufoff, gbase, voff) do { _Pragma("unroll") for (int _i = 0; _i < 2; ++_i) \
;         __builtin_amdgcn_global_load_lds((const unsigned*)((const char*)(gbase) + (voff)[_i]), (PG8_LAS unsigned*)(lds + (bufoff) + ldsw + _i * 8192), 16, 0, 0); } while (0)
; #define PG8_LDA(dst, b, h) do { _Pragma("unroll") for (int m = 0; m < 4; ++m) _Pragma("unroll") for (int k = 0; k < 2; ++k) dst[m][k] = *(const PG8_LAS bf16x8*)(lds + PG8_SA(b, h) + aoff + m * 2048 + k * 1024); } while (0)
; #define PG8_LDB(dst, b, h) do { _Pragma("unroll") for (int n = 0; n < 2; ++n) _Pragma("unroll") for (int k = 0; k < 2; ++k) dst[n][k] = *(const PG8_LAS bf16x8*)(lds + PG8_SB(b, h) + boff + n * 2048 + k * 1024); } while (0)
; #define PG8_MMA(ai, bj, At, Bt) do { __builtin_amdgcn_s_setprio(1); _Pragma("unroll") for (int m = 0; m < 4; ++m) _Pragma("unroll") for (int n = 0; n < 2; ++n) _Pragma("unroll") for (int k = 0; k < 2; ++k) \
;         acc[ai][bj][m][n] = __builtin_amdgcn_mfma_f32_16x16x32_bf16(Bt[n][k], At[m][k], acc[ai][bj][m][n], 0, 0, 0); __builtin_amdgcn_s_setprio(0); } while (0)
; #define PG8_WAIT_V(n) asm volatile("s_waitcnt vmcnt(" #n ")" ::: "memory")
; #define PG8_WAIT_L(n) asm volatile("s_waitcnt lgkmcnt(" #n ")" ::: "memory")
; #define PG8_BAR __builtin_amdgcn_s_barrier()
; #define PG8_SCHED __builtin_amdgcn_sched_barrier(0)
; template <class Epi, class Sched, bool ALIGN_EPI = false, bool SP2 = false>
; __device__ __forceinline__ void gemm_phase(PG8_LAS unsigned char* lds, const Gemm g, const Sched& S, const Epi& E) {
;     ...
;             const char* a1 = cA + (size_t)(t + 1) * kstep;
;             const char* a2 = last ? nA : cA + (size_t)(t + 2) * kstep; const char* b2 = last ? nB : cB + (size_t)(t + 2) * kstep;
;             const char* a3 = a2 + kstep; const char* b3 = b2 + kstep;
;             if (last && has_next) S.a_ready(nxt);
;             if constexpr (SP2) {
;             PG8_LDB(B0, 0, 0); PG8_LDB(B1, 0, 1); PG8_SCHED; PG8_LDA(At, 0, 0); PG8_STAGE(PG8_SA(1, 1), a1 + hstep, voffA);
;             PG8_WAIT_V(8); PG8_WAIT_L(0); PG8_BAR; PG8_MMA(0, 0, At, B0); PG8_MMA(0, 1, At, B1); PG8_BAR; PG8_SCHED;
.LBB0_717:
	s_add_i32 s38, s36, 2
	s_add_u32 s39, s6, 0x80
	s_addc_u32 s37, s7, 0
	s_add_i32 s86, 0, 0x10000
	s_cmp_eq_u32 s78, s36
	s_cselect_b32 s37, s63, s37
	s_cselect_b32 s36, s62, s39
	v_add_u32_e32 v0, s86, v158
	s_cselect_b32 s85, s53, s83
	s_cselect_b32 s84, s52, s82
	s_add_i32 s39, 0, 0x14000
	ds_read_b128 v[130:133], v0
	ds_read_b128 v[134:137], v0 offset:1024
	ds_read_b128 v[138:141], v0 offset:2048
	ds_read_b128 v[142:145], v0 offset:3072
	v_add_u32_e32 v0, s39, v158
	ds_read_b128 v[146:149], v0
	ds_read_b128 v[160:163], v0 offset:1024
	ds_read_b128 v[164:167], v0 offset:2048
	ds_read_b128 v[168:171], v0 offset:3072
	v_lshl_add_u64 v[204:205], s[6:7], 0, v[156:157]
	s_add_i32 m0, s69, 0xc000
	ds_read_b128 v[172:175], v159
	ds_read_b128 v[176:179], v159 offset:1024
	ds_read_b128 v[180:183], v159 offset:2048
	ds_read_b128 v[184:187], v159 offset:3072
	ds_read_b128 v[188:191], v159 offset:4096
	ds_read_b128 v[192:195], v159 offset:5120
	ds_read_b128 v[196:199], v159 offset:6144
	ds_read_b128 v[200:203], v159 offset:7168
	global_load_lds_dwordx4 v[204:205], off
	v_lshl_add_u64 v[204:205], s[6:7], 0, v[154:155]
	s_add_i32 m0, s69, 0xe000
	s_nop 0
	global_load_lds_dwordx4 v[204:205], off
	s_waitcnt vmcnt(8)
	s_waitcnt lgkmcnt(0)
	s_barrier
	s_waitcnt lgkmcnt(0)
	v_mfma_f32_16x16x32_bf16 v[126:129], v[130:133], v[172:175], v[126:129]
	v_mfma_f32_16x16x32_bf16 v[122:125], v[138:141], v[172:175], v[122:125]
	v_mfma_f32_16x16x32_bf16 v[118:121], v[130:133], v[180:183], v[118:121]
	v_mfma_f32_16x16x32_bf16 v[114:117], v[138:141], v[180:183], v[114:117]
	v_mfma_f32_16x16x32_bf16 v[110:113], v[130:133], v[188:191], v[110:113]
	v_mfma_f32_16x16x32_bf16 v[106:109], v[138:141], v[188:191], v[106:109]
	v_mfma_f32_16x16x32_bf16 v[102:105], v[130:133], v[196:199], v[102:105]
	v_mfma_f32_16x16x32_bf16 v[86:89], v[138:141], v[196:199], v[86:89]
	v_mfma_f32_16x16x32_bf16 v[126:129], v[134:137], v[176:179], v[126:129]
	v_mfma_f32_16x16x32_bf16 v[122:125], v[142:145], v[176:179], v[122:125]
	v_mfma_f32_16x16x32_bf16 v[118:121], v[134:137], v[184:187], v[118:121]
	v_mfma_f32_16x16x32_bf16 v[114:117], v[142:145], v[184:187], v[114:117]
	v_mfma_f32_16x16x32_bf16 v[110:113], v[134:137], v[192:195], v[110:113]
	v_mfma_f32_16x16x32_bf16 v[106:109], v[142:145], v[192:195], v[106:109]
	v_mfma_f32_16x16x32_bf16 v[102:105], v[134:137], v[200:203], v[102:105]
	v_mfma_f32_16x16x32_bf16 v[86:89], v[142:145], v[200:203], v[86:89]
	v_mfma_f32_16x16x32_bf16 v[98:101], v[146:149], v[172:175], v[98:101]
	v_mfma_f32_16x16x32_bf16 v[94:97], v[164:167], v[172:175], v[94:97]
	v_mfma_f32_16x16x32_bf16 v[90:93], v[146:149], v[180:183], v[90:93]
	v_mfma_f32_16x16x32_bf16 v[78:81], v[164:167], v[180:183], v[78:81]
	v_mfma_f32_16x16x32_bf16 v[74:77], v[146:149], v[188:191], v[74:77]
	v_mfma_f32_16x16x32_bf16 v[42:45], v[164:167], v[188:191], v[42:45]
	v_mfma_f32_16x16x32_bf16 v[38:41], v[146:149], v[196:199], v[38:41]
	v_mfma_f32_16x16x32_bf16 v[34:37], v[164:167], v[196:199], v[34:37]
	v_mfma_f32_16x16x32_bf16 v[98:101], v[160:163], v[176:179], v[98:101]
	v_mfma_f32_16x16x32_bf16 v[94:97], v[168:171], v[176:179], v[94:97]
	v_mfma_f32_16x16x32_bf16 v[90:93], v[160:163], v[184:187], v[90:93]
	v_mfma_f32_16x16x32_bf16 v[78:81], v[168:171], v[184:187], v[78:81]
	v_mfma_f32_16x16x32_bf16 v[74:77], v[160:163], v[192:195], v[74:77]
	v_mfma_f32_16x16x32_bf16 v[42:45], v[168:171], v[192:195], v[42:45]
	v_mfma_f32_16x16x32_bf16 v[38:41], v[160:163], v[200:203], v[38:41]
	v_mfma_f32_16x16x32_bf16 v[34:37], v[168:171], v[200:203], v[34:37]
	s_barrier
	s_add_i32 s86, s86, s41
	v_lshl_add_u64 v[204:205], s[84:85], 0, v[150:151]
	s_mov_b32 m0, s86
	ds_read_b128 v[172:175], v159 offset:16384
	ds_read_b128 v[176:179], v159 offset:17408
	ds_read_b128 v[180:183], v159 offset:18432
	ds_read_b128 v[184:187], v159 offset:19456
	ds_read_b128 v[188:191], v159 offset:20480
	ds_read_b128 v[192:195], v159 offset:21504
	ds_read_b128 v[196:199], v159 offset:22528
	ds_read_b128 v[200:203], v159 offset:23552
	global_load_lds_dwordx4 v[204:205], off
	s_add_i32 m0, s86, 0x2000
	v_lshl_add_u64 v[206:207], s[84:85], 0, v[152:153]
	s_add_u32 s84, s84, s10
	s_addc_u32 s85, s85, s11
	s_add_i32 s39, s39, s41
	global_load_lds_dwordx4 v[206:207], off
	v_lshl_add_u64 v[208:209], s[84:85], 0, v[150:151]
	s_mov_b32 m0, s39
	v_lshl_add_u64 v[210:211], s[84:85], 0, v[152:153]
	global_load_lds_dwordx4 v[208:209], off
	s_add_i32 m0, s39, 0x2000
	v_lshl_add_u64 v[212:213], s[36:37], 0, v[150:151]
	global_load_lds_dwordx4 v[210:211], off
	s_mov_b32 m0, s69
	v_lshl_add_u64 v[214:215], s[36:37], 0, v[152:153]
	global_load_lds_dwordx4 v[212:213], off
	s_mov_b32 m0, s70
	s_nop 0
	global_load_lds_dwordx4 v[214:215], off
	s_waitcnt vmcnt(8)
	s_waitcnt lgkmcnt(0)
	s_barrier
; #define PG8_STAGE(bufoff, gbase, voff) do { _Pragma("unroll") for (int _i = 0; _i < 2; ++_i) \
;         __builtin_amdgcn_global_load_lds((const unsigned*)((const char*)(gbase) + (voff)[_i]), (PG8_LAS unsigned*)(lds + (bufoff) + ldsw + _i * 8192), 16, 0, 0); } while (0)
; #define PG8_LDA(dst, b, h) do { _Pragma("unroll") for (int m = 0; m < 4; ++m) _Pragma("unroll") for (int k = 0; k < 2; ++k) dst[m][k] = *(const PG8_LAS bf16x8*)(lds + PG8_SA(b, h) + aoff + m * 2048 + k * 1024); } while (0)
; #define PG8_LDB(dst, b, h) do { _Pragma("unroll") for (int n = 0; n < 2; ++n) _Pragma("unroll") for (int k = 0; k < 2; ++k) dst[n][k] = *(const PG8_LAS bf16x8*)(lds + PG8_SB(b, h) + boff + n * 2048 + k * 1024); } while (0)
; #define PG8_MMA(ai, bj, At, Bt) do { __builtin_amdgcn_s_setprio(1); _Pragma("unroll") for (int m = 0; m < 4; ++m) _Pragma("unroll") for (int n = 0; n < 2; ++n) _Pragma("unroll") for (int k = 0; k < 2; ++k) \
;         acc[ai][bj][m][n] = __builtin_amdgcn_mfma_f32_16x16x32_bf16(Bt[n][k], At[m][k], acc[ai][bj][m][n], 0, 0, 0); __builtin_amdgcn_s_setprio(0); } while (0)
; #define PG8_WAIT_V(n) asm volatile("s_waitcnt vmcnt(" #n ")" ::: "memory")
; #define PG8_WAIT_L(n) asm volatile("s_waitcnt lgkmcnt(" #n ")" ::: "memory")
; #define PG8_BAR __builtin_amdgcn_s_barrier()
; #define PG8_SCHED __builtin_amdgcn_sched_barrier(0)
; template <class Epi, class Sched, bool ALIGN_EPI = false, bool SP2 = false>
; __device__ __forceinline__ void gemm_phase(PG8_LAS unsigned char* lds, const Gemm g, const Sched& S, const Epi& E) {
;     ...
;             PG8_WAIT_V(8); PG8_WAIT_L(0); PG8_BAR; PG8_MMA(1, 0, At, B0); PG8_MMA(1, 1, At, B1); PG8_BAR; PG8_SCHED;
;             PG8_LDB(B0, 1, 0); PG8_LDB(B1, 1, 1); PG8_SCHED; PG8_LDA(At, 1, 0); PG8_STAGE(PG8_SA(0, 1), a2 + hstep, voffA);
;             PG8_WAIT_V(8); PG8_WAIT_L(0); PG8_BAR; PG8_MMA(0, 0, At, B0); PG8_MMA(0, 1, At, B1); PG8_BAR; PG8_SCHED;
	s_waitcnt lgkmcnt(0)
	v_mfma_f32_16x16x32_bf16 v[82:85], v[130:133], v[172:175], v[82:85]
	v_mfma_f32_16x16x32_bf16 v[70:73], v[138:141], v[172:175], v[70:73]
	v_mfma_f32_16x16x32_bf16 v[66:69], v[130:133], v[180:183], v[66:69]
	v_mfma_f32_16x16x32_bf16 v[62:65], v[138:141], v[180:183], v[62:65]
	v_mfma_f32_16x16x32_bf16 v[58:61], v[130:133], v[188:191], v[58:61]
	v_mfma_f32_16x16x32_bf16 v[54:57], v[138:141], v[188:191], v[54:57]
	v_mfma_f32_16x16x32_bf16 v[50:53], v[130:133], v[196:199], v[50:53]
	v_mfma_f32_16x16x32_bf16 v[46:49], v[138:141], v[196:199], v[46:49]
	v_mfma_f32_16x16x32_bf16 v[82:85], v[134:137], v[176:179], v[82:85]
	v_mfma_f32_16x16x32_bf16 v[70:73], v[142:145], v[176:179], v[70:73]
	v_mfma_f32_16x16x32_bf16 v[66:69], v[134:137], v[184:187], v[66:69]
	v_mfma_f32_16x16x32_bf16 v[62:65], v[142:145], v[184:187], v[62:65]
	v_mfma_f32_16x16x32_bf16 v[58:61], v[134:137], v[192:195], v[58:61]
	v_mfma_f32_16x16x32_bf16 v[54:57], v[142:145], v[192:195], v[54:57]
	v_mfma_f32_16x16x32_bf16 v[50:53], v[134:137], v[200:203], v[50:53]
	v_mfma_f32_16x16x32_bf16 v[46:49], v[142:145], v[200:203], v[46:49]
	v_mfma_f32_16x16x32_bf16 v[30:33], v[146:149], v[172:175], v[30:33]
	v_mfma_f32_16x16x32_bf16 v[26:29], v[164:167], v[172:175], v[26:29]
	v_mfma_f32_16x16x32_bf16 v[22:25], v[146:149], v[180:183], v[22:25]
	v_mfma_f32_16x16x32_bf16 v[18:21], v[164:167], v[180:183], v[18:21]
	v_mfma_f32_16x16x32_bf16 v[14:17], v[146:149], v[188:191], v[14:17]
	v_mfma_f32_16x16x32_bf16 v[10:13], v[164:167], v[188:191], v[10:13]
	v_mfma_f32_16x16x32_bf16 v[6:9], v[146:149], v[196:199], v[6:9]
	v_mfma_f32_16x16x32_bf16 v[2:5], v[164:167], v[196:199], v[2:5]
	v_mfma_f32_16x16x32_bf16 v[30:33], v[160:163], v[176:179], v[30:33]
	v_mfma_f32_16x16x32_bf16 v[26:29], v[168:171], v[176:179], v[26:29]
	v_mfma_f32_16x16x32_bf16 v[22:25], v[160:163], v[184:187], v[22:25]
	v_mfma_f32_16x16x32_bf16 v[18:21], v[168:171], v[184:187], v[18:21]
	v_mfma_f32_16x16x32_bf16 v[14:17], v[160:163], v[192:195], v[14:17]
	v_mfma_f32_16x16x32_bf16 v[10:13], v[168:171], v[192:195], v[10:13]
	v_mfma_f32_16x16x32_bf16 v[6:9], v[160:163], v[200:203], v[6:9]
	v_mfma_f32_16x16x32_bf16 v[2:5], v[168:171], v[200:203], v[2:5]
	s_barrier
	s_add_i32 s39, 0, 0x18000
	v_add_u32_e32 v0, s39, v158
	s_add_i32 s84, 0, 0x1c000
	ds_read_b128 v[130:133], v0
	ds_read_b128 v[134:137], v0 offset:1024
	ds_read_b128 v[138:141], v0 offset:2048
	ds_read_b128 v[142:145], v0 offset:3072
	v_add_u32_e32 v0, s84, v158
	ds_read_b128 v[146:149], v0
	ds_read_b128 v[160:163], v0 offset:1024
	ds_read_b128 v[164:167], v0 offset:2048
	ds_read_b128 v[168:171], v0 offset:3072
	s_add_u32 s36, s36, s10
	s_addc_u32 s37, s37, s11
	s_mov_b32 m0, s71
	v_lshl_add_u64 v[220:221], s[36:37], 0, v[150:151]
	ds_read_b128 v[172:175], v159 offset:32768
	ds_read_b128 v[176:179], v159 offset:33792
	ds_read_b128 v[180:183], v159 offset:34816
	ds_read_b128 v[184:187], v159 offset:35840
	ds_read_b128 v[188:191], v159 offset:36864
	ds_read_b128 v[192:195], v159 offset:37888
	ds_read_b128 v[196:199], v159 offset:38912
	ds_read_b128 v[200:203], v159 offset:39936
	global_load_lds_dwordx4 v[220:221], off
	v_lshl_add_u64 v[220:221], s[36:37], 0, v[152:153]
	s_mov_b32 m0, s72
	s_nop 0
	global_load_lds_dwordx4 v[220:221], off
	s_waitcnt vmcnt(8)
	s_waitcnt lgkmcnt(0)
	s_barrier
	s_waitcnt lgkmcnt(0)
	v_mfma_f32_16x16x32_bf16 v[126:129], v[130:133], v[172:175], v[126:129]
	v_mfma_f32_16x16x32_bf16 v[122:125], v[138:141], v[172:175], v[122:125]
	v_mfma_f32_16x16x32_bf16 v[118:121], v[130:133], v[180:183], v[118:121]
	v_mfma_f32_16x16x32_bf16 v[114:117], v[138:141], v[180:183], v[114:117]
	v_mfma_f32_16x16x32_bf16 v[110:113], v[130:133], v[188:191], v[110:113]
	v_mfma_f32_16x16x32_bf16 v[106:109], v[138:141], v[188:191], v[106:109]
	v_mfma_f32_16x16x32_bf16 v[102:105], v[130:133], v[196:199], v[102:105]
	v_mfma_f32_16x16x32_bf16 v[86:89], v[138:141], v[196:199], v[86:89]
	v_mfma_f32_16x16x32_bf16 v[126:129], v[134:137], v[176:179], v[126:129]
	v_mfma_f32_16x16x32_bf16 v[122:125], v[142:145], v[176:179], v[122:125]
	v_mfma_f32_16x16x32_bf16 v[118:121], v[134:137], v[184:187], v[118:121]
	v_mfma_f32_16x16x32_bf16 v[114:117], v[142:145], v[184:187], v[114:117]
	v_mfma_f32_16x16x32_bf16 v[110:113], v[134:137], v[192:195], v[110:113]
	v_mfma_f32_16x16x32_bf16 v[106:109], v[142:145], v[192:195], v[106:109]
	v_mfma_f32_16x16x32_bf16 v[102:105], v[134:137], v[200:203], v[102:105]
	v_mfma_f32_16x16x32_bf16 v[86:89], v[142:145], v[200:203], v[86:89]
	v_mfma_f32_16x16x32_bf16 v[98:101], v[146:149], v[172:175], v[98:101]
	v_mfma_f32_16x16x32_bf16 v[94:97], v[164:167], v[172:175], v[94:97]
	v_mfma_f32_16x16x32_bf16 v[90:93], v[146:149], v[180:183], v[90:93]
	v_mfma_f32_16x16x32_bf16 v[78:81], v[164:167], v[180:183], v[78:81]
	v_mfma_f32_16x16x32_bf16 v[74:77], v[146:149], v[188:191], v[74:77]
	v_mfma_f32_16x16x32_bf16 v[42:45], v[164:167], v[188:191], v[42:45]
	v_mfma_f32_16x16x32_bf16 v[38:41], v[146:149], v[196:199], v[38:41]
	v_mfma_f32_16x16x32_bf16 v[34:37], v[164:167], v[196:199], v[34:37]
	v_mfma_f32_16x16x32_bf16 v[98:101], v[160:163], v[176:179], v[98:101]
	v_mfma_f32_16x16x32_bf16 v[94:97], v[168:171], v[176:179], v[94:97]
	v_mfma_f32_16x16x32_bf16 v[90:93], v[160:163], v[184:187], v[90:93]
	v_mfma_f32_16x16x32_bf16 v[78:81], v[168:171], v[184:187], v[78:81]
	v_mfma_f32_16x16x32_bf16 v[74:77], v[160:163], v[192:195], v[74:77]
	v_mfma_f32_16x16x32_bf16 v[42:45], v[168:171], v[192:195], v[42:45]
	v_mfma_f32_16x16x32_bf16 v[38:41], v[160:163], v[200:203], v[38:41]
	v_mfma_f32_16x16x32_bf16 v[34:37], v[168:171], v[200:203], v[34:37]
	s_barrier
; #define PG8_STAGE(bufoff, gbase, voff) do { _Pragma("unroll") for (int _i = 0; _i < 2; ++_i) \
;         __builtin_amdgcn_global_load_lds((const unsigned*)((const char*)(gbase) + (voff)[_i]), (PG8_LAS unsigned*)(lds + (bufoff) + ldsw + _i * 8192), 16, 0, 0); } while (0)
; #define PG8_LDA(dst, b, h) do { _Pragma("unroll") for (int m = 0; m < 4; ++m) _Pragma("unroll") for (int k = 0; k < 2; ++k) dst[m][k] = *(const PG8_LAS bf16x8*)(lds + PG8_SA(b, h) + aoff + m * 2048 + k * 1024); } while (0)
; #define PG8_MMA(ai, bj, At, Bt) do { __builtin_amdgcn_s_setprio(1); _Pragma("unroll") for (int m = 0; m < 4; ++m) _Pragma("unroll") for (int n = 0; n < 2; ++n) _Pragma("unroll") for (int k = 0; k < 2; ++k) \
;         acc[ai][bj][m][n] = __builtin_amdgcn_mfma_f32_16x16x32_bf16(Bt[n][k], At[m][k], acc[ai][bj][m][n], 0, 0, 0); __builtin_amdgcn_s_setprio(0); } while (0)
; #define PG8_WAIT_V(n) asm volatile("s_waitcnt vmcnt(" #n ")" ::: "memory")
; #define PG8_WAIT_L(n) asm volatile("s_waitcnt lgkmcnt(" #n ")" ::: "memory")
; #define PG8_BAR __builtin_amdgcn_s_barrier()
; #define PG8_SCHED __builtin_amdgcn_sched_barrier(0)
; template <class Epi, class Sched, bool ALIGN_EPI = false, bool SP2 = false>
; __device__ __forceinline__ void gemm_phase(PG8_LAS unsigned char* lds, const Gemm g, const Sched& S, const Epi& E) {
;     ...
;             PG8_LDA(At, 1, 1); PG8_STAGE(PG8_SB(1, 0), b3, voffB); PG8_STAGE(PG8_SB(1, 1), b3 + hstep, voffB); PG8_STAGE(PG8_SA(1, 0), a3, voffA);
;             PG8_WAIT_V(8); PG8_WAIT_L(0); PG8_BAR; PG8_MMA(1, 0, At, B0); PG8_MMA(1, 1, At, B1); PG8_BAR; PG8_SCHED;
	s_add_i32 s36, s39, s41
	v_lshl_add_u64 v[204:205], v[204:205], 0, s[28:29]
	s_mov_b32 m0, s36
	ds_read_b128 v[172:175], v159 offset:49152
	ds_read_b128 v[176:179], v159 offset:50176
	ds_read_b128 v[180:183], v159 offset:51200
	ds_read_b128 v[184:187], v159 offset:52224
	ds_read_b128 v[188:191], v159 offset:53248
	ds_read_b128 v[192:195], v159 offset:54272
	ds_read_b128 v[196:199], v159 offset:55296
	ds_read_b128 v[200:203], v159 offset:56320
	global_load_lds_dwordx4 v[204:205], off
	v_lshl_add_u64 v[204:205], v[206:207], 0, s[28:29]
	s_add_i32 m0, s36, 0x2000
	s_add_i32 s36, s84, s41
	global_load_lds_dwordx4 v[204:205], off
	v_lshl_add_u64 v[204:205], v[208:209], 0, s[28:29]
	s_mov_b32 m0, s36
	s_nop 0
	global_load_lds_dwordx4 v[204:205], off
	v_lshl_add_u64 v[204:205], v[210:211], 0, s[28:29]
	s_add_i32 m0, s36, 0x2000
	s_nop 0
	global_load_lds_dwordx4 v[204:205], off
	v_lshl_add_u64 v[204:205], v[212:213], 0, s[28:29]
	s_mov_b32 m0, s76
	s_nop 0
	global_load_lds_dwordx4 v[204:205], off
	v_lshl_add_u64 v[204:205], v[214:215], 0, s[28:29]
	s_mov_b32 m0, s77
	s_nop 0
	global_load_lds_dwordx4 v[204:205], off
	s_waitcnt vmcnt(8)
	s_waitcnt lgkmcnt(0)
	s_barrier
	s_waitcnt lgkmcnt(0)
	v_mfma_f32_16x16x32_bf16 v[82:85], v[130:133], v[172:175], v[82:85]
	v_mfma_f32_16x16x32_bf16 v[70:73], v[138:141], v[172:175], v[70:73]
	v_mfma_f32_16x16x32_bf16 v[66:69], v[130:133], v[180:183], v[66:69]
	v_mfma_f32_16x16x32_bf16 v[62:65], v[138:141], v[180:183], v[62:65]
	v_mfma_f32_16x16x32_bf16 v[58:61], v[130:133], v[188:191], v[58:61]
	v_mfma_f32_16x16x32_bf16 v[54:57], v[138:141], v[188:191], v[54:57]
	v_mfma_f32_16x16x32_bf16 v[50:53], v[130:133], v[196:199], v[50:53]
	v_mfma_f32_16x16x32_bf16 v[46:49], v[138:141], v[196:199], v[46:49]
	v_mfma_f32_16x16x32_bf16 v[82:85], v[134:137], v[176:179], v[82:85]
	v_mfma_f32_16x16x32_bf16 v[70:73], v[142:145], v[176:179], v[70:73]
	v_mfma_f32_16x16x32_bf16 v[66:69], v[134:137], v[184:187], v[66:69]
	v_mfma_f32_16x16x32_bf16 v[62:65], v[142:145], v[184:187], v[62:65]
	v_mfma_f32_16x16x32_bf16 v[58:61], v[134:137], v[192:195], v[58:61]
	v_mfma_f32_16x16x32_bf16 v[54:57], v[142:145], v[192:195], v[54:57]
	v_mfma_f32_16x16x32_bf16 v[50:53], v[134:137], v[200:203], v[50:53]
	v_mfma_f32_16x16x32_bf16 v[46:49], v[142:145], v[200:203], v[46:49]
	v_mfma_f32_16x16x32_bf16 v[30:33], v[146:149], v[172:175], v[30:33]
	v_mfma_f32_16x16x32_bf16 v[26:29], v[164:167], v[172:175], v[26:29]
	v_mfma_f32_16x16x32_bf16 v[22:25], v[146:149], v[180:183], v[22:25]
	v_mfma_f32_16x16x32_bf16 v[18:21], v[164:167], v[180:183], v[18:21]
	v_mfma_f32_16x16x32_bf16 v[14:17], v[146:149], v[188:191], v[14:17]
	v_mfma_f32_16x16x32_bf16 v[10:13], v[164:167], v[188:191], v[10:13]
	v_mfma_f32_16x16x32_bf16 v[6:9], v[146:149], v[196:199], v[6:9]
	v_mfma_f32_16x16x32_bf16 v[2:5], v[164:167], v[196:199], v[2:5]
	v_mfma_f32_16x16x32_bf16 v[30:33], v[160:163], v[176:179], v[30:33]
	v_mfma_f32_16x16x32_bf16 v[26:29], v[168:171], v[176:179], v[26:29]
	v_mfma_f32_16x16x32_bf16 v[22:25], v[160:163], v[184:187], v[22:25]
	v_mfma_f32_16x16x32_bf16 v[18:21], v[168:171], v[184:187], v[18:21]
	v_mfma_f32_16x16x32_bf16 v[14:17], v[160:163], v[192:195], v[14:17]
	v_mfma_f32_16x16x32_bf16 v[10:13], v[168:171], v[192:195], v[10:13]
	v_mfma_f32_16x16x32_bf16 v[6:9], v[160:163], v[200:203], v[6:9]
	v_mfma_f32_16x16x32_bf16 v[2:5], v[168:171], v[200:203], v[2:5]
	s_barrier
	s_add_u32 s82, s82, 0x100
	s_addc_u32 s83, s83, 0
	s_add_u32 s6, s6, 0x100
	s_addc_u32 s7, s7, 0
	s_cmp_ge_i32 s38, s73
	s_mov_b32 s36, s38
	s_cbranch_scc0 .LBB0_717
;     __device__ __forceinline__ void operator()(const f32x4 (&acc)[2][2][4][2], const Unit& u, int wr, int wc, int fr_in, int fq_in) const {
;     ...
;             for (int ai = 0; ai < 2; ++ai)
; #pragma unroll
;                 for (int m = 0; m < 4; ++m) {
;                     const int r = row0 + ai * HALF + m * 16;
;                     f32x4 x1 = acc[ai][bj][m][0] * qs, x2 = acc[ai][bj][m][1] * qs;
;                     if (isrope) {
	v_pk_mul_f32 v[148:149], v[128:129], s[54:55] op_sel_hi:[1,0]
	v_pk_mul_f32 v[146:147], v[126:127], s[54:55] op_sel_hi:[1,0]
	v_pk_mul_f32 v[144:145], v[124:125], s[54:55] op_sel_hi:[1,0]
	v_pk_mul_f32 v[142:143], v[122:123], s[54:55] op_sel_hi:[1,0]
	v_pk_mul_f32 v[140:141], v[120:121], s[54:55] op_sel_hi:[1,0]
	v_pk_mul_f32 v[138:139], v[118:119], s[54:55] op_sel_hi:[1,0]
	v_pk_mul_f32 v[136:137], v[116:117], s[54:55] op_sel_hi:[1,0]
	v_pk_mul_f32 v[134:135], v[114:115], s[54:55] op_sel_hi:[1,0]
	v_pk_mul_f32 v[132:133], v[112:113], s[54:55] op_sel_hi:[1,0]
	v_pk_mul_f32 v[130:131], v[110:111], s[54:55] op_sel_hi:[1,0]
	v_pk_mul_f32 v[128:129], v[108:109], s[54:55] op_sel_hi:[1,0]
	v_pk_mul_f32 v[126:127], v[106:107], s[54:55] op_sel_hi:[1,0]
	v_pk_mul_f32 v[124:125], v[104:105], s[54:55] op_sel_hi:[1,0]
	v_pk_mul_f32 v[122:123], v[102:103], s[54:55] op_sel_hi:[1,0]
	v_pk_mul_f32 v[120:121], v[88:89], s[54:55] op_sel_hi:[1,0]
	v_pk_mul_f32 v[118:119], v[86:87], s[54:55] op_sel_hi:[1,0]
	v_pk_mul_f32 v[116:117], v[84:85], s[54:55] op_sel_hi:[1,0]
	v_pk_mul_f32 v[114:115], v[82:83], s[54:55] op_sel_hi:[1,0]
	v_pk_mul_f32 v[112:113], v[72:73], s[54:55] op_sel_hi:[1,0]
	v_pk_mul_f32 v[110:111], v[70:71], s[54:55] op_sel_hi:[1,0]
	v_pk_mul_f32 v[108:109], v[68:69], s[54:55] op_sel_hi:[1,0]
	v_pk_mul_f32 v[106:107], v[66:67], s[54:55] op_sel_hi:[1,0]
	v_pk_mul_f32 v[104:105], v[64:65], s[54:55] op_sel_hi:[1,0]
	v_pk_mul_f32 v[102:103], v[62:63], s[54:55] op_sel_hi:[1,0]
	v_pk_mul_f32 v[88:89], v[60:61], s[54:55] op_sel_hi:[1,0]
	v_pk_mul_f32 v[86:87], v[58:59], s[54:55] op_sel_hi:[1,0]
	v_pk_mul_f32 v[84:85], v[56:57], s[54:55] op_sel_hi:[1,0]
	v_pk_mul_f32 v[82:83], v[54:55], s[54:55] op_sel_hi:[1,0]
	v_pk_mul_f32 v[72:73], v[52:53], s[54:55] op_sel_hi:[1,0]
	v_pk_mul_f32 v[70:71], v[50:51], s[54:55] op_sel_hi:[1,0]
	v_pk_mul_f32 v[68:69], v[48:49], s[54:55] op_sel_hi:[1,0]
	v_pk_mul_f32 v[66:67], v[46:47], s[54:55] op_sel_hi:[1,0]
	v_pk_mul_f32 v[64:65], v[100:101], s[54:55] op_sel_hi:[1,0]
	v_pk_mul_f32 v[62:63], v[98:99], s[54:55] op_sel_hi:[1,0]
	v_pk_mul_f32 v[60:61], v[96:97], s[54:55] op_sel_hi:[1,0]
	v_pk_mul_f32 v[58:59], v[94:95], s[54:55] op_sel_hi:[1,0]
	v_pk_mul_f32 v[56:57], v[92:93], s[54:55] op_sel_hi:[1,0]
	v_pk_mul_f32 v[54:55], v[90:91], s[54:55] op_sel_hi:[1,0]
	v_pk_mul_f32 v[52:53], v[80:81], s[54:55] op_sel_hi:[1,0]
	v_pk_mul_f32 v[50:51], v[78:79], s[54:55] op_sel_hi:[1,0]
	v_pk_mul_f32 v[48:49], v[76:77], s[54:55] op_sel_hi:[1,0]
	v_pk_mul_f32 v[46:47], v[74:75], s[54:55] op_sel_hi:[1,0]
	v_pk_mul_f32 v[44:45], v[44:45], s[54:55] op_sel_hi:[1,0]
	v_pk_mul_f32 v[42:43], v[42:43], s[54:55] op_sel_hi:[1,0]
	v_pk_mul_f32 v[40:41], v[40:41], s[54:55] op_sel_hi:[1,0]
	v_pk_mul_f32 v[38:39], v[38:39], s[54:55] op_sel_hi:[1,0]
	v_pk_mul_f32 v[36:37], v[36:37], s[54:55] op_sel_hi:[1,0]
	v_pk_mul_f32 v[34:35], v[34:35], s[54:55] op_sel_hi:[1,0]
	v_pk_mul_f32 v[32:33], v[32:33], s[54:55] op_sel_hi:[1,0]
	v_pk_mul_f32 v[30:31], v[30:31], s[54:55] op_sel_hi:[1,0]
	v_pk_mul_f32 v[28:29], v[28:29], s[54:55] op_sel_hi:[1,0]
	v_pk_mul_f32 v[26:27], v[26:27], s[54:55] op_sel_hi:[1,0]
	v_pk_mul_f32 v[24:25], v[24:25], s[54:55] op_sel_hi:[1,0]
	v_pk_mul_f32 v[22:23], v[22:23], s[54:55] op_sel_hi:[1,0]
	v_pk_mul_f32 v[20:21], v[20:21], s[54:55] op_sel_hi:[1,0]
	v_pk_mul_f32 v[18:19], v[18:19], s[54:55] op_sel_hi:[1,0]
	v_pk_mul_f32 v[16:17], v[16:17], s[54:55] op_sel_hi:[1,0]
	v_pk_mul_f32 v[14:15], v[14:15], s[54:55] op_sel_hi:[1,0]
	v_pk_mul_f32 v[12:13], v[12:13], s[54:55] op_sel_hi:[1,0]
	v_pk_mul_f32 v[10:11], v[10:11], s[54:55] op_sel_hi:[1,0]
	v_pk_mul_f32 v[8:9], v[8:9], s[54:55] op_sel_hi:[1,0]
	v_pk_mul_f32 v[6:7], v[6:7], s[54:55] op_sel_hi:[1,0]
	v_pk_mul_f32 v[4:5], v[4:5], s[54:55] op_sel_hi:[1,0]
	v_pk_mul_f32 v[2:3], v[2:3], s[54:55] op_sel_hi:[1,0]
	s_mov_b64 s[84:85], 0x1000
	s_and_b64 vcc, exec, s[26:27]
	s_cbranch_vccnz .LBB0_722
	s_branch .LBB0_723

; #define PG8_STAGE(bufoff, gbase, voff) do { _Pragma("unroll") for (int _i = 0; _i < 2; ++_i) \
;         __builtin_amdgcn_global_load_lds((const unsigned*)((const char*)(gbase) + (voff)[_i]), (PG8_LAS unsigned*)(lds + (bufoff) + ldsw + _i * 8192), 16, 0, 0); } while (0)
; #define PG8_LDA(dst, b, h) do { _Pragma("unroll") for (int m = 0; m < 4; ++m) _Pragma("unroll") for (int k = 0; k < 2; ++k) dst[m][k] = *(const PG8_LAS bf16x8*)(lds + PG8_SA(b, h) + aoff + m * 2048 + k * 1024); } while (0)
; #define PG8_LDB(dst, b, h) do { _Pragma("unroll") for (int n = 0; n < 2; ++n) _Pragma("unroll") for (int k = 0; k < 2; ++k) dst[n][k] = *(const PG8_LAS bf16x8*)(lds + PG8_SB(b, h) + boff + n * 2048 + k * 1024); } while (0)
; #define PG8_MMA(ai, bj, At, Bt) do { __builtin_amdgcn_s_setprio(1); _Pragma("unroll") for (int m = 0; m < 4; ++m) _Pragma("unroll") for (int n = 0; n < 2; ++n) _Pragma("unroll") for (int k = 0; k < 2; ++k) \
;         acc[ai][bj][m][n] = __builtin_amdgcn_mfma_f32_16x16x32_bf16(Bt[n][k], At[m][k], acc[ai][bj][m][n], 0, 0, 0); __builtin_amdgcn_s_setprio(0); } while (0)
; #define PG8_WAIT_V(n) asm volatile("s_waitcnt vmcnt(" #n ")" ::: "memory")
; #define PG8_WAIT_L(n) asm volatile("s_waitcnt lgkmcnt(" #n ")" ::: "memory")
; template <class Epi, class Sched, bool ALIGN_EPI = false, bool SP2 = false>
; __device__ __forceinline__ void gemm_phase(PG8_LAS unsigned char* lds, const Gemm g, const Sched& S, const Epi& E) {
;     ...
;             const bool last = (t == nt - 2);
;             const char* a1 = cA + (size_t)(t + 1) * kstep;
;             const char* a2 = last ? nA : cA + (size_t)(t + 2) * kstep; const char* b2 = last ? nB : cB + (size_t)(t + 2) * kstep;
;             const char* a3 = a2 + kstep; const char* b3 = b2 + kstep;
;             if (last && has_next) S.a_ready(nxt);
;             if constexpr (SP2) {
;             PG8_LDB(B0, 0, 0); PG8_LDB(B1, 0, 1); PG8_SCHED; PG8_LDA(At, 0, 0); PG8_STAGE(PG8_SA(1, 1), a1 + hstep, voffA);
;             PG8_WAIT_V(8); PG8_WAIT_L(0); PG8_BAR; PG8_MMA(0, 0, At, B0); PG8_MMA(0, 1, At, B1); PG8_BAR; PG8_SCHED;
;             PG8_LDA(At, 0, 1); PG8_STAGE(PG8_SB(0, 0), b2, voffB); PG8_STAGE(PG8_SB(0, 1), b2 + hstep, voffB); PG8_STAGE(PG8_SA(0, 0), a2, voffA);
;             PG8_WAIT_V(8); PG8_WAIT_L(0); PG8_BAR; PG8_MMA(1, 0, At, B0); PG8_MMA(1, 1, At, B1); PG8_BAR; PG8_SCHED;
.LBB0_783:
	s_add_i32 s38, s36, 2
	s_add_u32 s39, s4, 0x80
	s_addc_u32 s37, s5, 0
	s_add_i32 vcc_lo, 0, 0x10000
	s_cmp_eq_u32 s79, s36
	s_cselect_b32 s37, s63, s37
	s_cselect_b32 s36, s62, s39
	v_add_u32_e32 v0, vcc_lo, v146
	s_cselect_b32 s87, s65, s41
	s_cselect_b32 s86, s64, s40
	s_add_i32 s39, 0, 0x14000
	ds_read_b128 v[142:145], v0
	ds_read_b128 v[148:151], v0 offset:1024
	ds_read_b128 v[152:155], v0 offset:2048
	ds_read_b128 v[156:159], v0 offset:3072
	v_add_u32_e32 v0, s39, v146
	ds_read_b128 v[160:163], v0
	ds_read_b128 v[164:167], v0 offset:1024
	ds_read_b128 v[168:171], v0 offset:2048
	ds_read_b128 v[172:175], v0 offset:3072
	v_lshl_add_u64 v[208:209], s[4:5], 0, v[140:141]
	s_add_i32 m0, s72, 0xc000
	ds_read_b128 v[176:179], v147
	ds_read_b128 v[180:183], v147 offset:1024
	ds_read_b128 v[184:187], v147 offset:2048
	ds_read_b128 v[188:191], v147 offset:3072
	ds_read_b128 v[192:195], v147 offset:4096
	ds_read_b128 v[196:199], v147 offset:5120
	ds_read_b128 v[200:203], v147 offset:6144
	ds_read_b128 v[204:207], v147 offset:7168
	global_load_lds_dwordx4 v[208:209], off
	v_lshl_add_u64 v[208:209], s[4:5], 0, v[138:139]
	s_add_i32 m0, s72, 0xe000
	s_nop 0
	global_load_lds_dwordx4 v[208:209], off
	s_waitcnt vmcnt(8)
	s_waitcnt lgkmcnt(0)
	s_barrier
	s_waitcnt lgkmcnt(0)
	v_mfma_f32_16x16x32_bf16 v[122:125], v[142:145], v[176:179], v[122:125]
	v_mfma_f32_16x16x32_bf16 v[126:129], v[152:155], v[176:179], v[126:129]
	v_mfma_f32_16x16x32_bf16 v[110:113], v[142:145], v[184:187], v[110:113]
	v_mfma_f32_16x16x32_bf16 v[106:109], v[152:155], v[184:187], v[106:109]
	v_mfma_f32_16x16x32_bf16 v[94:97], v[142:145], v[192:195], v[94:97]
	v_mfma_f32_16x16x32_bf16 v[90:93], v[152:155], v[192:195], v[90:93]
	v_mfma_f32_16x16x32_bf16 v[78:81], v[142:145], v[200:203], v[78:81]
	v_mfma_f32_16x16x32_bf16 v[74:77], v[152:155], v[200:203], v[74:77]
	v_mfma_f32_16x16x32_bf16 v[122:125], v[148:151], v[180:183], v[122:125]
	v_mfma_f32_16x16x32_bf16 v[126:129], v[156:159], v[180:183], v[126:129]
	v_mfma_f32_16x16x32_bf16 v[110:113], v[148:151], v[188:191], v[110:113]
	v_mfma_f32_16x16x32_bf16 v[106:109], v[156:159], v[188:191], v[106:109]
	v_mfma_f32_16x16x32_bf16 v[94:97], v[148:151], v[196:199], v[94:97]
	v_mfma_f32_16x16x32_bf16 v[90:93], v[156:159], v[196:199], v[90:93]
	v_mfma_f32_16x16x32_bf16 v[78:81], v[148:151], v[204:207], v[78:81]
	v_mfma_f32_16x16x32_bf16 v[74:77], v[156:159], v[204:207], v[74:77]
	v_mfma_f32_16x16x32_bf16 v[118:121], v[160:163], v[176:179], v[118:121]
	v_mfma_f32_16x16x32_bf16 v[114:117], v[168:171], v[176:179], v[114:117]
	v_mfma_f32_16x16x32_bf16 v[102:105], v[160:163], v[184:187], v[102:105]
	v_mfma_f32_16x16x32_bf16 v[98:101], v[168:171], v[184:187], v[98:101]
	v_mfma_f32_16x16x32_bf16 v[86:89], v[160:163], v[192:195], v[86:89]
	v_mfma_f32_16x16x32_bf16 v[82:85], v[168:171], v[192:195], v[82:85]
	v_mfma_f32_16x16x32_bf16 v[70:73], v[160:163], v[200:203], v[70:73]
	v_mfma_f32_16x16x32_bf16 v[66:69], v[168:171], v[200:203], v[66:69]
	v_mfma_f32_16x16x32_bf16 v[118:121], v[164:167], v[180:183], v[118:121]
	v_mfma_f32_16x16x32_bf16 v[114:117], v[172:175], v[180:183], v[114:117]
	v_mfma_f32_16x16x32_bf16 v[102:105], v[164:167], v[188:191], v[102:105]
	v_mfma_f32_16x16x32_bf16 v[98:101], v[172:175], v[188:191], v[98:101]
	v_mfma_f32_16x16x32_bf16 v[86:89], v[164:167], v[196:199], v[86:89]
	v_mfma_f32_16x16x32_bf16 v[82:85], v[172:175], v[196:199], v[82:85]
	v_mfma_f32_16x16x32_bf16 v[70:73], v[164:167], v[204:207], v[70:73]
	v_mfma_f32_16x16x32_bf16 v[66:69], v[172:175], v[204:207], v[66:69]
	s_barrier
	s_add_i32 vcc_lo, vcc_lo, s71
	v_lshl_add_u64 v[208:209], s[86:87], 0, v[132:133]
	s_mov_b32 m0, vcc_lo
	ds_read_b128 v[176:179], v147 offset:16384
	ds_read_b128 v[180:183], v147 offset:17408
	ds_read_b128 v[184:187], v147 offset:18432
	ds_read_b128 v[188:191], v147 offset:19456
	ds_read_b128 v[192:195], v147 offset:20480
	ds_read_b128 v[196:199], v147 offset:21504
	ds_read_b128 v[200:203], v147 offset:22528
	ds_read_b128 v[204:207], v147 offset:23552
	global_load_lds_dwordx4 v[208:209], off
	s_add_i32 m0, vcc_lo, 0x2000
	v_lshl_add_u64 v[210:211], s[86:87], 0, v[136:137]
	s_add_u32 s86, s86, s6
	s_addc_u32 s87, s87, s7
	s_add_i32 s39, s39, s71
	global_load_lds_dwordx4 v[210:211], off
	v_lshl_add_u64 v[212:213], s[86:87], 0, v[132:133]
	s_mov_b32 m0, s39
	v_lshl_add_u64 v[214:215], s[86:87], 0, v[136:137]
	global_load_lds_dwordx4 v[212:213], off
	s_add_i32 m0, s39, 0x2000
	v_lshl_add_u64 v[220:221], s[36:37], 0, v[130:131]
	global_load_lds_dwordx4 v[214:215], off
	s_mov_b32 m0, s72
	v_lshl_add_u64 v[222:223], s[36:37], 0, v[134:135]
	global_load_lds_dwordx4 v[220:221], off
	s_mov_b32 m0, s74
	s_nop 0
	global_load_lds_dwordx4 v[222:223], off
	s_waitcnt vmcnt(8)
	s_waitcnt lgkmcnt(0)
	s_barrier
; #define PG8_STAGE(bufoff, gbase, voff) do { _Pragma("unroll") for (int _i = 0; _i < 2; ++_i) \
;         __builtin_amdgcn_global_load_lds((const unsigned*)((const char*)(gbase) + (voff)[_i]), (PG8_LAS unsigned*)(lds + (bufoff) + ldsw + _i * 8192), 16, 0, 0); } while (0)
; #define PG8_LDA(dst, b, h) do { _Pragma("unroll") for (int m = 0; m < 4; ++m) _Pragma("unroll") for (int k = 0; k < 2; ++k) dst[m][k] = *(const PG8_LAS bf16x8*)(lds + PG8_SA(b, h) + aoff + m * 2048 + k * 1024); } while (0)
; #define PG8_LDB(dst, b, h) do { _Pragma("unroll") for (int n = 0; n < 2; ++n) _Pragma("unroll") for (int k = 0; k < 2; ++k) dst[n][k] = *(const PG8_LAS bf16x8*)(lds + PG8_SB(b, h) + boff + n * 2048 + k * 1024); } while (0)
; #define PG8_MMA(ai, bj, At, Bt) do { __builtin_amdgcn_s_setprio(1); _Pragma("unroll") for (int m = 0; m < 4; ++m) _Pragma("unroll") for (int n = 0; n < 2; ++n) _Pragma("unroll") for (int k = 0; k < 2; ++k) \
;         acc[ai][bj][m][n] = __builtin_amdgcn_mfma_f32_16x16x32_bf16(Bt[n][k], At[m][k], acc[ai][bj][m][n], 0, 0, 0); __builtin_amdgcn_s_setprio(0); } while (0)
; #define PG8_WAIT_V(n) asm volatile("s_waitcnt vmcnt(" #n ")" ::: "memory")
; #define PG8_WAIT_L(n) asm volatile("s_waitcnt lgkmcnt(" #n ")" ::: "memory")
; #define PG8_BAR __builtin_amdgcn_s_barrier()
; #define PG8_SCHED __builtin_amdgcn_sched_barrier(0)
; template <class Epi, class Sched, bool ALIGN_EPI = false, bool SP2 = false>
; __device__ __forceinline__ void gemm_phase(PG8_LAS unsigned char* lds, const Gemm g, const Sched& S, const Epi& E) {
;     ...
;             PG8_WAIT_V(8); PG8_WAIT_L(0); PG8_BAR; PG8_MMA(1, 0, At, B0); PG8_MMA(1, 1, At, B1); PG8_BAR; PG8_SCHED;
;             PG8_LDB(B0, 1, 0); PG8_LDB(B1, 1, 1); PG8_SCHED; PG8_LDA(At, 1, 0); PG8_STAGE(PG8_SA(0, 1), a2 + hstep, voffA);
;             PG8_WAIT_V(8); PG8_WAIT_L(0); PG8_BAR; PG8_MMA(0, 0, At, B0); PG8_MMA(0, 1, At, B1); PG8_BAR; PG8_SCHED;
	s_waitcnt lgkmcnt(0)
	v_mfma_f32_16x16x32_bf16 v[62:65], v[142:145], v[176:179], v[62:65]
	v_mfma_f32_16x16x32_bf16 v[58:61], v[152:155], v[176:179], v[58:61]
	v_mfma_f32_16x16x32_bf16 v[46:49], v[142:145], v[184:187], v[46:49]
	v_mfma_f32_16x16x32_bf16 v[42:45], v[152:155], v[184:187], v[42:45]
	v_mfma_f32_16x16x32_bf16 v[30:33], v[142:145], v[192:195], v[30:33]
	v_mfma_f32_16x16x32_bf16 v[26:29], v[152:155], v[192:195], v[26:29]
	v_mfma_f32_16x16x32_bf16 v[14:17], v[142:145], v[200:203], v[14:17]
	v_mfma_f32_16x16x32_bf16 v[10:13], v[152:155], v[200:203], v[10:13]
	v_mfma_f32_16x16x32_bf16 v[62:65], v[148:151], v[180:183], v[62:65]
	v_mfma_f32_16x16x32_bf16 v[58:61], v[156:159], v[180:183], v[58:61]
	v_mfma_f32_16x16x32_bf16 v[46:49], v[148:151], v[188:191], v[46:49]
	v_mfma_f32_16x16x32_bf16 v[42:45], v[156:159], v[188:191], v[42:45]
	v_mfma_f32_16x16x32_bf16 v[30:33], v[148:151], v[196:199], v[30:33]
	v_mfma_f32_16x16x32_bf16 v[26:29], v[156:159], v[196:199], v[26:29]
	v_mfma_f32_16x16x32_bf16 v[14:17], v[148:151], v[204:207], v[14:17]
	v_mfma_f32_16x16x32_bf16 v[10:13], v[156:159], v[204:207], v[10:13]
	v_mfma_f32_16x16x32_bf16 v[54:57], v[160:163], v[176:179], v[54:57]
	v_mfma_f32_16x16x32_bf16 v[50:53], v[168:171], v[176:179], v[50:53]
	v_mfma_f32_16x16x32_bf16 v[38:41], v[160:163], v[184:187], v[38:41]
	v_mfma_f32_16x16x32_bf16 v[34:37], v[168:171], v[184:187], v[34:37]
	v_mfma_f32_16x16x32_bf16 v[22:25], v[160:163], v[192:195], v[22:25]
	v_mfma_f32_16x16x32_bf16 v[18:21], v[168:171], v[192:195], v[18:21]
	v_mfma_f32_16x16x32_bf16 v[6:9], v[160:163], v[200:203], v[6:9]
	v_mfma_f32_16x16x32_bf16 v[2:5], v[168:171], v[200:203], v[2:5]
	v_mfma_f32_16x16x32_bf16 v[54:57], v[164:167], v[180:183], v[54:57]
	v_mfma_f32_16x16x32_bf16 v[50:53], v[172:175], v[180:183], v[50:53]
	v_mfma_f32_16x16x32_bf16 v[38:41], v[164:167], v[188:191], v[38:41]
	v_mfma_f32_16x16x32_bf16 v[34:37], v[172:175], v[188:191], v[34:37]
	v_mfma_f32_16x16x32_bf16 v[22:25], v[164:167], v[196:199], v[22:25]
	v_mfma_f32_16x16x32_bf16 v[18:21], v[172:175], v[196:199], v[18:21]
	v_mfma_f32_16x16x32_bf16 v[6:9], v[164:167], v[204:207], v[6:9]
	v_mfma_f32_16x16x32_bf16 v[2:5], v[172:175], v[204:207], v[2:5]
	s_barrier
	s_add_i32 s39, 0, 0x18000
	v_add_u32_e32 v0, s39, v146
	s_add_i32 s86, 0, 0x1c000
	ds_read_b128 v[142:145], v0
	ds_read_b128 v[148:151], v0 offset:1024
	ds_read_b128 v[152:155], v0 offset:2048
	ds_read_b128 v[156:159], v0 offset:3072
	v_add_u32_e32 v0, s86, v146
	ds_read_b128 v[160:163], v0
	ds_read_b128 v[164:167], v0 offset:1024
	ds_read_b128 v[168:171], v0 offset:2048
	ds_read_b128 v[172:175], v0 offset:3072
	s_add_u32 s36, s36, s6
	s_addc_u32 s37, s37, s7
	s_mov_b32 m0, s75
	v_lshl_add_u64 v[224:225], s[36:37], 0, v[130:131]
	ds_read_b128 v[176:179], v147 offset:32768
	ds_read_b128 v[180:183], v147 offset:33792
	ds_read_b128 v[184:187], v147 offset:34816
	ds_read_b128 v[188:191], v147 offset:35840
	ds_read_b128 v[192:195], v147 offset:36864
	ds_read_b128 v[196:199], v147 offset:37888
	ds_read_b128 v[200:203], v147 offset:38912
	ds_read_b128 v[204:207], v147 offset:39936
	global_load_lds_dwordx4 v[224:225], off
	v_lshl_add_u64 v[224:225], s[36:37], 0, v[134:135]
	s_mov_b32 m0, s76
	s_nop 0
	global_load_lds_dwordx4 v[224:225], off
	s_waitcnt vmcnt(8)
	s_waitcnt lgkmcnt(0)
	s_barrier
	s_waitcnt lgkmcnt(0)
	v_mfma_f32_16x16x32_bf16 v[122:125], v[142:145], v[176:179], v[122:125]
	v_mfma_f32_16x16x32_bf16 v[126:129], v[152:155], v[176:179], v[126:129]
	v_mfma_f32_16x16x32_bf16 v[110:113], v[142:145], v[184:187], v[110:113]
	v_mfma_f32_16x16x32_bf16 v[106:109], v[152:155], v[184:187], v[106:109]
	v_mfma_f32_16x16x32_bf16 v[94:97], v[142:145], v[192:195], v[94:97]
	v_mfma_f32_16x16x32_bf16 v[90:93], v[152:155], v[192:195], v[90:93]
	v_mfma_f32_16x16x32_bf16 v[78:81], v[142:145], v[200:203], v[78:81]
	v_mfma_f32_16x16x32_bf16 v[74:77], v[152:155], v[200:203], v[74:77]
	v_mfma_f32_16x16x32_bf16 v[122:125], v[148:151], v[180:183], v[122:125]
	v_mfma_f32_16x16x32_bf16 v[126:129], v[156:159], v[180:183], v[126:129]
	v_mfma_f32_16x16x32_bf16 v[110:113], v[148:151], v[188:191], v[110:113]
	v_mfma_f32_16x16x32_bf16 v[106:109], v[156:159], v[188:191], v[106:109]
	v_mfma_f32_16x16x32_bf16 v[94:97], v[148:151], v[196:199], v[94:97]
	v_mfma_f32_16x16x32_bf16 v[90:93], v[156:159], v[196:199], v[90:93]
	v_mfma_f32_16x16x32_bf16 v[78:81], v[148:151], v[204:207], v[78:81]
	v_mfma_f32_16x16x32_bf16 v[74:77], v[156:159], v[204:207], v[74:77]
	v_mfma_f32_16x16x32_bf16 v[118:121], v[160:163], v[176:179], v[118:121]
	v_mfma_f32_16x16x32_bf16 v[114:117], v[168:171], v[176:179], v[114:117]
	v_mfma_f32_16x16x32_bf16 v[102:105], v[160:163], v[184:187], v[102:105]
	v_mfma_f32_16x16x32_bf16 v[98:101], v[168:171], v[184:187], v[98:101]
	v_mfma_f32_16x16x32_bf16 v[86:89], v[160:163], v[192:195], v[86:89]
	v_mfma_f32_16x16x32_bf16 v[82:85], v[168:171], v[192:195], v[82:85]
	v_mfma_f32_16x16x32_bf16 v[70:73], v[160:163], v[200:203], v[70:73]
	v_mfma_f32_16x16x32_bf16 v[66:69], v[168:171], v[200:203], v[66:69]
	v_mfma_f32_16x16x32_bf16 v[118:121], v[164:167], v[180:183], v[118:121]
	v_mfma_f32_16x16x32_bf16 v[114:117], v[172:175], v[180:183], v[114:117]
	v_mfma_f32_16x16x32_bf16 v[102:105], v[164:167], v[188:191], v[102:105]
	v_mfma_f32_16x16x32_bf16 v[98:101], v[172:175], v[188:191], v[98:101]
	v_mfma_f32_16x16x32_bf16 v[86:89], v[164:167], v[196:199], v[86:89]
	v_mfma_f32_16x16x32_bf16 v[82:85], v[172:175], v[196:199], v[82:85]
	v_mfma_f32_16x16x32_bf16 v[70:73], v[164:167], v[204:207], v[70:73]
	v_mfma_f32_16x16x32_bf16 v[66:69], v[172:175], v[204:207], v[66:69]
	s_barrier
; #define PG8_STAGE(bufoff, gbase, voff) do { _Pragma("unroll") for (int _i = 0; _i < 2; ++_i) \
;         __builtin_amdgcn_global_load_lds((const unsigned*)((const char*)(gbase) + (voff)[_i]), (PG8_LAS unsigned*)(lds + (bufoff) + ldsw + _i * 8192), 16, 0, 0); } while (0)
; #define PG8_LDA(dst, b, h) do { _Pragma("unroll") for (int m = 0; m < 4; ++m) _Pragma("unroll") for (int k = 0; k < 2; ++k) dst[m][k] = *(const PG8_LAS bf16x8*)(lds + PG8_SA(b, h) + aoff + m * 2048 + k * 1024); } while (0)
; #define PG8_MMA(ai, bj, At, Bt) do { __builtin_amdgcn_s_setprio(1); _Pragma("unroll") for (int m = 0; m < 4; ++m) _Pragma("unroll") for (int n = 0; n < 2; ++n) _Pragma("unroll") for (int k = 0; k < 2; ++k) \
;         acc[ai][bj][m][n] = __builtin_amdgcn_mfma_f32_16x16x32_bf16(Bt[n][k], At[m][k], acc[ai][bj][m][n], 0, 0, 0); __builtin_amdgcn_s_setprio(0); } while (0)
; #define PG8_WAIT_V(n) asm volatile("s_waitcnt vmcnt(" #n ")" ::: "memory")
; #define PG8_WAIT_L(n) asm volatile("s_waitcnt lgkmcnt(" #n ")" ::: "memory")
; #define PG8_BAR __builtin_amdgcn_s_barrier()
; #define PG8_SCHED __builtin_amdgcn_sched_barrier(0)
; template <class Epi, class Sched, bool ALIGN_EPI = false, bool SP2 = false>
; __device__ __forceinline__ void gemm_phase(PG8_LAS unsigned char* lds, const Gemm g, const Sched& S, const Epi& E) {
;     ...
;             PG8_LDA(At, 1, 1); PG8_STAGE(PG8_SB(1, 0), b3, voffB); PG8_STAGE(PG8_SB(1, 1), b3 + hstep, voffB); PG8_STAGE(PG8_SA(1, 0), a3, voffA);
;             PG8_WAIT_V(8); PG8_WAIT_L(0); PG8_BAR; PG8_MMA(1, 0, At, B0); PG8_MMA(1, 1, At, B1); PG8_BAR; PG8_SCHED;
	s_add_i32 s36, s39, s71
	v_lshl_add_u64 v[208:209], v[208:209], 0, s[28:29]
	s_mov_b32 m0, s36
	ds_read_b128 v[176:179], v147 offset:49152
	ds_read_b128 v[180:183], v147 offset:50176
	ds_read_b128 v[184:187], v147 offset:51200
	ds_read_b128 v[188:191], v147 offset:52224
	ds_read_b128 v[192:195], v147 offset:53248
	ds_read_b128 v[196:199], v147 offset:54272
	ds_read_b128 v[200:203], v147 offset:55296
	ds_read_b128 v[204:207], v147 offset:56320
	global_load_lds_dwordx4 v[208:209], off
	v_lshl_add_u64 v[208:209], v[210:211], 0, s[28:29]
	s_add_i32 m0, s36, 0x2000
	s_add_i32 s36, s86, s71
	global_load_lds_dwordx4 v[208:209], off
	v_lshl_add_u64 v[208:209], v[212:213], 0, s[28:29]
	s_mov_b32 m0, s36
	s_nop 0
	global_load_lds_dwordx4 v[208:209], off
	v_lshl_add_u64 v[208:209], v[214:215], 0, s[28:29]
	s_add_i32 m0, s36, 0x2000
	s_nop 0
	global_load_lds_dwordx4 v[208:209], off
	v_lshl_add_u64 v[208:209], v[220:221], 0, s[28:29]
	s_mov_b32 m0, s77
	s_nop 0
	global_load_lds_dwordx4 v[208:209], off
	v_lshl_add_u64 v[208:209], v[222:223], 0, s[28:29]
	s_mov_b32 m0, s78
	s_nop 0
	global_load_lds_dwordx4 v[208:209], off
	s_waitcnt vmcnt(8)
	s_waitcnt lgkmcnt(0)
	s_barrier
	s_waitcnt lgkmcnt(0)
	v_mfma_f32_16x16x32_bf16 v[62:65], v[142:145], v[176:179], v[62:65]
	v_mfma_f32_16x16x32_bf16 v[58:61], v[152:155], v[176:179], v[58:61]
	v_mfma_f32_16x16x32_bf16 v[46:49], v[142:145], v[184:187], v[46:49]
	v_mfma_f32_16x16x32_bf16 v[42:45], v[152:155], v[184:187], v[42:45]
	v_mfma_f32_16x16x32_bf16 v[30:33], v[142:145], v[192:195], v[30:33]
	v_mfma_f32_16x16x32_bf16 v[26:29], v[152:155], v[192:195], v[26:29]
	v_mfma_f32_16x16x32_bf16 v[14:17], v[142:145], v[200:203], v[14:17]
	v_mfma_f32_16x16x32_bf16 v[10:13], v[152:155], v[200:203], v[10:13]
	v_mfma_f32_16x16x32_bf16 v[62:65], v[148:151], v[180:183], v[62:65]
	v_mfma_f32_16x16x32_bf16 v[58:61], v[156:159], v[180:183], v[58:61]
	v_mfma_f32_16x16x32_bf16 v[46:49], v[148:151], v[188:191], v[46:49]
	v_mfma_f32_16x16x32_bf16 v[42:45], v[156:159], v[188:191], v[42:45]
	v_mfma_f32_16x16x32_bf16 v[30:33], v[148:151], v[196:199], v[30:33]
	v_mfma_f32_16x16x32_bf16 v[26:29], v[156:159], v[196:199], v[26:29]
	v_mfma_f32_16x16x32_bf16 v[14:17], v[148:151], v[204:207], v[14:17]
	v_mfma_f32_16x16x32_bf16 v[10:13], v[156:159], v[204:207], v[10:13]
	v_mfma_f32_16x16x32_bf16 v[54:57], v[160:163], v[176:179], v[54:57]
	v_mfma_f32_16x16x32_bf16 v[50:53], v[168:171], v[176:179], v[50:53]
	v_mfma_f32_16x16x32_bf16 v[38:41], v[160:163], v[184:187], v[38:41]
	v_mfma_f32_16x16x32_bf16 v[34:37], v[168:171], v[184:187], v[34:37]
	v_mfma_f32_16x16x32_bf16 v[22:25], v[160:163], v[192:195], v[22:25]
	v_mfma_f32_16x16x32_bf16 v[18:21], v[168:171], v[192:195], v[18:21]
	v_mfma_f32_16x16x32_bf16 v[6:9], v[160:163], v[200:203], v[6:9]
	v_mfma_f32_16x16x32_bf16 v[2:5], v[168:171], v[200:203], v[2:5]
	v_mfma_f32_16x16x32_bf16 v[54:57], v[164:167], v[180:183], v[54:57]
	v_mfma_f32_16x16x32_bf16 v[50:53], v[172:175], v[180:183], v[50:53]
	v_mfma_f32_16x16x32_bf16 v[38:41], v[164:167], v[188:191], v[38:41]
	v_mfma_f32_16x16x32_bf16 v[34:37], v[172:175], v[188:191], v[34:37]
	v_mfma_f32_16x16x32_bf16 v[22:25], v[164:167], v[196:199], v[22:25]
	v_mfma_f32_16x16x32_bf16 v[18:21], v[172:175], v[196:199], v[18:21]
	v_mfma_f32_16x16x32_bf16 v[6:9], v[164:167], v[204:207], v[6:9]
	v_mfma_f32_16x16x32_bf16 v[2:5], v[172:175], v[204:207], v[2:5]
	s_barrier
	s_add_u32 s40, s40, 0x100
	s_addc_u32 s41, s41, 0
	s_add_u32 s4, s4, 0x100
	s_addc_u32 s5, s5, 0
	s_cmp_ge_i32 s38, s82
	s_mov_b32 s36, s38
	s_cbranch_scc0 .LBB0_783
	s_mov_b32 s87, vcc_hi

; #define PG8_STAGE(bufoff, gbase, voff) do { _Pragma("unroll") for (int _i = 0; _i < 2; ++_i) \
;         __builtin_amdgcn_global_load_lds((const unsigned*)((const char*)(gbase) + (voff)[_i]), (PG8_LAS unsigned*)(lds + (bufoff) + ldsw + _i * 8192), 16, 0, 0); } while (0)
; #define PG8_LDA(dst, b, h) do { _Pragma("unroll") for (int m = 0; m < 4; ++m) _Pragma("unroll") for (int k = 0; k < 2; ++k) dst[m][k] = *(const PG8_LAS bf16x8*)(lds + PG8_SA(b, h) + aoff + m * 2048 + k * 1024); } while (0)
; #define PG8_MMA(ai, bj, At, Bt) do { __builtin_amdgcn_s_setprio(1); _Pragma("unroll") for (int m = 0; m < 4; ++m) _Pragma("unroll") for (int n = 0; n < 2; ++n) _Pragma("unroll") for (int k = 0; k < 2; ++k) \
;         acc[ai][bj][m][n] = __builtin_amdgcn_mfma_f32_16x16x32_bf16(Bt[n][k], At[m][k], acc[ai][bj][m][n], 0, 0, 0); __builtin_amdgcn_s_setprio(0); } while (0)
; #define PG8_WAIT_V(n) asm volatile("s_waitcnt vmcnt(" #n ")" ::: "memory")
; #define PG8_WAIT_L(n) asm volatile("s_waitcnt lgkmcnt(" #n ")" ::: "memory")
; #define PG8_BAR __builtin_amdgcn_s_barrier()
; #define PG8_SCHED __builtin_amdgcn_sched_barrier(0)
; template <class Epi, class Sched, bool ALIGN_EPI = false, bool SP2 = false>
; __device__ __forceinline__ void gemm_phase(PG8_LAS unsigned char* lds, const Gemm g, const Sched& S, const Epi& E) {
;     ...
;             PG8_WAIT_V(8); PG8_WAIT_L(0); PG8_BAR; PG8_MMA(0, 0, At, B0); PG8_MMA(0, 1, At, B1); PG8_BAR; PG8_SCHED;
;             PG8_LDA(At, 0, 1); PG8_STAGE(PG8_SB(0, 0), b2, voffB); PG8_STAGE(PG8_SB(0, 1), b2 + hstep, voffB); PG8_STAGE(PG8_SA(0, 0), a2, voffA);
;             PG8_WAIT_V(8); PG8_WAIT_L(0); PG8_BAR; PG8_MMA(1, 0, At, B0); PG8_MMA(1, 1, At, B1); PG8_BAR; PG8_SCHED;
.Lrw_out_1:
	s_waitcnt lgkmcnt(0)
	s_barrier
	s_waitcnt lgkmcnt(0)
	v_mfma_f32_16x16x32_bf16 v[142:145], v[66:69], v[162:165], v[142:145]
	v_mfma_f32_16x16x32_bf16 v[138:141], v[74:77], v[162:165], v[138:141]
	v_mfma_f32_16x16x32_bf16 v[126:129], v[66:69], v[170:173], v[126:129]
	v_mfma_f32_16x16x32_bf16 v[122:125], v[74:77], v[170:173], v[122:125]
	v_mfma_f32_16x16x32_bf16 v[110:113], v[66:69], v[178:181], v[110:113]
	v_mfma_f32_16x16x32_bf16 v[106:109], v[74:77], v[178:181], v[106:109]
	v_mfma_f32_16x16x32_bf16 v[94:97], v[66:69], v[186:189], v[94:97]
	v_mfma_f32_16x16x32_bf16 v[90:93], v[74:77], v[186:189], v[90:93]
	v_mfma_f32_16x16x32_bf16 v[142:145], v[70:73], v[166:169], v[142:145]
	v_mfma_f32_16x16x32_bf16 v[138:141], v[78:81], v[166:169], v[138:141]
	v_mfma_f32_16x16x32_bf16 v[126:129], v[70:73], v[174:177], v[126:129]
	v_mfma_f32_16x16x32_bf16 v[122:125], v[78:81], v[174:177], v[122:125]
	v_mfma_f32_16x16x32_bf16 v[110:113], v[70:73], v[182:185], v[110:113]
	v_mfma_f32_16x16x32_bf16 v[106:109], v[78:81], v[182:185], v[106:109]
	v_mfma_f32_16x16x32_bf16 v[94:97], v[70:73], v[190:193], v[94:97]
	v_mfma_f32_16x16x32_bf16 v[90:93], v[78:81], v[190:193], v[90:93]
	v_mfma_f32_16x16x32_bf16 v[134:137], v[146:149], v[162:165], v[134:137]
	v_mfma_f32_16x16x32_bf16 v[130:133], v[154:157], v[162:165], v[130:133]
	v_mfma_f32_16x16x32_bf16 v[118:121], v[146:149], v[170:173], v[118:121]
	v_mfma_f32_16x16x32_bf16 v[114:117], v[154:157], v[170:173], v[114:117]
	v_mfma_f32_16x16x32_bf16 v[102:105], v[146:149], v[178:181], v[102:105]
	v_mfma_f32_16x16x32_bf16 v[98:101], v[154:157], v[178:181], v[98:101]
	v_mfma_f32_16x16x32_bf16 v[86:89], v[146:149], v[186:189], v[86:89]
	v_mfma_f32_16x16x32_bf16 v[82:85], v[154:157], v[186:189], v[82:85]
	v_mfma_f32_16x16x32_bf16 v[134:137], v[150:153], v[166:169], v[134:137]
	v_mfma_f32_16x16x32_bf16 v[130:133], v[158:161], v[166:169], v[130:133]
	v_mfma_f32_16x16x32_bf16 v[118:121], v[150:153], v[174:177], v[118:121]
	v_mfma_f32_16x16x32_bf16 v[114:117], v[158:161], v[174:177], v[114:117]
	v_mfma_f32_16x16x32_bf16 v[102:105], v[150:153], v[182:185], v[102:105]
	v_mfma_f32_16x16x32_bf16 v[98:101], v[158:161], v[182:185], v[98:101]
	v_mfma_f32_16x16x32_bf16 v[86:89], v[150:153], v[190:193], v[86:89]
	v_mfma_f32_16x16x32_bf16 v[82:85], v[158:161], v[190:193], v[82:85]
	s_barrier
	s_add_i32 s75, s75, s41
	v_lshl_add_u64 v[194:195], s[36:37], 0, v[222:223]
	s_mov_b32 m0, s75
	ds_read_b128 v[162:165], v211 offset:16384
	ds_read_b128 v[166:169], v211 offset:17408
	ds_read_b128 v[170:173], v211 offset:18432
	ds_read_b128 v[174:177], v211 offset:19456
	ds_read_b128 v[178:181], v211 offset:20480
	ds_read_b128 v[182:185], v211 offset:21504
	ds_read_b128 v[186:189], v211 offset:22528
	ds_read_b128 v[190:193], v211 offset:23552
	global_load_lds_dwordx4 v[194:195], off
	s_add_i32 m0, s75, 0x2000
	s_add_u32 s76, s36, 0x40000
	v_lshl_add_u64 v[196:197], s[36:37], 0, v[226:227]
	s_addc_u32 s77, s37, 0
	s_add_i32 s75, s78, s41
	global_load_lds_dwordx4 v[196:197], off
	v_lshl_add_u64 v[198:199], s[76:77], 0, v[222:223]
	s_mov_b32 m0, s75
	v_lshl_add_u64 v[200:201], s[38:39], 0, v[224:225]
	global_load_lds_dwordx4 v[198:199], off
	v_lshl_add_u64 v[198:199], s[76:77], 0, v[226:227]
	s_add_i32 m0, s75, 0x2000
	s_nop 0
	global_load_lds_dwordx4 v[198:199], off
	v_lshl_add_u64 v[198:199], s[38:39], 0, v[220:221]
	s_mov_b32 m0, s27
	s_nop 0
	global_load_lds_dwordx4 v[198:199], off
	s_mov_b32 m0, s60
	s_nop 0
	global_load_lds_dwordx4 v[200:201], off
	s_cmp_lg_u32 s98, 0
	s_cbranch_scc1 .Lrw_out_2
	s_waitcnt vmcnt(8)
.Lrw_out_2:
	s_mov_b32 s98, 0
	s_waitcnt lgkmcnt(0)
	s_barrier
	s_waitcnt lgkmcnt(0)
	v_mfma_f32_16x16x32_bf16 v[62:65], v[66:69], v[162:165], v[62:65]
	v_mfma_f32_16x16x32_bf16 v[58:61], v[74:77], v[162:165], v[58:61]
	v_mfma_f32_16x16x32_bf16 v[46:49], v[66:69], v[170:173], v[46:49]
	v_mfma_f32_16x16x32_bf16 v[42:45], v[74:77], v[170:173], v[42:45]
	v_mfma_f32_16x16x32_bf16 v[30:33], v[66:69], v[178:181], v[30:33]
	v_mfma_f32_16x16x32_bf16 v[26:29], v[74:77], v[178:181], v[26:29]
	v_mfma_f32_16x16x32_bf16 v[14:17], v[66:69], v[186:189], v[14:17]
	v_mfma_f32_16x16x32_bf16 v[10:13], v[74:77], v[186:189], v[10:13]
	v_mfma_f32_16x16x32_bf16 v[62:65], v[70:73], v[166:169], v[62:65]
	v_mfma_f32_16x16x32_bf16 v[58:61], v[78:81], v[166:169], v[58:61]
	v_mfma_f32_16x16x32_bf16 v[46:49], v[70:73], v[174:177], v[46:49]
	v_mfma_f32_16x16x32_bf16 v[42:45], v[78:81], v[174:177], v[42:45]
	v_mfma_f32_16x16x32_bf16 v[30:33], v[70:73], v[182:185], v[30:33]
	v_mfma_f32_16x16x32_bf16 v[26:29], v[78:81], v[182:185], v[26:29]
	v_mfma_f32_16x16x32_bf16 v[14:17], v[70:73], v[190:193], v[14:17]
	v_mfma_f32_16x16x32_bf16 v[10:13], v[78:81], v[190:193], v[10:13]
	v_mfma_f32_16x16x32_bf16 v[54:57], v[146:149], v[162:165], v[54:57]
	v_mfma_f32_16x16x32_bf16 v[50:53], v[154:157], v[162:165], v[50:53]
	v_mfma_f32_16x16x32_bf16 v[38:41], v[146:149], v[170:173], v[38:41]
	v_mfma_f32_16x16x32_bf16 v[34:37], v[154:157], v[170:173], v[34:37]
	v_mfma_f32_16x16x32_bf16 v[22:25], v[146:149], v[178:181], v[22:25]
	v_mfma_f32_16x16x32_bf16 v[18:21], v[154:157], v[178:181], v[18:21]
	v_mfma_f32_16x16x32_bf16 v[6:9], v[146:149], v[186:189], v[6:9]
	v_mfma_f32_16x16x32_bf16 v[2:5], v[154:157], v[186:189], v[2:5]
	v_mfma_f32_16x16x32_bf16 v[54:57], v[150:153], v[166:169], v[54:57]
	v_mfma_f32_16x16x32_bf16 v[50:53], v[158:161], v[166:169], v[50:53]
	v_mfma_f32_16x16x32_bf16 v[38:41], v[150:153], v[174:177], v[38:41]
	v_mfma_f32_16x16x32_bf16 v[34:37], v[158:161], v[174:177], v[34:37]
	v_mfma_f32_16x16x32_bf16 v[22:25], v[150:153], v[182:185], v[22:25]
	v_mfma_f32_16x16x32_bf16 v[18:21], v[158:161], v[182:185], v[18:21]
	v_mfma_f32_16x16x32_bf16 v[6:9], v[150:153], v[190:193], v[6:9]
	v_mfma_f32_16x16x32_bf16 v[2:5], v[158:161], v[190:193], v[2:5]
	s_barrier
; #define PG8_STAGE(bufoff, gbase, voff) do { _Pragma("unroll") for (int _i = 0; _i < 2; ++_i) \
;         __builtin_amdgcn_global_load_lds((const unsigned*)((const char*)(gbase) + (voff)[_i]), (PG8_LAS unsigned*)(lds + (bufoff) + ldsw + _i * 8192), 16, 0, 0); } while (0)
; #define PG8_LDA(dst, b, h) do { _Pragma("unroll") for (int m = 0; m < 4; ++m) _Pragma("unroll") for (int k = 0; k < 2; ++k) dst[m][k] = *(const PG8_LAS bf16x8*)(lds + PG8_SA(b, h) + aoff + m * 2048 + k * 1024); } while (0)
; #define PG8_LDB(dst, b, h) do { _Pragma("unroll") for (int n = 0; n < 2; ++n) _Pragma("unroll") for (int k = 0; k < 2; ++k) dst[n][k] = *(const PG8_LAS bf16x8*)(lds + PG8_SB(b, h) + boff + n * 2048 + k * 1024); } while (0)
; #define PG8_MMA(ai, bj, At, Bt) do { __builtin_amdgcn_s_setprio(1); _Pragma("unroll") for (int m = 0; m < 4; ++m) _Pragma("unroll") for (int n = 0; n < 2; ++n) _Pragma("unroll") for (int k = 0; k < 2; ++k) \
;         acc[ai][bj][m][n] = __builtin_amdgcn_mfma_f32_16x16x32_bf16(Bt[n][k], At[m][k], acc[ai][bj][m][n], 0, 0, 0); __builtin_amdgcn_s_setprio(0); } while (0)
; #define PG8_WAIT_V(n) asm volatile("s_waitcnt vmcnt(" #n ")" ::: "memory")
; #define PG8_WAIT_L(n) asm volatile("s_waitcnt lgkmcnt(" #n ")" ::: "memory")
; #define PG8_BAR __builtin_amdgcn_s_barrier()
; #define PG8_SCHED __builtin_amdgcn_sched_barrier(0)
; template <class Epi, class Sched, bool ALIGN_EPI = false, bool SP2 = false>
; __device__ __forceinline__ void gemm_phase(PG8_LAS unsigned char* lds, const Gemm g, const Sched& S, const Epi& E) {
;     ...
;             PG8_LDB(B0, 1, 0); PG8_LDB(B1, 1, 1); PG8_SCHED; PG8_LDA(At, 1, 0); PG8_STAGE(PG8_SA(0, 1), a2 + hstep, voffA);
;             PG8_WAIT_V(8); PG8_WAIT_L(0); PG8_BAR; PG8_MMA(0, 0, At, B0); PG8_MMA(0, 1, At, B1); PG8_BAR; PG8_SCHED;
	s_add_i32 s75, 0, 0x18000
	v_add_u32_e32 v0, s75, v210
	s_add_i32 s76, 0, 0x1c000
	ds_read_b128 v[66:69], v0
	ds_read_b128 v[70:73], v0 offset:1024
	ds_read_b128 v[74:77], v0 offset:2048
	ds_read_b128 v[78:81], v0 offset:3072
	v_add_u32_e32 v0, s76, v210
	ds_read_b128 v[146:149], v0
	ds_read_b128 v[150:153], v0 offset:1024
	ds_read_b128 v[154:157], v0 offset:2048
	ds_read_b128 v[158:161], v0 offset:3072
	s_add_u32 s38, s38, 0x40000
	s_addc_u32 s39, s39, 0
	s_mov_b32 m0, s61
	v_lshl_add_u64 v[202:203], s[38:39], 0, v[220:221]
	ds_read_b128 v[162:165], v211 offset:32768
	ds_read_b128 v[166:169], v211 offset:33792
	ds_read_b128 v[170:173], v211 offset:34816
	ds_read_b128 v[174:177], v211 offset:35840
	ds_read_b128 v[178:181], v211 offset:36864
	ds_read_b128 v[182:185], v211 offset:37888
	ds_read_b128 v[186:189], v211 offset:38912
	ds_read_b128 v[190:193], v211 offset:39936
	global_load_lds_dwordx4 v[202:203], off
	v_lshl_add_u64 v[202:203], s[38:39], 0, v[224:225]
	s_mov_b32 m0, s62
	s_nop 0
	global_load_lds_dwordx4 v[202:203], off
	s_waitcnt vmcnt(8)
	s_waitcnt lgkmcnt(0)
	s_barrier
	s_waitcnt lgkmcnt(0)
	v_mfma_f32_16x16x32_bf16 v[142:145], v[66:69], v[162:165], v[142:145]
	v_mfma_f32_16x16x32_bf16 v[138:141], v[74:77], v[162:165], v[138:141]
	v_mfma_f32_16x16x32_bf16 v[126:129], v[66:69], v[170:173], v[126:129]
	v_mfma_f32_16x16x32_bf16 v[122:125], v[74:77], v[170:173], v[122:125]
	v_mfma_f32_16x16x32_bf16 v[110:113], v[66:69], v[178:181], v[110:113]
	v_mfma_f32_16x16x32_bf16 v[106:109], v[74:77], v[178:181], v[106:109]
	v_mfma_f32_16x16x32_bf16 v[94:97], v[66:69], v[186:189], v[94:97]
	v_mfma_f32_16x16x32_bf16 v[90:93], v[74:77], v[186:189], v[90:93]
	v_mfma_f32_16x16x32_bf16 v[142:145], v[70:73], v[166:169], v[142:145]
	v_mfma_f32_16x16x32_bf16 v[138:141], v[78:81], v[166:169], v[138:141]
	v_mfma_f32_16x16x32_bf16 v[126:129], v[70:73], v[174:177], v[126:129]
	v_mfma_f32_16x16x32_bf16 v[122:125], v[78:81], v[174:177], v[122:125]
	v_mfma_f32_16x16x32_bf16 v[110:113], v[70:73], v[182:185], v[110:113]
	v_mfma_f32_16x16x32_bf16 v[106:109], v[78:81], v[182:185], v[106:109]
	v_mfma_f32_16x16x32_bf16 v[94:97], v[70:73], v[190:193], v[94:97]
	v_mfma_f32_16x16x32_bf16 v[90:93], v[78:81], v[190:193], v[90:93]
	v_mfma_f32_16x16x32_bf16 v[134:137], v[146:149], v[162:165], v[134:137]
	v_mfma_f32_16x16x32_bf16 v[130:133], v[154:157], v[162:165], v[130:133]
	v_mfma_f32_16x16x32_bf16 v[118:121], v[146:149], v[170:173], v[118:121]
	v_mfma_f32_16x16x32_bf16 v[114:117], v[154:157], v[170:173], v[114:117]
	v_mfma_f32_16x16x32_bf16 v[102:105], v[146:149], v[178:181], v[102:105]
	v_mfma_f32_16x16x32_bf16 v[98:101], v[154:157], v[178:181], v[98:101]
	v_mfma_f32_16x16x32_bf16 v[86:89], v[146:149], v[186:189], v[86:89]
	v_mfma_f32_16x16x32_bf16 v[82:85], v[154:157], v[186:189], v[82:85]
	v_mfma_f32_16x16x32_bf16 v[134:137], v[150:153], v[166:169], v[134:137]
	v_mfma_f32_16x16x32_bf16 v[130:133], v[158:161], v[166:169], v[130:133]
	v_mfma_f32_16x16x32_bf16 v[118:121], v[150:153], v[174:177], v[118:121]
	v_mfma_f32_16x16x32_bf16 v[114:117], v[158:161], v[174:177], v[114:117]
	v_mfma_f32_16x16x32_bf16 v[102:105], v[150:153], v[182:185], v[102:105]
	v_mfma_f32_16x16x32_bf16 v[98:101], v[158:161], v[182:185], v[98:101]
	v_mfma_f32_16x16x32_bf16 v[86:89], v[150:153], v[190:193], v[86:89]
	v_mfma_f32_16x16x32_bf16 v[82:85], v[158:161], v[190:193], v[82:85]
	s_barrier
; #define PG8_STAGE(bufoff, gbase, voff) do { _Pragma("unroll") for (int _i = 0; _i < 2; ++_i) \
;         __builtin_amdgcn_global_load_lds((const unsigned*)((const char*)(gbase) + (voff)[_i]), (PG8_LAS unsigned*)(lds + (bufoff) + ldsw + _i * 8192), 16, 0, 0); } while (0)
; #define PG8_LDA(dst, b, h) do { _Pragma("unroll") for (int m = 0; m < 4; ++m) _Pragma("unroll") for (int k = 0; k < 2; ++k) dst[m][k] = *(const PG8_LAS bf16x8*)(lds + PG8_SA(b, h) + aoff + m * 2048 + k * 1024); } while (0)
; #define PG8_MMA(ai, bj, At, Bt) do { __builtin_amdgcn_s_setprio(1); _Pragma("unroll") for (int m = 0; m < 4; ++m) _Pragma("unroll") for (int n = 0; n < 2; ++n) _Pragma("unroll") for (int k = 0; k < 2; ++k) \
;         acc[ai][bj][m][n] = __builtin_amdgcn_mfma_f32_16x16x32_bf16(Bt[n][k], At[m][k], acc[ai][bj][m][n], 0, 0, 0); __builtin_amdgcn_s_setprio(0); } while (0)
; #define PG8_WAIT_V(n) asm volatile("s_waitcnt vmcnt(" #n ")" ::: "memory")
; #define PG8_WAIT_L(n) asm volatile("s_waitcnt lgkmcnt(" #n ")" ::: "memory")
; #define PG8_BAR __builtin_amdgcn_s_barrier()
; #define PG8_SCHED __builtin_amdgcn_sched_barrier(0)
; template <class Epi, class Sched, bool ALIGN_EPI = false, bool SP2 = false>
; __device__ __forceinline__ void gemm_phase(PG8_LAS unsigned char* lds, const Gemm g, const Sched& S, const Epi& E) {
;     ...
;             PG8_LDA(At, 1, 1); PG8_STAGE(PG8_SB(1, 0), b3, voffB); PG8_STAGE(PG8_SB(1, 1), b3 + hstep, voffB); PG8_STAGE(PG8_SA(1, 0), a3, voffA);
;             PG8_WAIT_V(8); PG8_WAIT_L(0); PG8_BAR; PG8_MMA(1, 0, At, B0); PG8_MMA(1, 1, At, B1); PG8_BAR; PG8_SCHED;
;     ...
;         if constexpr (ALIGN_EPI) { if (wr == 0) PG8_BAR; }
	s_add_i32 s38, s75, s41
	v_lshl_add_u64 v[194:195], v[194:195], 0, s[28:29]
	s_mov_b32 m0, s38
	ds_read_b128 v[162:165], v211 offset:49152
	ds_read_b128 v[166:169], v211 offset:50176
	ds_read_b128 v[170:173], v211 offset:51200
	ds_read_b128 v[174:177], v211 offset:52224
	ds_read_b128 v[178:181], v211 offset:53248
	ds_read_b128 v[182:185], v211 offset:54272
	ds_read_b128 v[186:189], v211 offset:55296
	ds_read_b128 v[190:193], v211 offset:56320
	global_load_lds_dwordx4 v[194:195], off
	s_add_i32 m0, s38, 0x2000
	s_add_u32 s36, s36, 0x40080
	v_lshl_add_u64 v[194:195], v[196:197], 0, s[28:29]
	s_addc_u32 s37, s37, 0
	s_add_i32 s38, s76, s41
	global_load_lds_dwordx4 v[194:195], off
	v_lshl_add_u64 v[194:195], s[36:37], 0, v[222:223]
	s_mov_b32 m0, s38
	s_nop 0
	global_load_lds_dwordx4 v[194:195], off
	v_lshl_add_u64 v[194:195], s[36:37], 0, v[226:227]
	s_add_i32 m0, s38, 0x2000
	s_nop 0
	global_load_lds_dwordx4 v[194:195], off
	v_lshl_add_u64 v[194:195], v[198:199], 0, s[28:29]
	s_mov_b32 m0, s65
	s_nop 0
	global_load_lds_dwordx4 v[194:195], off
	v_lshl_add_u64 v[194:195], v[200:201], 0, s[28:29]
	s_mov_b32 m0, s69
	s_nop 0
	global_load_lds_dwordx4 v[194:195], off
	s_waitcnt vmcnt(8)
	s_waitcnt lgkmcnt(0)
	s_barrier
	s_waitcnt lgkmcnt(0)
	v_mfma_f32_16x16x32_bf16 v[62:65], v[66:69], v[162:165], v[62:65]
	v_mfma_f32_16x16x32_bf16 v[58:61], v[74:77], v[162:165], v[58:61]
	v_mfma_f32_16x16x32_bf16 v[46:49], v[66:69], v[170:173], v[46:49]
	v_mfma_f32_16x16x32_bf16 v[42:45], v[74:77], v[170:173], v[42:45]
	v_mfma_f32_16x16x32_bf16 v[30:33], v[66:69], v[178:181], v[30:33]
	v_mfma_f32_16x16x32_bf16 v[26:29], v[74:77], v[178:181], v[26:29]
	v_mfma_f32_16x16x32_bf16 v[14:17], v[66:69], v[186:189], v[14:17]
	v_mfma_f32_16x16x32_bf16 v[10:13], v[74:77], v[186:189], v[10:13]
	v_mfma_f32_16x16x32_bf16 v[62:65], v[70:73], v[166:169], v[62:65]
	v_mfma_f32_16x16x32_bf16 v[58:61], v[78:81], v[166:169], v[58:61]
	v_mfma_f32_16x16x32_bf16 v[46:49], v[70:73], v[174:177], v[46:49]
	v_mfma_f32_16x16x32_bf16 v[42:45], v[78:81], v[174:177], v[42:45]
	v_mfma_f32_16x16x32_bf16 v[30:33], v[70:73], v[182:185], v[30:33]
	v_mfma_f32_16x16x32_bf16 v[26:29], v[78:81], v[182:185], v[26:29]
	v_mfma_f32_16x16x32_bf16 v[14:17], v[70:73], v[190:193], v[14:17]
	v_mfma_f32_16x16x32_bf16 v[10:13], v[78:81], v[190:193], v[10:13]
	v_mfma_f32_16x16x32_bf16 v[54:57], v[146:149], v[162:165], v[54:57]
	v_mfma_f32_16x16x32_bf16 v[50:53], v[154:157], v[162:165], v[50:53]
	v_mfma_f32_16x16x32_bf16 v[38:41], v[146:149], v[170:173], v[38:41]
	v_mfma_f32_16x16x32_bf16 v[34:37], v[154:157], v[170:173], v[34:37]
	v_mfma_f32_16x16x32_bf16 v[22:25], v[146:149], v[178:181], v[22:25]
	v_mfma_f32_16x16x32_bf16 v[18:21], v[154:157], v[178:181], v[18:21]
	v_mfma_f32_16x16x32_bf16 v[6:9], v[146:149], v[186:189], v[6:9]
	v_mfma_f32_16x16x32_bf16 v[2:5], v[154:157], v[186:189], v[2:5]
	v_mfma_f32_16x16x32_bf16 v[54:57], v[150:153], v[166:169], v[54:57]
	v_mfma_f32_16x16x32_bf16 v[50:53], v[158:161], v[166:169], v[50:53]
	v_mfma_f32_16x16x32_bf16 v[38:41], v[150:153], v[174:177], v[38:41]
	v_mfma_f32_16x16x32_bf16 v[34:37], v[158:161], v[174:177], v[34:37]
	v_mfma_f32_16x16x32_bf16 v[22:25], v[150:153], v[182:185], v[22:25]
	v_mfma_f32_16x16x32_bf16 v[18:21], v[158:161], v[182:185], v[18:21]
	v_mfma_f32_16x16x32_bf16 v[6:9], v[150:153], v[190:193], v[6:9]
	v_mfma_f32_16x16x32_bf16 v[2:5], v[158:161], v[190:193], v[2:5]
	s_barrier
	s_add_i32 s74, s74, 2
	s_add_u32 s72, s72, 0x100
	s_addc_u32 s73, s73, 0
	s_add_u32 s52, s52, 0x100
	s_addc_u32 s53, s53, 0
	s_cmp_gt_u32 s74, 13
	s_cbranch_scc0 .LBB0_1079
	s_and_b64 vcc, exec, s[14:15]
	s_cbranch_vccz .LBB0_1082
	s_barrier
